# indexer tile steps: MFMAs interleaved with previous tile's relu-fma epilogue on the hot path, cold path out of line (on top of count loop, mask build, attn nops)
# speedup vs baseline: 1.0041x; 1.0041x over previous
.LBB0_1141:
	ds_read_b128 v[0:3], v131 offset:0
	ds_read_b128 v[4:7], v131 offset:32
	ds_read_b128 v[10:13], v131 offset:64
	ds_read_b128 v[80:83], v131 offset:0x60
	s_cmp_lt_u32 s95, 2
	s_waitcnt lgkmcnt(0)
	ds_read_b128 v[108:111], v131 offset:0x1200
	ds_read_b128 v[104:107], v131 offset:0x1220
	ds_read_b128 v[100:103], v131 offset:0x1240
	ds_read_b128 v[96:99], v131 offset:0x1260
	s_cselect_b64 s[48:49], -1, 0
	v_mfma_f32_32x32x16_bf16 v[16:31], v[32:35], v[0:3], 0
	s_cmp_gt_u32 s95, 1
	v_mov_b32_e32 v0, 0
	v_mov_b32_e32 v1, 0
	v_mov_b32_e32 v2, 0
	v_mov_b32_e32 v3, 0
	v_mov_b32_e32 v8, 0
	v_mov_b32_e32 v9, 0
	v_mfma_f32_32x32x16_bf16 v[16:31], v[36:39], v[4:7], v[16:31]
	v_mov_b32_e32 v4, 0
	v_mov_b32_e32 v5, 0
	v_mov_b32_e32 v6, 0
	v_mov_b32_e32 v7, 0
	s_cselect_b64 s[50:51], -1, 0
	s_and_b64 vcc, exec, s[48:49]
	v_mov_b32_e32 v14, 0
	v_mfma_f32_32x32x16_bf16 v[16:31], v[40:43], v[10:13], v[16:31]
	v_mov_b32_e32 v10, 0
	v_mov_b32_e32 v11, 0
	v_mov_b32_e32 v12, 0
	v_mov_b32_e32 v13, 0
	v_mov_b32_e32 v15, 0
	v_mfma_f32_32x32x16_bf16 v[16:31], v[44:47], v[80:83], v[16:31]
	s_waitcnt lgkmcnt(0)
	ds_read_b128 v[92:95], v131 offset:0x2400
	ds_read_b128 v[88:91], v131 offset:0x2420
	ds_read_b128 v[84:87], v131 offset:0x2440
	ds_read_b128 v[80:83], v131 offset:0x2460
	s_cbranch_vccnz .Lixc112
	v_mfma_f32_32x32x16_bf16 v[0:15], v[32:35], v[108:111], 0
	s_nop 5
	v_max_i32_e32 v109, 0, v16
	v_fma_f32 v110, v48, v109, 0
	v_max_i32_e32 v109, 0, v17
	v_fmac_f32_e32 v110, v49, v109
	v_max_i32_e32 v109, 0, v18
	v_fmac_f32_e32 v110, v50, v109
	v_max_i32_e32 v109, 0, v19
	v_fmac_f32_e32 v110, v51, v109
	v_max_i32_e32 v109, 0, v20
	v_fmac_f32_e32 v110, v52, v109
	v_mfma_f32_32x32x16_bf16 v[0:15], v[36:39], v[104:107], v[0:15]
	v_max_i32_e32 v109, 0, v21
	v_fmac_f32_e32 v110, v53, v109
	v_max_i32_e32 v109, 0, v22
	v_fmac_f32_e32 v110, v54, v109
	v_max_i32_e32 v109, 0, v23
	v_fmac_f32_e32 v110, v55, v109
	v_max_i32_e32 v109, 0, v24
	v_fmac_f32_e32 v110, v56, v109
	v_max_i32_e32 v109, 0, v25
	v_fmac_f32_e32 v110, v57, v109
	v_mfma_f32_32x32x16_bf16 v[0:15], v[40:43], v[100:103], v[0:15]
	v_max_i32_e32 v109, 0, v26
	s_ashr_i32 s58, s58, 5
	v_fmac_f32_e32 v110, v58, v109
	v_max_i32_e32 v109, 0, v27
	s_lshl_b32 s64, s95, 4
	s_and_b32 s96, s58, -2
	v_fmac_f32_e32 v110, v59, v109
	v_max_i32_e32 v109, 0, v28
	s_add_i32 s96, s96, s64
	v_fmac_f32_e32 v110, v60, v109
	v_max_i32_e32 v109, 0, v29
	v_or_b32_e32 v203, s96, v129
	v_fmac_f32_e32 v110, v61, v109
	v_mfma_f32_32x32x16_bf16 v[0:15], v[44:47], v[96:99], v[0:15]
	v_max_i32_e32 v109, 0, v30
	v_fmac_f32_e32 v110, v62, v109
	v_max_i32_e32 v109, 0, v31
	v_cmp_gt_i32_e32 vcc, v130, v203
	v_fmac_f32_e32 v110, v63, v109
	s_and_b64 vcc, s[48:49], vcc
	v_cndmask_b32_e32 v200, v110, v197, vcc
.Lixj112:
	s_waitcnt lgkmcnt(0)
	ds_read_b128 v[104:107], v131 offset:0x3600
	ds_read_b128 v[100:103], v131 offset:0x3620
	ds_read_b128 v[96:99], v131 offset:0x3640
	ds_read_b128 v[108:111], v131 offset:0x3660
	s_cmp_gt_u32 s95, 3
	s_cselect_b64 s[64:65], -1, 0
	s_cmp_lt_u32 s95, 4
	s_cbranch_scc1 .Lixc111
	v_mfma_f32_32x32x16_bf16 v[16:31], v[32:35], v[92:95], 0
	s_lshr_b32 s58, s95, 1
	v_cndmask_b32_e64 v93, 0, 1, s[50:51]
	s_add_i32 s58, s58, 1
	v_cmp_ne_u32_e64 s[48:49], 1, v93
	s_andn2_b64 vcc, exec, s[50:51]
	v_max_i32_e32 v93, 0, v0
	v_fma_f32 v94, v48, v93, 0
	v_max_i32_e32 v93, 0, v1
	v_fmac_f32_e32 v94, v49, v93
	v_max_i32_e32 v93, 0, v2
	v_fmac_f32_e32 v94, v50, v93
	v_max_i32_e32 v93, 0, v3
	v_fmac_f32_e32 v94, v51, v93
	v_max_i32_e32 v93, 0, v4
	v_fmac_f32_e32 v94, v52, v93
	v_mfma_f32_32x32x16_bf16 v[16:31], v[36:39], v[88:91], v[16:31]
	v_max_i32_e32 v93, 0, v5
	v_fmac_f32_e32 v94, v53, v93
	v_max_i32_e32 v93, 0, v6
	v_fmac_f32_e32 v94, v54, v93
	v_max_i32_e32 v93, 0, v7
	v_fmac_f32_e32 v94, v55, v93
	v_max_i32_e32 v93, 0, v8
	v_fmac_f32_e32 v94, v56, v93
	v_max_i32_e32 v93, 0, v9
	v_fmac_f32_e32 v94, v57, v93
	v_mfma_f32_32x32x16_bf16 v[16:31], v[40:43], v[84:87], v[16:31]
	v_max_i32_e32 v93, 0, v10
	v_fmac_f32_e32 v94, v58, v93
	v_max_i32_e32 v93, 0, v11
	v_fmac_f32_e32 v94, v59, v93
	v_max_i32_e32 v93, 0, v12
	v_fmac_f32_e32 v94, v60, v93
	v_max_i32_e32 v93, 0, v13
	v_fmac_f32_e32 v94, v61, v93
	v_mfma_f32_32x32x16_bf16 v[16:31], v[44:47], v[80:83], v[16:31]
	v_max_i32_e32 v93, 0, v14
	v_fmac_f32_e32 v94, v62, v93
	v_max_i32_e32 v93, 0, v15
	v_fmac_f32_e32 v94, v63, v93
	s_cmp_eq_u32 s58, 2
	v_or_b32_e32 v93, 32, v130
	s_cselect_b64 s[50:51], -1, 0
	v_cmp_gt_i32_e32 vcc, v93, v203
	s_and_b64 vcc, s[50:51], vcc
	s_nop 0
	v_cndmask_b32_e32 v201, v94, v197, vcc
.Lixj111:
.LBB0_1147:
	s_and_b64 vcc, exec, s[48:49]
	s_cbranch_vccnz .LBB0_1149

.Lixj110:
.LBB0_1153:
	s_and_b64 vcc, exec, s[50:51]
	s_cbranch_vccnz .LBB0_1155

.LBB0_1188:
	ds_read_b128 v[16:19], v134 offset:0
	ds_read_b128 v[80:83], v134 offset:32
	ds_read_b128 v[84:87], v134 offset:64
	ds_read_b128 v[92:95], v134 offset:0x60
	v_max_i32_e32 v88, 0, v0
	s_waitcnt lgkmcnt(0)
	v_max_i32_e32 v89, 0, v1
	v_mfma_f32_32x32x16_bf16 v[16:31], v[32:35], v[16:19], 0
	v_fma_f32 v116, v48, v88, 0
	v_max_i32_e32 v90, 0, v2
	v_fmac_f32_e32 v116, v49, v89
	v_max_i32_e32 v91, 0, v3
	v_fmac_f32_e32 v116, v50, v90
	v_max_i32_e32 v96, 0, v4
	v_fmac_f32_e32 v116, v51, v91
	v_mfma_f32_32x32x16_bf16 v[16:31], v[36:39], v[80:83], v[16:31]
	v_max_i32_e32 v97, 0, v5
	v_fmac_f32_e32 v116, v52, v96
	v_max_i32_e32 v98, 0, v6
	v_fmac_f32_e32 v116, v53, v97
	v_max_i32_e32 v99, 0, v7
	v_fmac_f32_e32 v116, v54, v98
	v_max_i32_e32 v100, 0, v8
	v_mfma_f32_32x32x16_bf16 v[16:31], v[40:43], v[84:87], v[16:31]
	v_fmac_f32_e32 v116, v55, v99
	v_max_i32_e32 v101, 0, v9
	v_fmac_f32_e32 v116, v56, v100
	v_max_i32_e32 v102, 0, v10
	v_fmac_f32_e32 v116, v57, v101
	v_max_i32_e32 v103, 0, v11
	v_fmac_f32_e32 v116, v58, v102
	v_fmac_f32_e32 v116, v59, v103
	v_max_i32_e32 v84, 0, v12
	ds_read_b128 v[80:83], v134 offset:0x1200
	v_fmac_f32_e32 v116, v60, v84
	v_max_i32_e32 v84, 0, v13
	ds_read_b128 v[88:91], v134 offset:0x1220
	v_fmac_f32_e32 v116, v61, v84
	v_max_i32_e32 v84, 0, v14
	ds_read_b128 v[96:99], v134 offset:0x1240
	v_fmac_f32_e32 v116, v62, v84
	v_max_i32_e32 v84, 0, v15
	ds_read_b128 v[104:107], v134 offset:0x1260
	v_mfma_f32_32x32x16_bf16 v[16:31], v[44:47], v[92:95], v[16:31]
	v_fmac_f32_e32 v116, v63, v84
	s_waitcnt lgkmcnt(0)
	ds_read_b128 v[108:111], v134 offset:0x2400
	ds_read_b128 v[100:103], v134 offset:0x2420
	ds_read_b128 v[92:95], v134 offset:0x2440
	ds_read_b128 v[84:87], v134 offset:0x2460
	s_cmp_eq_u32 s58, 9
	s_cselect_b64 s[52:53], -1, 0
	s_cmp_lg_u32 s58, 9
	s_cselect_b64 s[66:67], -1, 0
	s_and_b64 vcc, exec, s[52:53]
	s_cbranch_vccnz .Lixc105
	v_mfma_f32_32x32x16_bf16 v[0:15], v[32:35], v[80:83], 0
	v_max_i32_e32 v81, 0, v16
	v_fma_f32 v82, v48, v81, 0
	v_max_i32_e32 v81, 0, v17
	v_fmac_f32_e32 v82, v49, v81
	v_max_i32_e32 v81, 0, v18
	v_fmac_f32_e32 v82, v50, v81
	v_max_i32_e32 v81, 0, v19
	v_fmac_f32_e32 v82, v51, v81
	v_max_i32_e32 v81, 0, v20
	v_fmac_f32_e32 v82, v52, v81
	v_mfma_f32_32x32x16_bf16 v[0:15], v[36:39], v[88:91], v[0:15]
	v_max_i32_e32 v81, 0, v21
	v_fmac_f32_e32 v82, v53, v81
	v_max_i32_e32 v81, 0, v22
	v_fmac_f32_e32 v82, v54, v81
	v_max_i32_e32 v81, 0, v23
	v_fmac_f32_e32 v82, v55, v81
	v_max_i32_e32 v81, 0, v24
	v_fmac_f32_e32 v82, v56, v81
	v_max_i32_e32 v81, 0, v25
	v_fmac_f32_e32 v82, v57, v81
	v_mfma_f32_32x32x16_bf16 v[0:15], v[40:43], v[96:99], v[0:15]
	v_max_i32_e32 v81, 0, v26
	v_fmac_f32_e32 v82, v58, v81
	v_max_i32_e32 v81, 0, v27
	v_fmac_f32_e32 v82, v59, v81
	v_max_i32_e32 v81, 0, v28
	v_fmac_f32_e32 v82, v60, v81
	v_max_i32_e32 v81, 0, v29
	v_fmac_f32_e32 v82, v61, v81
	v_mfma_f32_32x32x16_bf16 v[0:15], v[44:47], v[104:107], v[0:15]
	v_max_i32_e32 v81, 0, v30
	v_fmac_f32_e32 v82, v62, v81
	v_max_i32_e32 v81, 0, v31
	v_cmp_gt_i32_e32 vcc, v135, v203
	v_fmac_f32_e32 v82, v63, v81
	s_and_b64 vcc, s[52:53], vcc
	v_cndmask_b32_e32 v117, v82, v197, vcc
.Lixj105:
	s_waitcnt lgkmcnt(0)
	ds_read_b128 v[96:99], v134 offset:0x3600
	ds_read_b128 v[88:91], v134 offset:0x3620
	ds_read_b128 v[80:83], v134 offset:0x3640
	ds_read_b128 v[104:107], v134 offset:0x3660
	s_cmp_gt_u32 s95, 19
	s_cselect_b64 s[64:65], -1, 0
	s_cmp_lt_u32 s95, 20
	s_cbranch_scc1 .Lixc104
	v_mfma_f32_32x32x16_bf16 v[16:31], v[32:35], v[108:111], 0
	v_cndmask_b32_e64 v109, 0, 1, s[66:67]
	v_cmp_ne_u32_e64 s[52:53], 1, v109
	s_andn2_b64 vcc, exec, s[66:67]
	v_max_i32_e32 v109, 0, v0
	v_fma_f32 v110, v48, v109, 0
	v_max_i32_e32 v109, 0, v1
	v_fmac_f32_e32 v110, v49, v109
	v_max_i32_e32 v109, 0, v2
	v_fmac_f32_e32 v110, v50, v109
	v_max_i32_e32 v109, 0, v3
	v_fmac_f32_e32 v110, v51, v109
	v_max_i32_e32 v109, 0, v4
	v_fmac_f32_e32 v110, v52, v109
	v_mfma_f32_32x32x16_bf16 v[16:31], v[36:39], v[100:103], v[16:31]
	v_max_i32_e32 v109, 0, v5
	v_fmac_f32_e32 v110, v53, v109
	v_max_i32_e32 v109, 0, v6
	v_fmac_f32_e32 v110, v54, v109
	v_max_i32_e32 v109, 0, v7
	v_fmac_f32_e32 v110, v55, v109
	v_max_i32_e32 v109, 0, v8
	v_fmac_f32_e32 v110, v56, v109
	v_max_i32_e32 v109, 0, v9
	v_fmac_f32_e32 v110, v57, v109
	v_mfma_f32_32x32x16_bf16 v[16:31], v[40:43], v[92:95], v[16:31]
	v_max_i32_e32 v109, 0, v10
	v_fmac_f32_e32 v110, v58, v109
	v_max_i32_e32 v109, 0, v11
	v_fmac_f32_e32 v110, v59, v109
	v_max_i32_e32 v109, 0, v12
	v_fmac_f32_e32 v110, v60, v109
	v_max_i32_e32 v109, 0, v13
	v_fmac_f32_e32 v110, v61, v109
	v_mfma_f32_32x32x16_bf16 v[16:31], v[44:47], v[84:87], v[16:31]
	v_max_i32_e32 v109, 0, v14
	s_cmp_eq_u32 s58, 10
	v_fmac_f32_e32 v110, v62, v109
	v_max_i32_e32 v109, 0, v15
	s_cselect_b64 s[66:67], -1, 0
	v_cmp_gt_i32_e32 vcc, v136, v203
	v_fmac_f32_e32 v110, v63, v109
	s_and_b64 vcc, s[66:67], vcc
	v_cndmask_b32_e32 v118, v110, v197, vcc
.Lixj104:
.LBB0_1194:
	s_and_b64 vcc, exec, s[52:53]
	s_cbranch_vccnz .LBB0_1196

.LBB0_1232:
	ds_read_b128 v[16:19], v131 offset:0
	ds_read_b128 v[80:83], v131 offset:32
	ds_read_b128 v[84:87], v131 offset:64
	ds_read_b128 v[92:95], v131 offset:0x60
	v_max_i32_e32 v88, 0, v0
	s_waitcnt lgkmcnt(0)
	v_max_i32_e32 v89, 0, v1
	v_mfma_f32_32x32x16_bf16 v[16:31], v[32:35], v[16:19], 0
	v_fma_f32 v209, v48, v88, 0
	v_max_i32_e32 v90, 0, v2
	v_fmac_f32_e32 v209, v49, v89
	v_max_i32_e32 v91, 0, v3
	v_fmac_f32_e32 v209, v50, v90
	v_max_i32_e32 v96, 0, v4
	v_fmac_f32_e32 v209, v51, v91
	v_mfma_f32_32x32x16_bf16 v[16:31], v[36:39], v[80:83], v[16:31]
	v_max_i32_e32 v97, 0, v5
	v_fmac_f32_e32 v209, v52, v96
	v_max_i32_e32 v98, 0, v6
	v_fmac_f32_e32 v209, v53, v97
	v_max_i32_e32 v99, 0, v7
	v_fmac_f32_e32 v209, v54, v98
	v_max_i32_e32 v100, 0, v8
	v_mfma_f32_32x32x16_bf16 v[16:31], v[40:43], v[84:87], v[16:31]
	v_fmac_f32_e32 v209, v55, v99
	v_max_i32_e32 v101, 0, v9
	v_fmac_f32_e32 v209, v56, v100
	v_max_i32_e32 v102, 0, v10
	v_fmac_f32_e32 v209, v57, v101
	v_max_i32_e32 v103, 0, v11
	v_fmac_f32_e32 v209, v58, v102
	v_fmac_f32_e32 v209, v59, v103
	v_max_i32_e32 v84, 0, v12
	ds_read_b128 v[80:83], v131 offset:0x1200
	v_fmac_f32_e32 v209, v60, v84
	v_max_i32_e32 v84, 0, v13
	ds_read_b128 v[88:91], v131 offset:0x1220
	v_fmac_f32_e32 v209, v61, v84
	v_max_i32_e32 v84, 0, v14
	ds_read_b128 v[96:99], v131 offset:0x1240
	v_fmac_f32_e32 v209, v62, v84
	v_max_i32_e32 v84, 0, v15
	ds_read_b128 v[104:107], v131 offset:0x1260
	v_mfma_f32_32x32x16_bf16 v[16:31], v[44:47], v[92:95], v[16:31]
	v_fmac_f32_e32 v209, v63, v84
	s_waitcnt lgkmcnt(0)
	ds_read_b128 v[108:111], v131 offset:0x2400
	ds_read_b128 v[100:103], v131 offset:0x2420
	ds_read_b128 v[92:95], v131 offset:0x2440
	ds_read_b128 v[84:87], v131 offset:0x2460
	s_cmp_eq_u32 s58, 17
	s_cselect_b64 s[52:53], -1, 0
	s_cmp_lg_u32 s58, 17
	s_cselect_b64 s[66:67], -1, 0
	s_and_b64 vcc, exec, s[52:53]
	s_cbranch_vccnz .Lixc98
	v_mfma_f32_32x32x16_bf16 v[0:15], v[32:35], v[80:83], 0
	v_max_i32_e32 v81, 0, v16
	v_fma_f32 v82, v48, v81, 0
	v_max_i32_e32 v81, 0, v17
	v_fmac_f32_e32 v82, v49, v81
	v_max_i32_e32 v81, 0, v18
	v_fmac_f32_e32 v82, v50, v81
	v_max_i32_e32 v81, 0, v19
	v_fmac_f32_e32 v82, v51, v81
	v_max_i32_e32 v81, 0, v20
	v_fmac_f32_e32 v82, v52, v81
	v_mfma_f32_32x32x16_bf16 v[0:15], v[36:39], v[88:91], v[0:15]
	v_max_i32_e32 v81, 0, v21
	v_fmac_f32_e32 v82, v53, v81
	v_max_i32_e32 v81, 0, v22
	v_fmac_f32_e32 v82, v54, v81
	v_max_i32_e32 v81, 0, v23
	v_fmac_f32_e32 v82, v55, v81
	v_max_i32_e32 v81, 0, v24
	v_fmac_f32_e32 v82, v56, v81
	v_max_i32_e32 v81, 0, v25
	v_fmac_f32_e32 v82, v57, v81
	v_mfma_f32_32x32x16_bf16 v[0:15], v[40:43], v[96:99], v[0:15]
	v_max_i32_e32 v81, 0, v26
	v_fmac_f32_e32 v82, v58, v81
	v_max_i32_e32 v81, 0, v27
	v_fmac_f32_e32 v82, v59, v81
	v_max_i32_e32 v81, 0, v28
	v_fmac_f32_e32 v82, v60, v81
	v_max_i32_e32 v81, 0, v29
	v_fmac_f32_e32 v82, v61, v81
	v_mfma_f32_32x32x16_bf16 v[0:15], v[44:47], v[104:107], v[0:15]
	v_max_i32_e32 v81, 0, v30
	v_fmac_f32_e32 v82, v62, v81
	v_max_i32_e32 v81, 0, v31
	v_cmp_gt_i32_e32 vcc, v143, v203
	v_fmac_f32_e32 v82, v63, v81
	s_and_b64 vcc, s[52:53], vcc
	v_cndmask_b32_e32 v210, v82, v197, vcc
.Lixj98:
	s_waitcnt lgkmcnt(0)
	ds_read_b128 v[96:99], v131 offset:0x3600
	ds_read_b128 v[88:91], v131 offset:0x3620
	ds_read_b128 v[80:83], v131 offset:0x3640
	ds_read_b128 v[104:107], v131 offset:0x3660
	s_cmp_gt_u32 s95, 35
	s_cselect_b64 s[64:65], -1, 0
	s_cmp_lt_u32 s95, 36
	s_cbranch_scc1 .Lixc97
	v_mfma_f32_32x32x16_bf16 v[16:31], v[32:35], v[108:111], 0
	v_cndmask_b32_e64 v109, 0, 1, s[66:67]
	v_cmp_ne_u32_e64 s[52:53], 1, v109
	s_andn2_b64 vcc, exec, s[66:67]
	v_max_i32_e32 v109, 0, v0
	v_fma_f32 v110, v48, v109, 0
	v_max_i32_e32 v109, 0, v1
	v_fmac_f32_e32 v110, v49, v109
	v_max_i32_e32 v109, 0, v2
	v_fmac_f32_e32 v110, v50, v109
	v_max_i32_e32 v109, 0, v3
	v_fmac_f32_e32 v110, v51, v109
	v_max_i32_e32 v109, 0, v4
	v_fmac_f32_e32 v110, v52, v109
	v_mfma_f32_32x32x16_bf16 v[16:31], v[36:39], v[100:103], v[16:31]
	v_max_i32_e32 v109, 0, v5
	v_fmac_f32_e32 v110, v53, v109
	v_max_i32_e32 v109, 0, v6
	v_fmac_f32_e32 v110, v54, v109
	v_max_i32_e32 v109, 0, v7
	v_fmac_f32_e32 v110, v55, v109
	v_max_i32_e32 v109, 0, v8
	v_fmac_f32_e32 v110, v56, v109
	v_max_i32_e32 v109, 0, v9
	v_fmac_f32_e32 v110, v57, v109
	v_mfma_f32_32x32x16_bf16 v[16:31], v[40:43], v[92:95], v[16:31]
	v_max_i32_e32 v109, 0, v10
	v_fmac_f32_e32 v110, v58, v109
	v_max_i32_e32 v109, 0, v11
	v_fmac_f32_e32 v110, v59, v109
	v_max_i32_e32 v109, 0, v12
	v_fmac_f32_e32 v110, v60, v109
	v_max_i32_e32 v109, 0, v13
	v_fmac_f32_e32 v110, v61, v109
	v_mfma_f32_32x32x16_bf16 v[16:31], v[44:47], v[84:87], v[16:31]
	v_max_i32_e32 v109, 0, v14
	s_cmp_eq_u32 s58, 18
	v_fmac_f32_e32 v110, v62, v109
	v_max_i32_e32 v109, 0, v15
	s_cselect_b64 s[66:67], -1, 0
	v_cmp_gt_i32_e32 vcc, v144, v203
	v_fmac_f32_e32 v110, v63, v109
	s_and_b64 vcc, s[66:67], vcc
	v_cndmask_b32_e32 v211, v110, v197, vcc

.LBB0_1276:
	ds_read_b128 v[16:19], v134 offset:0
	ds_read_b128 v[80:83], v134 offset:32
	ds_read_b128 v[84:87], v134 offset:64
	ds_read_b128 v[92:95], v134 offset:0x60
	v_max_i32_e32 v88, 0, v0
	s_waitcnt lgkmcnt(0)
	v_max_i32_e32 v89, 0, v1
	v_mfma_f32_32x32x16_bf16 v[16:31], v[32:35], v[16:19], 0
	v_fma_f32 v218, v48, v88, 0
	v_max_i32_e32 v90, 0, v2
	v_fmac_f32_e32 v218, v49, v89
	v_max_i32_e32 v91, 0, v3
	v_fmac_f32_e32 v218, v50, v90
	v_max_i32_e32 v96, 0, v4
	v_fmac_f32_e32 v218, v51, v91
	v_mfma_f32_32x32x16_bf16 v[16:31], v[36:39], v[80:83], v[16:31]
	v_max_i32_e32 v97, 0, v5
	v_fmac_f32_e32 v218, v52, v96
	v_max_i32_e32 v98, 0, v6
	v_fmac_f32_e32 v218, v53, v97
	v_max_i32_e32 v99, 0, v7
	v_fmac_f32_e32 v218, v54, v98
	v_max_i32_e32 v100, 0, v8
	v_mfma_f32_32x32x16_bf16 v[16:31], v[40:43], v[84:87], v[16:31]
	v_fmac_f32_e32 v218, v55, v99
	v_max_i32_e32 v101, 0, v9
	v_fmac_f32_e32 v218, v56, v100
	v_max_i32_e32 v102, 0, v10
	v_fmac_f32_e32 v218, v57, v101
	v_max_i32_e32 v103, 0, v11
	v_fmac_f32_e32 v218, v58, v102
	v_fmac_f32_e32 v218, v59, v103
	v_max_i32_e32 v84, 0, v12
	ds_read_b128 v[80:83], v134 offset:0x1200
	v_fmac_f32_e32 v218, v60, v84
	v_max_i32_e32 v84, 0, v13
	ds_read_b128 v[88:91], v134 offset:0x1220
	v_fmac_f32_e32 v218, v61, v84
	v_max_i32_e32 v84, 0, v14
	ds_read_b128 v[96:99], v134 offset:0x1240
	v_fmac_f32_e32 v218, v62, v84
	v_max_i32_e32 v84, 0, v15
	ds_read_b128 v[104:107], v134 offset:0x1260
	v_mfma_f32_32x32x16_bf16 v[16:31], v[44:47], v[92:95], v[16:31]
	v_fmac_f32_e32 v218, v63, v84
	s_waitcnt lgkmcnt(0)
	ds_read_b128 v[108:111], v134 offset:0x2400
	ds_read_b128 v[100:103], v134 offset:0x2420
	ds_read_b128 v[92:95], v134 offset:0x2440
	ds_read_b128 v[84:87], v134 offset:0x2460
	s_cmp_eq_u32 s58, 25
	s_cselect_b64 s[52:53], -1, 0
	s_cmp_lg_u32 s58, 25
	s_cselect_b64 s[66:67], -1, 0
	s_and_b64 vcc, exec, s[52:53]
	s_cbranch_vccnz .Lixc91
	v_mfma_f32_32x32x16_bf16 v[0:15], v[32:35], v[80:83], 0
	v_max_i32_e32 v81, 0, v16
	v_fma_f32 v82, v48, v81, 0
	v_max_i32_e32 v81, 0, v17
	v_fmac_f32_e32 v82, v49, v81
	v_max_i32_e32 v81, 0, v18
	v_fmac_f32_e32 v82, v50, v81
	v_max_i32_e32 v81, 0, v19
	v_fmac_f32_e32 v82, v51, v81
	v_max_i32_e32 v81, 0, v20
	v_fmac_f32_e32 v82, v52, v81
	v_mfma_f32_32x32x16_bf16 v[0:15], v[36:39], v[88:91], v[0:15]
	v_max_i32_e32 v81, 0, v21
	v_fmac_f32_e32 v82, v53, v81
	v_max_i32_e32 v81, 0, v22
	v_fmac_f32_e32 v82, v54, v81
	v_max_i32_e32 v81, 0, v23
	v_fmac_f32_e32 v82, v55, v81
	v_max_i32_e32 v81, 0, v24
	v_fmac_f32_e32 v82, v56, v81
	v_max_i32_e32 v81, 0, v25
	v_fmac_f32_e32 v82, v57, v81
	v_mfma_f32_32x32x16_bf16 v[0:15], v[40:43], v[96:99], v[0:15]
	v_max_i32_e32 v81, 0, v26
	v_fmac_f32_e32 v82, v58, v81
	v_max_i32_e32 v81, 0, v27
	v_fmac_f32_e32 v82, v59, v81
	v_max_i32_e32 v81, 0, v28
	v_fmac_f32_e32 v82, v60, v81
	v_max_i32_e32 v81, 0, v29
	v_fmac_f32_e32 v82, v61, v81
	v_mfma_f32_32x32x16_bf16 v[0:15], v[44:47], v[104:107], v[0:15]
	v_max_i32_e32 v81, 0, v30
	v_fmac_f32_e32 v82, v62, v81
	v_max_i32_e32 v81, 0, v31
	v_cmp_gt_i32_e32 vcc, v151, v203
	v_fmac_f32_e32 v82, v63, v81
	s_and_b64 vcc, s[52:53], vcc
	v_cndmask_b32_e32 v219, v82, v197, vcc
.Lixj91:
	s_waitcnt lgkmcnt(0)
	ds_read_b128 v[96:99], v134 offset:0x3600
	ds_read_b128 v[88:91], v134 offset:0x3620
	ds_read_b128 v[80:83], v134 offset:0x3640
	ds_read_b128 v[104:107], v134 offset:0x3660
	s_cmp_gt_u32 s95, 51
	s_cselect_b64 s[64:65], -1, 0
	s_cmp_lt_u32 s95, 52
	s_cbranch_scc1 .Lixc90
	v_mfma_f32_32x32x16_bf16 v[16:31], v[32:35], v[108:111], 0
	v_cndmask_b32_e64 v109, 0, 1, s[66:67]
	v_cmp_ne_u32_e64 s[52:53], 1, v109
	s_andn2_b64 vcc, exec, s[66:67]
	v_max_i32_e32 v109, 0, v0
	v_fma_f32 v110, v48, v109, 0
	v_max_i32_e32 v109, 0, v1
	v_fmac_f32_e32 v110, v49, v109
	v_max_i32_e32 v109, 0, v2
	v_fmac_f32_e32 v110, v50, v109
	v_max_i32_e32 v109, 0, v3
	v_fmac_f32_e32 v110, v51, v109
	v_max_i32_e32 v109, 0, v4
	v_fmac_f32_e32 v110, v52, v109
	v_mfma_f32_32x32x16_bf16 v[16:31], v[36:39], v[100:103], v[16:31]
	v_max_i32_e32 v109, 0, v5
	v_fmac_f32_e32 v110, v53, v109
	v_max_i32_e32 v109, 0, v6
	v_fmac_f32_e32 v110, v54, v109
	v_max_i32_e32 v109, 0, v7
	v_fmac_f32_e32 v110, v55, v109
	v_max_i32_e32 v109, 0, v8
	v_fmac_f32_e32 v110, v56, v109
	v_max_i32_e32 v109, 0, v9
	v_fmac_f32_e32 v110, v57, v109
	v_mfma_f32_32x32x16_bf16 v[16:31], v[40:43], v[92:95], v[16:31]
	v_max_i32_e32 v109, 0, v10
	v_fmac_f32_e32 v110, v58, v109
	v_max_i32_e32 v109, 0, v11
	v_fmac_f32_e32 v110, v59, v109
	v_max_i32_e32 v109, 0, v12
	v_fmac_f32_e32 v110, v60, v109
	v_max_i32_e32 v109, 0, v13
	v_fmac_f32_e32 v110, v61, v109
	v_mfma_f32_32x32x16_bf16 v[16:31], v[44:47], v[84:87], v[16:31]
	v_max_i32_e32 v109, 0, v14
	s_cmp_eq_u32 s58, 26
	v_fmac_f32_e32 v110, v62, v109
	v_max_i32_e32 v109, 0, v15
	s_cselect_b64 s[66:67], -1, 0
	v_cmp_gt_i32_e32 vcc, v152, v203
	v_fmac_f32_e32 v110, v63, v109
	s_and_b64 vcc, s[66:67], vcc
	v_cndmask_b32_e32 v220, v110, v197, vcc

.LBB0_1320:
	ds_read_b128 v[16:19], v131 offset:0
	ds_read_b128 v[80:83], v131 offset:32
	ds_read_b128 v[84:87], v131 offset:64
	ds_read_b128 v[92:95], v131 offset:0x60
	v_max_i32_e32 v88, 0, v0
	s_waitcnt lgkmcnt(0)
	v_max_i32_e32 v89, 0, v1
	v_mfma_f32_32x32x16_bf16 v[16:31], v[32:35], v[16:19], 0
	v_fma_f32 v226, v48, v88, 0
	v_max_i32_e32 v90, 0, v2
	v_fmac_f32_e32 v226, v49, v89
	v_max_i32_e32 v91, 0, v3
	v_fmac_f32_e32 v226, v50, v90
	v_max_i32_e32 v96, 0, v4
	v_fmac_f32_e32 v226, v51, v91
	v_mfma_f32_32x32x16_bf16 v[16:31], v[36:39], v[80:83], v[16:31]
	v_max_i32_e32 v97, 0, v5
	v_fmac_f32_e32 v226, v52, v96
	v_max_i32_e32 v98, 0, v6
	v_fmac_f32_e32 v226, v53, v97
	v_max_i32_e32 v99, 0, v7
	v_fmac_f32_e32 v226, v54, v98
	v_max_i32_e32 v100, 0, v8
	v_mfma_f32_32x32x16_bf16 v[16:31], v[40:43], v[84:87], v[16:31]
	v_fmac_f32_e32 v226, v55, v99
	v_max_i32_e32 v101, 0, v9
	v_fmac_f32_e32 v226, v56, v100
	v_max_i32_e32 v102, 0, v10
	v_fmac_f32_e32 v226, v57, v101
	v_max_i32_e32 v103, 0, v11
	v_fmac_f32_e32 v226, v58, v102
	v_fmac_f32_e32 v226, v59, v103
	v_max_i32_e32 v84, 0, v12
	ds_read_b128 v[80:83], v131 offset:0x1200
	v_fmac_f32_e32 v226, v60, v84
	v_max_i32_e32 v84, 0, v13
	ds_read_b128 v[88:91], v131 offset:0x1220
	v_fmac_f32_e32 v226, v61, v84
	v_max_i32_e32 v84, 0, v14
	ds_read_b128 v[96:99], v131 offset:0x1240
	v_fmac_f32_e32 v226, v62, v84
	v_max_i32_e32 v84, 0, v15
	ds_read_b128 v[104:107], v131 offset:0x1260
	v_mfma_f32_32x32x16_bf16 v[16:31], v[44:47], v[92:95], v[16:31]
	v_fmac_f32_e32 v226, v63, v84
	s_waitcnt lgkmcnt(0)
	ds_read_b128 v[108:111], v131 offset:0x2400
	ds_read_b128 v[100:103], v131 offset:0x2420
	ds_read_b128 v[92:95], v131 offset:0x2440
	ds_read_b128 v[84:87], v131 offset:0x2460
	s_cmp_eq_u32 s58, 33
	s_cselect_b64 s[52:53], -1, 0
	s_cmp_lg_u32 s58, 33
	s_cselect_b64 s[66:67], -1, 0
	s_and_b64 vcc, exec, s[52:53]
	s_cbranch_vccnz .Lixc84
	v_mfma_f32_32x32x16_bf16 v[0:15], v[32:35], v[80:83], 0
	v_max_i32_e32 v81, 0, v16
	v_fma_f32 v82, v48, v81, 0
	v_max_i32_e32 v81, 0, v17
	v_fmac_f32_e32 v82, v49, v81
	v_max_i32_e32 v81, 0, v18
	v_fmac_f32_e32 v82, v50, v81
	v_max_i32_e32 v81, 0, v19
	v_fmac_f32_e32 v82, v51, v81
	v_max_i32_e32 v81, 0, v20
	v_fmac_f32_e32 v82, v52, v81
	v_mfma_f32_32x32x16_bf16 v[0:15], v[36:39], v[88:91], v[0:15]
	v_max_i32_e32 v81, 0, v21
	v_fmac_f32_e32 v82, v53, v81
	v_max_i32_e32 v81, 0, v22
	v_fmac_f32_e32 v82, v54, v81
	v_max_i32_e32 v81, 0, v23
	v_fmac_f32_e32 v82, v55, v81
	v_max_i32_e32 v81, 0, v24
	v_fmac_f32_e32 v82, v56, v81
	v_max_i32_e32 v81, 0, v25
	v_fmac_f32_e32 v82, v57, v81
	v_mfma_f32_32x32x16_bf16 v[0:15], v[40:43], v[96:99], v[0:15]
	v_max_i32_e32 v81, 0, v26
	v_fmac_f32_e32 v82, v58, v81
	v_max_i32_e32 v81, 0, v27
	v_fmac_f32_e32 v82, v59, v81
	v_max_i32_e32 v81, 0, v28
	v_fmac_f32_e32 v82, v60, v81
	v_max_i32_e32 v81, 0, v29
	v_fmac_f32_e32 v82, v61, v81
	v_mfma_f32_32x32x16_bf16 v[0:15], v[44:47], v[104:107], v[0:15]
	v_max_i32_e32 v81, 0, v30
	v_fmac_f32_e32 v82, v62, v81
	v_max_i32_e32 v81, 0, v31
	v_cmp_gt_i32_e32 vcc, v159, v203
	v_fmac_f32_e32 v82, v63, v81
	s_and_b64 vcc, s[52:53], vcc
	v_cndmask_b32_e32 v227, v82, v197, vcc
.Lixj84:
	s_waitcnt lgkmcnt(0)
	ds_read_b128 v[96:99], v131 offset:0x3600
	ds_read_b128 v[88:91], v131 offset:0x3620
	ds_read_b128 v[80:83], v131 offset:0x3640
	ds_read_b128 v[104:107], v131 offset:0x3660
	s_cmpk_gt_u32 s95, 0x43
	s_cselect_b64 s[64:65], -1, 0
	s_cmpk_lt_u32 s95, 0x44
	s_cbranch_scc1 .Lixc83
	v_mfma_f32_32x32x16_bf16 v[16:31], v[32:35], v[108:111], 0
	v_cndmask_b32_e64 v109, 0, 1, s[66:67]
	v_cmp_ne_u32_e64 s[52:53], 1, v109
	s_andn2_b64 vcc, exec, s[66:67]
	v_max_i32_e32 v109, 0, v0
	v_fma_f32 v110, v48, v109, 0
	v_max_i32_e32 v109, 0, v1
	v_fmac_f32_e32 v110, v49, v109
	v_max_i32_e32 v109, 0, v2
	v_fmac_f32_e32 v110, v50, v109
	v_max_i32_e32 v109, 0, v3
	v_fmac_f32_e32 v110, v51, v109
	v_max_i32_e32 v109, 0, v4
	v_fmac_f32_e32 v110, v52, v109
	v_mfma_f32_32x32x16_bf16 v[16:31], v[36:39], v[100:103], v[16:31]
	v_max_i32_e32 v109, 0, v5
	v_fmac_f32_e32 v110, v53, v109
	v_max_i32_e32 v109, 0, v6
	v_fmac_f32_e32 v110, v54, v109
	v_max_i32_e32 v109, 0, v7
	v_fmac_f32_e32 v110, v55, v109
	v_max_i32_e32 v109, 0, v8
	v_fmac_f32_e32 v110, v56, v109
	v_max_i32_e32 v109, 0, v9
	v_fmac_f32_e32 v110, v57, v109
	v_mfma_f32_32x32x16_bf16 v[16:31], v[40:43], v[92:95], v[16:31]
	v_max_i32_e32 v109, 0, v10
	v_fmac_f32_e32 v110, v58, v109
	v_max_i32_e32 v109, 0, v11
	v_fmac_f32_e32 v110, v59, v109
	v_max_i32_e32 v109, 0, v12
	v_fmac_f32_e32 v110, v60, v109
	v_max_i32_e32 v109, 0, v13
	v_fmac_f32_e32 v110, v61, v109
	v_mfma_f32_32x32x16_bf16 v[16:31], v[44:47], v[84:87], v[16:31]
	v_max_i32_e32 v109, 0, v14
	s_cmp_eq_u32 s58, 34
	v_fmac_f32_e32 v110, v62, v109
	v_max_i32_e32 v109, 0, v15
	s_cselect_b64 s[66:67], -1, 0
	v_cmp_gt_i32_e32 vcc, v160, v203
	v_fmac_f32_e32 v110, v63, v109
	s_and_b64 vcc, s[66:67], vcc
	v_cndmask_b32_e32 v228, v110, v197, vcc

.LBB0_1364:
	ds_read_b128 v[16:19], v134 offset:0
	ds_read_b128 v[80:83], v134 offset:32
	ds_read_b128 v[84:87], v134 offset:64
	ds_read_b128 v[92:95], v134 offset:0x60
	v_max_i32_e32 v88, 0, v0
	s_waitcnt lgkmcnt(0)
	v_max_i32_e32 v89, 0, v1
	v_mfma_f32_32x32x16_bf16 v[16:31], v[32:35], v[16:19], 0
	v_fma_f32 v234, v48, v88, 0
	v_max_i32_e32 v90, 0, v2
	v_fmac_f32_e32 v234, v49, v89
	v_max_i32_e32 v91, 0, v3
	v_fmac_f32_e32 v234, v50, v90
	v_max_i32_e32 v96, 0, v4
	v_fmac_f32_e32 v234, v51, v91
	v_mfma_f32_32x32x16_bf16 v[16:31], v[36:39], v[80:83], v[16:31]
	v_max_i32_e32 v97, 0, v5
	v_fmac_f32_e32 v234, v52, v96
	v_max_i32_e32 v98, 0, v6
	v_fmac_f32_e32 v234, v53, v97
	v_max_i32_e32 v99, 0, v7
	v_fmac_f32_e32 v234, v54, v98
	v_max_i32_e32 v100, 0, v8
	v_mfma_f32_32x32x16_bf16 v[16:31], v[40:43], v[84:87], v[16:31]
	v_fmac_f32_e32 v234, v55, v99
	v_max_i32_e32 v101, 0, v9
	v_fmac_f32_e32 v234, v56, v100
	v_max_i32_e32 v102, 0, v10
	v_fmac_f32_e32 v234, v57, v101
	v_max_i32_e32 v103, 0, v11
	v_fmac_f32_e32 v234, v58, v102
	v_fmac_f32_e32 v234, v59, v103
	v_max_i32_e32 v84, 0, v12
	ds_read_b128 v[80:83], v134 offset:0x1200
	v_fmac_f32_e32 v234, v60, v84
	v_max_i32_e32 v84, 0, v13
	ds_read_b128 v[88:91], v134 offset:0x1220
	v_fmac_f32_e32 v234, v61, v84
	v_max_i32_e32 v84, 0, v14
	ds_read_b128 v[96:99], v134 offset:0x1240
	v_fmac_f32_e32 v234, v62, v84
	v_max_i32_e32 v84, 0, v15
	ds_read_b128 v[104:107], v134 offset:0x1260
	v_mfma_f32_32x32x16_bf16 v[16:31], v[44:47], v[92:95], v[16:31]
	v_fmac_f32_e32 v234, v63, v84
	s_waitcnt lgkmcnt(0)
	ds_read_b128 v[108:111], v134 offset:0x2400
	ds_read_b128 v[100:103], v134 offset:0x2420
	ds_read_b128 v[92:95], v134 offset:0x2440
	ds_read_b128 v[84:87], v134 offset:0x2460
	s_cmp_eq_u32 s58, 41
	s_cselect_b64 s[52:53], -1, 0
	s_cmp_lg_u32 s58, 41
	s_cselect_b64 s[66:67], -1, 0
	s_and_b64 vcc, exec, s[52:53]
	s_cbranch_vccnz .Lixc77
	v_mfma_f32_32x32x16_bf16 v[0:15], v[32:35], v[80:83], 0
	v_max_i32_e32 v81, 0, v16
	v_fma_f32 v82, v48, v81, 0
	v_max_i32_e32 v81, 0, v17
	v_fmac_f32_e32 v82, v49, v81
	v_max_i32_e32 v81, 0, v18
	v_fmac_f32_e32 v82, v50, v81
	v_max_i32_e32 v81, 0, v19
	v_fmac_f32_e32 v82, v51, v81
	v_max_i32_e32 v81, 0, v20
	v_fmac_f32_e32 v82, v52, v81
	v_mfma_f32_32x32x16_bf16 v[0:15], v[36:39], v[88:91], v[0:15]
	v_max_i32_e32 v81, 0, v21
	v_fmac_f32_e32 v82, v53, v81
	v_max_i32_e32 v81, 0, v22
	v_fmac_f32_e32 v82, v54, v81
	v_max_i32_e32 v81, 0, v23
	v_fmac_f32_e32 v82, v55, v81
	v_max_i32_e32 v81, 0, v24
	v_fmac_f32_e32 v82, v56, v81
	v_max_i32_e32 v81, 0, v25
	v_fmac_f32_e32 v82, v57, v81
	v_mfma_f32_32x32x16_bf16 v[0:15], v[40:43], v[96:99], v[0:15]
	v_max_i32_e32 v81, 0, v26
	v_fmac_f32_e32 v82, v58, v81
	v_max_i32_e32 v81, 0, v27
	v_fmac_f32_e32 v82, v59, v81
	v_max_i32_e32 v81, 0, v28
	v_fmac_f32_e32 v82, v60, v81
	v_max_i32_e32 v81, 0, v29
	v_fmac_f32_e32 v82, v61, v81
	v_mfma_f32_32x32x16_bf16 v[0:15], v[44:47], v[104:107], v[0:15]
	v_max_i32_e32 v81, 0, v30
	v_fmac_f32_e32 v82, v62, v81
	v_max_i32_e32 v81, 0, v31
	v_cmp_gt_i32_e32 vcc, v167, v203
	v_fmac_f32_e32 v82, v63, v81
	s_and_b64 vcc, s[52:53], vcc
	v_cndmask_b32_e32 v235, v82, v197, vcc
.Lixj77:
	s_waitcnt lgkmcnt(0)
	ds_read_b128 v[96:99], v134 offset:0x3600
	ds_read_b128 v[88:91], v134 offset:0x3620
	ds_read_b128 v[80:83], v134 offset:0x3640
	ds_read_b128 v[104:107], v134 offset:0x3660
	s_cmpk_gt_u32 s95, 0x53
	s_cselect_b64 s[64:65], -1, 0
	s_cmpk_lt_u32 s95, 0x54
	s_cbranch_scc1 .Lixc76
	v_mfma_f32_32x32x16_bf16 v[16:31], v[32:35], v[108:111], 0
	v_cndmask_b32_e64 v109, 0, 1, s[66:67]
	v_cmp_ne_u32_e64 s[52:53], 1, v109
	s_andn2_b64 vcc, exec, s[66:67]
	v_max_i32_e32 v109, 0, v0
	v_fma_f32 v110, v48, v109, 0
	v_max_i32_e32 v109, 0, v1
	v_fmac_f32_e32 v110, v49, v109
	v_max_i32_e32 v109, 0, v2
	v_fmac_f32_e32 v110, v50, v109
	v_max_i32_e32 v109, 0, v3
	v_fmac_f32_e32 v110, v51, v109
	v_max_i32_e32 v109, 0, v4
	v_fmac_f32_e32 v110, v52, v109
	v_mfma_f32_32x32x16_bf16 v[16:31], v[36:39], v[100:103], v[16:31]
	v_max_i32_e32 v109, 0, v5
	v_fmac_f32_e32 v110, v53, v109
	v_max_i32_e32 v109, 0, v6
	v_fmac_f32_e32 v110, v54, v109
	v_max_i32_e32 v109, 0, v7
	v_fmac_f32_e32 v110, v55, v109
	v_max_i32_e32 v109, 0, v8
	v_fmac_f32_e32 v110, v56, v109
	v_max_i32_e32 v109, 0, v9
	v_fmac_f32_e32 v110, v57, v109
	v_mfma_f32_32x32x16_bf16 v[16:31], v[40:43], v[92:95], v[16:31]
	v_max_i32_e32 v109, 0, v10
	v_fmac_f32_e32 v110, v58, v109
	v_max_i32_e32 v109, 0, v11
	v_fmac_f32_e32 v110, v59, v109
	v_max_i32_e32 v109, 0, v12
	v_fmac_f32_e32 v110, v60, v109
	v_max_i32_e32 v109, 0, v13
	v_fmac_f32_e32 v110, v61, v109
	v_mfma_f32_32x32x16_bf16 v[16:31], v[44:47], v[84:87], v[16:31]
	v_max_i32_e32 v109, 0, v14
	s_cmp_eq_u32 s58, 42
	v_fmac_f32_e32 v110, v62, v109
	v_max_i32_e32 v109, 0, v15
	s_cselect_b64 s[66:67], -1, 0
	v_cmp_gt_i32_e32 vcc, v168, v203
	v_fmac_f32_e32 v110, v63, v109
	s_and_b64 vcc, s[66:67], vcc
	v_cndmask_b32_e32 v236, v110, v197, vcc

.LBB0_1408:
	ds_read_b128 v[16:19], v131 offset:0
	ds_read_b128 v[80:83], v131 offset:32
	ds_read_b128 v[84:87], v131 offset:64
	ds_read_b128 v[92:95], v131 offset:0x60
	v_max_i32_e32 v88, 0, v0
	s_waitcnt lgkmcnt(0)
	v_max_i32_e32 v89, 0, v1
	v_mfma_f32_32x32x16_bf16 v[16:31], v[32:35], v[16:19], 0
	v_fma_f32 v242, v48, v88, 0
	v_max_i32_e32 v90, 0, v2
	v_fmac_f32_e32 v242, v49, v89
	v_max_i32_e32 v91, 0, v3
	v_fmac_f32_e32 v242, v50, v90
	v_max_i32_e32 v96, 0, v4
	v_fmac_f32_e32 v242, v51, v91
	v_mfma_f32_32x32x16_bf16 v[16:31], v[36:39], v[80:83], v[16:31]
	v_max_i32_e32 v97, 0, v5
	v_fmac_f32_e32 v242, v52, v96
	v_max_i32_e32 v98, 0, v6
	v_fmac_f32_e32 v242, v53, v97
	v_max_i32_e32 v99, 0, v7
	v_fmac_f32_e32 v242, v54, v98
	v_max_i32_e32 v100, 0, v8
	v_mfma_f32_32x32x16_bf16 v[16:31], v[40:43], v[84:87], v[16:31]
	v_fmac_f32_e32 v242, v55, v99
	v_max_i32_e32 v101, 0, v9
	v_fmac_f32_e32 v242, v56, v100
	v_max_i32_e32 v102, 0, v10
	v_fmac_f32_e32 v242, v57, v101
	v_max_i32_e32 v103, 0, v11
	v_fmac_f32_e32 v242, v58, v102
	v_fmac_f32_e32 v242, v59, v103
	v_max_i32_e32 v84, 0, v12
	ds_read_b128 v[80:83], v131 offset:0x1200
	v_fmac_f32_e32 v242, v60, v84
	v_max_i32_e32 v84, 0, v13
	ds_read_b128 v[88:91], v131 offset:0x1220
	v_fmac_f32_e32 v242, v61, v84
	v_max_i32_e32 v84, 0, v14
	ds_read_b128 v[96:99], v131 offset:0x1240
	v_fmac_f32_e32 v242, v62, v84
	v_max_i32_e32 v84, 0, v15
	ds_read_b128 v[104:107], v131 offset:0x1260
	v_mfma_f32_32x32x16_bf16 v[16:31], v[44:47], v[92:95], v[16:31]
	v_fmac_f32_e32 v242, v63, v84
	s_waitcnt lgkmcnt(0)
	ds_read_b128 v[108:111], v131 offset:0x2400
	ds_read_b128 v[100:103], v131 offset:0x2420
	ds_read_b128 v[92:95], v131 offset:0x2440
	ds_read_b128 v[84:87], v131 offset:0x2460
	s_cmp_eq_u32 s58, 49
	s_cselect_b64 s[52:53], -1, 0
	s_cmp_lg_u32 s58, 49
	s_cselect_b64 s[64:65], -1, 0
	s_and_b64 vcc, exec, s[52:53]
	s_cbranch_vccnz .Lixc70
	v_mfma_f32_32x32x16_bf16 v[0:15], v[32:35], v[80:83], 0
	v_max_i32_e32 v81, 0, v16
	v_fma_f32 v82, v48, v81, 0
	v_max_i32_e32 v81, 0, v17
	v_fmac_f32_e32 v82, v49, v81
	v_max_i32_e32 v81, 0, v18
	v_fmac_f32_e32 v82, v50, v81
	v_max_i32_e32 v81, 0, v19
	v_fmac_f32_e32 v82, v51, v81
	v_max_i32_e32 v81, 0, v20
	v_fmac_f32_e32 v82, v52, v81
	v_mfma_f32_32x32x16_bf16 v[0:15], v[36:39], v[88:91], v[0:15]
	v_max_i32_e32 v81, 0, v21
	v_fmac_f32_e32 v82, v53, v81
	v_max_i32_e32 v81, 0, v22
	v_fmac_f32_e32 v82, v54, v81
	v_max_i32_e32 v81, 0, v23
	v_fmac_f32_e32 v82, v55, v81
	v_max_i32_e32 v81, 0, v24
	v_fmac_f32_e32 v82, v56, v81
	v_max_i32_e32 v81, 0, v25
	v_fmac_f32_e32 v82, v57, v81
	v_mfma_f32_32x32x16_bf16 v[0:15], v[40:43], v[96:99], v[0:15]
	v_max_i32_e32 v81, 0, v26
	v_fmac_f32_e32 v82, v58, v81
	v_max_i32_e32 v81, 0, v27
	v_fmac_f32_e32 v82, v59, v81
	v_max_i32_e32 v81, 0, v28
	v_fmac_f32_e32 v82, v60, v81
	v_max_i32_e32 v81, 0, v29
	v_fmac_f32_e32 v82, v61, v81
	v_mfma_f32_32x32x16_bf16 v[0:15], v[44:47], v[104:107], v[0:15]
	v_max_i32_e32 v81, 0, v30
	v_fmac_f32_e32 v82, v62, v81
	v_max_i32_e32 v81, 0, v31
	v_cmp_gt_i32_e32 vcc, v175, v203
	v_fmac_f32_e32 v82, v63, v81
	s_and_b64 vcc, s[52:53], vcc
	v_cndmask_b32_e32 v243, v82, v197, vcc
.Lixj70:
	s_waitcnt lgkmcnt(0)
	ds_read_b128 v[96:99], v131 offset:0x3600
	ds_read_b128 v[88:91], v131 offset:0x3620
	ds_read_b128 v[80:83], v131 offset:0x3640
	ds_read_b128 v[104:107], v131 offset:0x3660
	s_cmpk_gt_u32 s95, 0x63
	s_cselect_b64 s[60:61], -1, 0
	s_cmpk_lt_u32 s95, 0x64
	s_cbranch_scc1 .Lixc69
	v_mfma_f32_32x32x16_bf16 v[16:31], v[32:35], v[108:111], 0
	v_cndmask_b32_e64 v109, 0, 1, s[64:65]
	v_cmp_ne_u32_e64 s[52:53], 1, v109
	s_andn2_b64 vcc, exec, s[64:65]
	v_max_i32_e32 v109, 0, v0
	v_fma_f32 v110, v48, v109, 0
	v_max_i32_e32 v109, 0, v1
	v_fmac_f32_e32 v110, v49, v109
	v_max_i32_e32 v109, 0, v2
	v_fmac_f32_e32 v110, v50, v109
	v_max_i32_e32 v109, 0, v3
	v_fmac_f32_e32 v110, v51, v109
	v_max_i32_e32 v109, 0, v4
	v_fmac_f32_e32 v110, v52, v109
	v_mfma_f32_32x32x16_bf16 v[16:31], v[36:39], v[100:103], v[16:31]
	v_max_i32_e32 v109, 0, v5
	v_fmac_f32_e32 v110, v53, v109
	v_max_i32_e32 v109, 0, v6
	v_fmac_f32_e32 v110, v54, v109
	v_max_i32_e32 v109, 0, v7
	v_fmac_f32_e32 v110, v55, v109
	v_max_i32_e32 v109, 0, v8
	v_fmac_f32_e32 v110, v56, v109
	v_max_i32_e32 v109, 0, v9
	v_fmac_f32_e32 v110, v57, v109
	v_mfma_f32_32x32x16_bf16 v[16:31], v[40:43], v[92:95], v[16:31]
	v_max_i32_e32 v109, 0, v10
	v_fmac_f32_e32 v110, v58, v109
	v_max_i32_e32 v109, 0, v11
	v_fmac_f32_e32 v110, v59, v109
	v_max_i32_e32 v109, 0, v12
	v_fmac_f32_e32 v110, v60, v109
	v_max_i32_e32 v109, 0, v13
	v_fmac_f32_e32 v110, v61, v109
	v_mfma_f32_32x32x16_bf16 v[16:31], v[44:47], v[84:87], v[16:31]
	v_max_i32_e32 v109, 0, v14
	s_cmp_eq_u32 s58, 50
	v_fmac_f32_e32 v110, v62, v109
	v_max_i32_e32 v109, 0, v15
	s_cselect_b64 s[64:65], -1, 0
	v_cmp_gt_i32_e32 vcc, v176, v203
	v_fmac_f32_e32 v110, v63, v109
	s_and_b64 vcc, s[64:65], vcc
	v_cndmask_b32_e32 v244, v110, v197, vcc

.LBB0_1450:
	ds_read_b128 v[16:19], v134 offset:0
	ds_read_b128 v[80:83], v134 offset:32
	ds_read_b128 v[84:87], v134 offset:64
	ds_read_b128 v[92:95], v134 offset:0x60
	v_max_i32_e32 v88, 0, v0
	s_waitcnt lgkmcnt(0)
	v_max_i32_e32 v89, 0, v1
	v_mfma_f32_32x32x16_bf16 v[16:31], v[32:35], v[16:19], 0
	v_fma_f32 v250, v48, v88, 0
	v_max_i32_e32 v90, 0, v2
	v_fmac_f32_e32 v250, v49, v89
	v_max_i32_e32 v91, 0, v3
	v_fmac_f32_e32 v250, v50, v90
	v_max_i32_e32 v96, 0, v4
	v_fmac_f32_e32 v250, v51, v91
	v_mfma_f32_32x32x16_bf16 v[16:31], v[36:39], v[80:83], v[16:31]
	v_max_i32_e32 v97, 0, v5
	v_fmac_f32_e32 v250, v52, v96
	v_max_i32_e32 v98, 0, v6
	v_fmac_f32_e32 v250, v53, v97
	v_max_i32_e32 v99, 0, v7
	v_fmac_f32_e32 v250, v54, v98
	v_max_i32_e32 v100, 0, v8
	v_mfma_f32_32x32x16_bf16 v[16:31], v[40:43], v[84:87], v[16:31]
	v_fmac_f32_e32 v250, v55, v99
	v_max_i32_e32 v101, 0, v9
	v_fmac_f32_e32 v250, v56, v100
	v_max_i32_e32 v102, 0, v10
	v_fmac_f32_e32 v250, v57, v101
	v_max_i32_e32 v103, 0, v11
	v_fmac_f32_e32 v250, v58, v102
	v_fmac_f32_e32 v250, v59, v103
	v_max_i32_e32 v84, 0, v12
	ds_read_b128 v[80:83], v134 offset:0x1200
	v_fmac_f32_e32 v250, v60, v84
	v_max_i32_e32 v84, 0, v13
	ds_read_b128 v[88:91], v134 offset:0x1220
	v_fmac_f32_e32 v250, v61, v84
	v_max_i32_e32 v84, 0, v14
	ds_read_b128 v[96:99], v134 offset:0x1240
	v_fmac_f32_e32 v250, v62, v84
	v_max_i32_e32 v84, 0, v15
	ds_read_b128 v[104:107], v134 offset:0x1260
	v_mfma_f32_32x32x16_bf16 v[16:31], v[44:47], v[92:95], v[16:31]
	v_fmac_f32_e32 v250, v63, v84
	s_waitcnt lgkmcnt(0)
	ds_read_b128 v[108:111], v134 offset:0x2400
	ds_read_b128 v[100:103], v134 offset:0x2420
	ds_read_b128 v[92:95], v134 offset:0x2440
	ds_read_b128 v[84:87], v134 offset:0x2460
	s_cmp_eq_u32 s58, 57
	s_cselect_b64 s[52:53], -1, 0
	s_cmp_lg_u32 s58, 57
	s_cselect_b64 s[62:63], -1, 0
	s_and_b64 vcc, exec, s[52:53]
	s_cbranch_vccnz .Lixc63
	v_mfma_f32_32x32x16_bf16 v[0:15], v[32:35], v[80:83], 0
	v_max_i32_e32 v81, 0, v16
	v_fma_f32 v82, v48, v81, 0
	v_max_i32_e32 v81, 0, v17
	v_fmac_f32_e32 v82, v49, v81
	v_max_i32_e32 v81, 0, v18
	v_fmac_f32_e32 v82, v50, v81
	v_max_i32_e32 v81, 0, v19
	v_fmac_f32_e32 v82, v51, v81
	v_max_i32_e32 v81, 0, v20
	v_fmac_f32_e32 v82, v52, v81
	v_mfma_f32_32x32x16_bf16 v[0:15], v[36:39], v[88:91], v[0:15]
	v_max_i32_e32 v81, 0, v21
	v_fmac_f32_e32 v82, v53, v81
	v_max_i32_e32 v81, 0, v22
	v_fmac_f32_e32 v82, v54, v81
	v_max_i32_e32 v81, 0, v23
	v_fmac_f32_e32 v82, v55, v81
	v_max_i32_e32 v81, 0, v24
	v_fmac_f32_e32 v82, v56, v81
	v_max_i32_e32 v81, 0, v25
	v_fmac_f32_e32 v82, v57, v81
	v_mfma_f32_32x32x16_bf16 v[0:15], v[40:43], v[96:99], v[0:15]
	v_max_i32_e32 v81, 0, v26
	v_fmac_f32_e32 v82, v58, v81
	v_max_i32_e32 v81, 0, v27
	v_fmac_f32_e32 v82, v59, v81
	v_max_i32_e32 v81, 0, v28
	v_fmac_f32_e32 v82, v60, v81
	v_max_i32_e32 v81, 0, v29
	v_fmac_f32_e32 v82, v61, v81
	v_mfma_f32_32x32x16_bf16 v[0:15], v[44:47], v[104:107], v[0:15]
	v_max_i32_e32 v81, 0, v30
	v_fmac_f32_e32 v82, v62, v81
	v_max_i32_e32 v81, 0, v31
	v_cmp_gt_i32_e32 vcc, v183, v203
	v_fmac_f32_e32 v82, v63, v81
	s_and_b64 vcc, s[52:53], vcc
	v_cndmask_b32_e32 v251, v82, v197, vcc
.Lixj63:
	s_waitcnt lgkmcnt(0)
	ds_read_b128 v[96:99], v134 offset:0x3600
	ds_read_b128 v[88:91], v134 offset:0x3620
	ds_read_b128 v[80:83], v134 offset:0x3640
	ds_read_b128 v[104:107], v134 offset:0x3660
	s_cmpk_gt_u32 s95, 0x73
	s_cselect_b64 s[60:61], -1, 0
	s_cmpk_lt_u32 s95, 0x74
	s_cbranch_scc1 .Lixc62
	v_mfma_f32_32x32x16_bf16 v[16:31], v[32:35], v[108:111], 0
	v_cndmask_b32_e64 v109, 0, 1, s[62:63]
	v_cmp_ne_u32_e64 s[52:53], 1, v109
	s_andn2_b64 vcc, exec, s[62:63]
	v_max_i32_e32 v109, 0, v0
	v_fma_f32 v110, v48, v109, 0
	v_max_i32_e32 v109, 0, v1
	v_fmac_f32_e32 v110, v49, v109
	v_max_i32_e32 v109, 0, v2
	v_fmac_f32_e32 v110, v50, v109
	v_max_i32_e32 v109, 0, v3
	v_fmac_f32_e32 v110, v51, v109
	v_max_i32_e32 v109, 0, v4
	v_fmac_f32_e32 v110, v52, v109
	v_mfma_f32_32x32x16_bf16 v[16:31], v[36:39], v[100:103], v[16:31]
	v_max_i32_e32 v109, 0, v5
	v_fmac_f32_e32 v110, v53, v109
	v_max_i32_e32 v109, 0, v6
	v_fmac_f32_e32 v110, v54, v109
	v_max_i32_e32 v109, 0, v7
	v_fmac_f32_e32 v110, v55, v109
	v_max_i32_e32 v109, 0, v8
	v_fmac_f32_e32 v110, v56, v109
	v_max_i32_e32 v109, 0, v9
	v_fmac_f32_e32 v110, v57, v109
	v_mfma_f32_32x32x16_bf16 v[16:31], v[40:43], v[92:95], v[16:31]
	v_max_i32_e32 v109, 0, v10
	v_fmac_f32_e32 v110, v58, v109
	v_max_i32_e32 v109, 0, v11
	v_fmac_f32_e32 v110, v59, v109
	v_max_i32_e32 v109, 0, v12
	v_fmac_f32_e32 v110, v60, v109
	v_max_i32_e32 v109, 0, v13
	v_fmac_f32_e32 v110, v61, v109
	v_mfma_f32_32x32x16_bf16 v[16:31], v[44:47], v[84:87], v[16:31]
	v_max_i32_e32 v109, 0, v14
	s_cmp_eq_u32 s58, 58
	v_fmac_f32_e32 v110, v62, v109
	v_max_i32_e32 v109, 0, v15
	s_cselect_b64 s[62:63], -1, 0
	v_cmp_gt_i32_e32 vcc, v184, v203
	v_fmac_f32_e32 v110, v63, v109
	s_and_b64 vcc, s[62:63], vcc
	v_cndmask_b32_e32 v252, v110, v197, vcc

.Lixc112:
.LBB0_1143:
	s_nop 10
	v_max_i32_e32 v96, 0, v16
	v_fma_f32 v96, v48, v96, 0
	v_max_i32_e32 v97, 0, v17
	v_fmac_f32_e32 v96, v49, v97
	v_max_i32_e32 v97, 0, v18
	v_fmac_f32_e32 v96, v50, v97
	v_max_i32_e32 v97, 0, v19
	v_fmac_f32_e32 v96, v51, v97
	v_max_i32_e32 v97, 0, v20
	v_fmac_f32_e32 v96, v52, v97
	v_max_i32_e32 v97, 0, v21
	v_fmac_f32_e32 v96, v53, v97
	v_max_i32_e32 v97, 0, v22
	v_fmac_f32_e32 v96, v54, v97
	v_max_i32_e32 v97, 0, v23
	v_fmac_f32_e32 v96, v55, v97
	v_max_i32_e32 v97, 0, v24
	v_fmac_f32_e32 v96, v56, v97
	v_max_i32_e32 v97, 0, v25
	v_fmac_f32_e32 v96, v57, v97
	v_max_i32_e32 v97, 0, v26
	s_ashr_i32 s58, s58, 5
	v_fmac_f32_e32 v96, v58, v97
	v_max_i32_e32 v97, 0, v27
	s_lshl_b32 s64, s95, 4
	s_and_b32 s96, s58, -2
	v_fmac_f32_e32 v96, v59, v97
	v_max_i32_e32 v97, 0, v28
	s_add_i32 s96, s96, s64
	v_fmac_f32_e32 v96, v60, v97
	v_max_i32_e32 v97, 0, v29
	v_or_b32_e32 v203, s96, v129
	v_fmac_f32_e32 v96, v61, v97
	v_max_i32_e32 v97, 0, v30
	v_fmac_f32_e32 v96, v62, v97
	v_max_i32_e32 v97, 0, v31
	v_cmp_gt_i32_e32 vcc, v130, v203
	v_fmac_f32_e32 v96, v63, v97
	s_and_b64 vcc, s[48:49], vcc
	v_cndmask_b32_e32 v200, v96, v197, vcc
	s_branch .Lixj112
.Lixc111:
.LBB0_1145:
	s_lshr_b32 s58, s95, 1
	v_cndmask_b32_e64 v80, 0, 1, s[50:51]
	s_add_i32 s58, s58, 1
	v_cmp_ne_u32_e64 s[48:49], 1, v80
	s_andn2_b64 vcc, exec, s[50:51]
	v_mov_b32_e32 v201, 0xff800000
	s_cbranch_vccnz .LBB0_1147
	v_max_i32_e32 v80, 0, v0
	v_fma_f32 v80, v48, v80, 0
	v_max_i32_e32 v81, 0, v1
	v_fmac_f32_e32 v80, v49, v81
	v_max_i32_e32 v81, 0, v2
	v_fmac_f32_e32 v80, v50, v81
	v_max_i32_e32 v81, 0, v3
	v_fmac_f32_e32 v80, v51, v81
	v_max_i32_e32 v81, 0, v4
	v_fmac_f32_e32 v80, v52, v81
	v_max_i32_e32 v81, 0, v5
	v_fmac_f32_e32 v80, v53, v81
	v_max_i32_e32 v81, 0, v6
	v_fmac_f32_e32 v80, v54, v81
	v_max_i32_e32 v81, 0, v7
	v_fmac_f32_e32 v80, v55, v81
	v_max_i32_e32 v81, 0, v8
	v_fmac_f32_e32 v80, v56, v81
	v_max_i32_e32 v81, 0, v9
	v_fmac_f32_e32 v80, v57, v81
	v_max_i32_e32 v81, 0, v10
	v_fmac_f32_e32 v80, v58, v81
	v_max_i32_e32 v81, 0, v11
	v_fmac_f32_e32 v80, v59, v81
	v_max_i32_e32 v81, 0, v12
	v_fmac_f32_e32 v80, v60, v81
	v_max_i32_e32 v81, 0, v13
	v_fmac_f32_e32 v80, v61, v81
	v_max_i32_e32 v81, 0, v14
	v_fmac_f32_e32 v80, v62, v81
	v_max_i32_e32 v81, 0, v15
	v_fmac_f32_e32 v80, v63, v81
	s_cmp_eq_u32 s58, 2
	v_or_b32_e32 v81, 32, v130
	s_cselect_b64 s[50:51], -1, 0
	v_cmp_gt_i32_e32 vcc, v81, v203
	s_and_b64 vcc, s[50:51], vcc
	s_nop 0
	v_cndmask_b32_e32 v201, v80, v197, vcc
	s_branch .Lixj111
.Lixc110:
.LBB0_1151:
	v_cndmask_b32_e64 v84, 0, 1, s[64:65]
	v_cmp_ne_u32_e64 s[50:51], 1, v84
	s_andn2_b64 vcc, exec, s[64:65]
	v_mov_b32_e32 v202, 0xff800000
	s_cbranch_vccnz .LBB0_1153
	v_max_i32_e32 v84, 0, v16
	v_fma_f32 v84, v48, v84, 0
	v_max_i32_e32 v85, 0, v17
	v_fmac_f32_e32 v84, v49, v85
	v_max_i32_e32 v85, 0, v18
	v_fmac_f32_e32 v84, v50, v85
	v_max_i32_e32 v85, 0, v19
	v_fmac_f32_e32 v84, v51, v85
	v_max_i32_e32 v85, 0, v20
	v_fmac_f32_e32 v84, v52, v85
	v_max_i32_e32 v85, 0, v21
	v_fmac_f32_e32 v84, v53, v85
	v_max_i32_e32 v85, 0, v22
	v_fmac_f32_e32 v84, v54, v85
	v_max_i32_e32 v85, 0, v23
	v_fmac_f32_e32 v84, v55, v85
	v_max_i32_e32 v85, 0, v24
	v_fmac_f32_e32 v84, v56, v85
	v_max_i32_e32 v85, 0, v25
	v_fmac_f32_e32 v84, v57, v85
	v_max_i32_e32 v85, 0, v26
	v_fmac_f32_e32 v84, v58, v85
	v_max_i32_e32 v85, 0, v27
	v_fmac_f32_e32 v84, v59, v85
	v_max_i32_e32 v85, 0, v28
	v_fmac_f32_e32 v84, v60, v85
	v_max_i32_e32 v85, 0, v29
	v_fmac_f32_e32 v84, v61, v85
	v_max_i32_e32 v85, 0, v30
	v_fmac_f32_e32 v84, v62, v85
	v_max_i32_e32 v85, 0, v31
	v_fmac_f32_e32 v84, v63, v85
	s_cmp_eq_u32 s58, 3
	v_or_b32_e32 v85, 64, v130
	s_cselect_b64 s[64:65], -1, 0
	v_cmp_gt_i32_e32 vcc, v85, v203
	s_and_b64 vcc, s[64:65], vcc
	s_nop 0
	v_cndmask_b32_e32 v202, v84, v197, vcc
	s_branch .Lixj110
.Lixc109:
.LBB0_1157:
	v_cndmask_b32_e64 v80, 0, 1, s[66:67]
	v_cmp_ne_u32_e64 s[50:51], 1, v80
	s_andn2_b64 vcc, exec, s[66:67]
	v_mov_b32_e32 v112, 0xff800000
	s_cbranch_vccnz .LBB0_1159
	v_max_i32_e32 v80, 0, v0
	v_fma_f32 v80, v48, v80, 0
	v_max_i32_e32 v81, 0, v1
	v_fmac_f32_e32 v80, v49, v81
	v_max_i32_e32 v81, 0, v2
	v_fmac_f32_e32 v80, v50, v81
	v_max_i32_e32 v81, 0, v3
	v_fmac_f32_e32 v80, v51, v81
	v_max_i32_e32 v81, 0, v4
	v_fmac_f32_e32 v80, v52, v81
	v_max_i32_e32 v81, 0, v5
	v_fmac_f32_e32 v80, v53, v81
	v_max_i32_e32 v81, 0, v6
	v_fmac_f32_e32 v80, v54, v81
	v_max_i32_e32 v81, 0, v7
	v_fmac_f32_e32 v80, v55, v81
	v_max_i32_e32 v81, 0, v8
	v_fmac_f32_e32 v80, v56, v81
	v_max_i32_e32 v81, 0, v9
	v_fmac_f32_e32 v80, v57, v81
	v_max_i32_e32 v81, 0, v10
	v_fmac_f32_e32 v80, v58, v81
	v_max_i32_e32 v81, 0, v11
	v_fmac_f32_e32 v80, v59, v81
	v_max_i32_e32 v81, 0, v12
	v_fmac_f32_e32 v80, v60, v81
	v_max_i32_e32 v81, 0, v13
	v_fmac_f32_e32 v80, v61, v81
	v_max_i32_e32 v81, 0, v14
	v_fmac_f32_e32 v80, v62, v81
	v_max_i32_e32 v81, 0, v15
	v_fmac_f32_e32 v80, v63, v81
	s_cmp_eq_u32 s58, 4
	v_or_b32_e32 v81, 0x60, v130
	s_cselect_b64 s[66:67], -1, 0
	v_cmp_gt_i32_e32 vcc, v81, v203
	s_and_b64 vcc, s[66:67], vcc
	s_nop 0
	v_cndmask_b32_e32 v112, v80, v197, vcc
	s_branch .Lixj109
.Lixc108:
.LBB0_1163:
	v_cndmask_b32_e64 v84, 0, 1, s[64:65]
	v_cmp_ne_u32_e64 s[50:51], 1, v84
	s_andn2_b64 vcc, exec, s[64:65]
	v_mov_b32_e32 v113, 0xff800000
	s_cbranch_vccnz .LBB0_1165
	v_max_i32_e32 v84, 0, v16
	v_fma_f32 v84, v48, v84, 0
	v_max_i32_e32 v85, 0, v17
	v_fmac_f32_e32 v84, v49, v85
	v_max_i32_e32 v85, 0, v18
	v_fmac_f32_e32 v84, v50, v85
	v_max_i32_e32 v85, 0, v19
	v_fmac_f32_e32 v84, v51, v85
	v_max_i32_e32 v85, 0, v20
	v_fmac_f32_e32 v84, v52, v85
	v_max_i32_e32 v85, 0, v21
	v_fmac_f32_e32 v84, v53, v85
	v_max_i32_e32 v85, 0, v22
	v_fmac_f32_e32 v84, v54, v85
	v_max_i32_e32 v85, 0, v23
	v_fmac_f32_e32 v84, v55, v85
	v_max_i32_e32 v85, 0, v24
	v_fmac_f32_e32 v84, v56, v85
	v_max_i32_e32 v85, 0, v25
	v_fmac_f32_e32 v84, v57, v85
	v_max_i32_e32 v85, 0, v26
	v_fmac_f32_e32 v84, v58, v85
	v_max_i32_e32 v85, 0, v27
	v_fmac_f32_e32 v84, v59, v85
	v_max_i32_e32 v85, 0, v28
	v_fmac_f32_e32 v84, v60, v85
	v_max_i32_e32 v85, 0, v29
	v_fmac_f32_e32 v84, v61, v85
	v_max_i32_e32 v85, 0, v30
	v_fmac_f32_e32 v84, v62, v85
	v_max_i32_e32 v85, 0, v31
	v_fmac_f32_e32 v84, v63, v85
	s_cmp_eq_u32 s58, 5
	v_or_b32_e32 v85, 0x80, v130
	s_cselect_b64 s[64:65], -1, 0
	v_cmp_gt_i32_e32 vcc, v85, v203
	s_and_b64 vcc, s[64:65], vcc
	s_nop 0
	v_cndmask_b32_e32 v113, v84, v197, vcc
	s_branch .Lixj108
.Lixc107:
.LBB0_1169:
	v_cndmask_b32_e64 v80, 0, 1, s[66:67]
	v_cmp_ne_u32_e64 s[50:51], 1, v80
	s_andn2_b64 vcc, exec, s[66:67]
	v_mov_b32_e32 v114, 0xff800000
	s_cbranch_vccnz .LBB0_1171
	v_max_i32_e32 v80, 0, v0
	v_fma_f32 v80, v48, v80, 0
	v_max_i32_e32 v81, 0, v1
	v_fmac_f32_e32 v80, v49, v81
	v_max_i32_e32 v81, 0, v2
	v_fmac_f32_e32 v80, v50, v81
	v_max_i32_e32 v81, 0, v3
	v_fmac_f32_e32 v80, v51, v81
	v_max_i32_e32 v81, 0, v4
	v_fmac_f32_e32 v80, v52, v81
	v_max_i32_e32 v81, 0, v5
	v_fmac_f32_e32 v80, v53, v81
	v_max_i32_e32 v81, 0, v6
	v_fmac_f32_e32 v80, v54, v81
	v_max_i32_e32 v81, 0, v7
	v_fmac_f32_e32 v80, v55, v81
	v_max_i32_e32 v81, 0, v8
	v_fmac_f32_e32 v80, v56, v81
	v_max_i32_e32 v81, 0, v9
	v_fmac_f32_e32 v80, v57, v81
	v_max_i32_e32 v81, 0, v10
	v_fmac_f32_e32 v80, v58, v81
	v_max_i32_e32 v81, 0, v11
	v_fmac_f32_e32 v80, v59, v81
	v_max_i32_e32 v81, 0, v12
	v_fmac_f32_e32 v80, v60, v81
	v_max_i32_e32 v81, 0, v13
	v_fmac_f32_e32 v80, v61, v81
	v_max_i32_e32 v81, 0, v14
	v_fmac_f32_e32 v80, v62, v81
	v_max_i32_e32 v81, 0, v15
	v_fmac_f32_e32 v80, v63, v81
	s_cmp_eq_u32 s58, 6
	v_or_b32_e32 v81, 0xa0, v130
	s_cselect_b64 s[66:67], -1, 0
	v_cmp_gt_i32_e32 vcc, v81, v203
	s_and_b64 vcc, s[66:67], vcc
	s_nop 0
	v_cndmask_b32_e32 v114, v80, v197, vcc
	s_branch .Lixj107
.Lixc106:
.LBB0_1175:
	v_cndmask_b32_e64 v80, 0, 1, s[64:65]
	v_cmp_ne_u32_e64 s[50:51], 1, v80
	s_andn2_b64 vcc, exec, s[64:65]
	v_mov_b32_e32 v115, 0xff800000
	s_cbranch_vccnz .LBB0_1177
	v_max_i32_e32 v16, 0, v16
	v_fma_f32 v16, v48, v16, 0
	v_max_i32_e32 v17, 0, v17
	v_fmac_f32_e32 v16, v49, v17
	v_max_i32_e32 v17, 0, v18
	v_fmac_f32_e32 v16, v50, v17
	v_max_i32_e32 v17, 0, v19
	v_fmac_f32_e32 v16, v51, v17
	v_max_i32_e32 v17, 0, v20
	v_fmac_f32_e32 v16, v52, v17
	v_max_i32_e32 v17, 0, v21
	v_fmac_f32_e32 v16, v53, v17
	v_max_i32_e32 v17, 0, v22
	v_fmac_f32_e32 v16, v54, v17
	v_max_i32_e32 v17, 0, v23
	v_fmac_f32_e32 v16, v55, v17
	v_max_i32_e32 v17, 0, v24
	v_fmac_f32_e32 v16, v56, v17
	v_max_i32_e32 v17, 0, v25
	v_fmac_f32_e32 v16, v57, v17
	v_max_i32_e32 v17, 0, v26
	v_fmac_f32_e32 v16, v58, v17
	v_max_i32_e32 v17, 0, v27
	v_fmac_f32_e32 v16, v59, v17
	v_max_i32_e32 v17, 0, v28
	v_fmac_f32_e32 v16, v60, v17
	v_max_i32_e32 v17, 0, v29
	v_fmac_f32_e32 v16, v61, v17
	v_max_i32_e32 v17, 0, v30
	s_cmp_eq_u32 s58, 7
	v_fmac_f32_e32 v16, v62, v17
	v_max_i32_e32 v17, 0, v31
	s_cselect_b64 s[64:65], -1, 0
	v_cmp_gt_i32_e32 vcc, v132, v203
	v_fmac_f32_e32 v16, v63, v17
	s_and_b64 vcc, s[64:65], vcc
	v_cndmask_b32_e32 v115, v16, v197, vcc
	s_branch .Lixj106
.Lixc105:
.LBB0_1190:
	s_nop 4
	v_max_i32_e32 v80, 0, v16
	v_fma_f32 v80, v48, v80, 0
	v_max_i32_e32 v81, 0, v17
	v_fmac_f32_e32 v80, v49, v81
	v_max_i32_e32 v81, 0, v18
	v_fmac_f32_e32 v80, v50, v81
	v_max_i32_e32 v81, 0, v19
	v_fmac_f32_e32 v80, v51, v81
	v_max_i32_e32 v81, 0, v20
	v_fmac_f32_e32 v80, v52, v81
	v_max_i32_e32 v81, 0, v21
	v_fmac_f32_e32 v80, v53, v81
	v_max_i32_e32 v81, 0, v22
	v_fmac_f32_e32 v80, v54, v81
	v_max_i32_e32 v81, 0, v23
	v_fmac_f32_e32 v80, v55, v81
	v_max_i32_e32 v81, 0, v24
	v_fmac_f32_e32 v80, v56, v81
	v_max_i32_e32 v81, 0, v25
	v_fmac_f32_e32 v80, v57, v81
	v_max_i32_e32 v81, 0, v26
	v_fmac_f32_e32 v80, v58, v81
	v_max_i32_e32 v81, 0, v27
	v_fmac_f32_e32 v80, v59, v81
	v_max_i32_e32 v81, 0, v28
	v_fmac_f32_e32 v80, v60, v81
	v_max_i32_e32 v81, 0, v29
	v_fmac_f32_e32 v80, v61, v81
	v_max_i32_e32 v81, 0, v30
	v_fmac_f32_e32 v80, v62, v81
	v_max_i32_e32 v81, 0, v31
	v_cmp_gt_i32_e32 vcc, v135, v203
	v_fmac_f32_e32 v80, v63, v81
	s_and_b64 vcc, s[52:53], vcc
	v_cndmask_b32_e32 v117, v80, v197, vcc
	s_branch .Lixj105
.Lixc104:
.LBB0_1192:
	v_cndmask_b32_e64 v84, 0, 1, s[66:67]
	v_cmp_ne_u32_e64 s[52:53], 1, v84
	s_andn2_b64 vcc, exec, s[66:67]
	v_mov_b32_e32 v118, 0xff800000
	s_cbranch_vccnz .LBB0_1194
	v_max_i32_e32 v84, 0, v0
	v_fma_f32 v84, v48, v84, 0
	v_max_i32_e32 v85, 0, v1
	v_fmac_f32_e32 v84, v49, v85
	v_max_i32_e32 v85, 0, v2
	v_fmac_f32_e32 v84, v50, v85
	v_max_i32_e32 v85, 0, v3
	v_fmac_f32_e32 v84, v51, v85
	v_max_i32_e32 v85, 0, v4
	v_fmac_f32_e32 v84, v52, v85
	v_max_i32_e32 v85, 0, v5
	v_fmac_f32_e32 v84, v53, v85
	v_max_i32_e32 v85, 0, v6
	v_fmac_f32_e32 v84, v54, v85
	v_max_i32_e32 v85, 0, v7
	v_fmac_f32_e32 v84, v55, v85
	v_max_i32_e32 v85, 0, v8
	v_fmac_f32_e32 v84, v56, v85
	v_max_i32_e32 v85, 0, v9
	v_fmac_f32_e32 v84, v57, v85
	v_max_i32_e32 v85, 0, v10
	v_fmac_f32_e32 v84, v58, v85
	v_max_i32_e32 v85, 0, v11
	v_fmac_f32_e32 v84, v59, v85
	v_max_i32_e32 v85, 0, v12
	v_fmac_f32_e32 v84, v60, v85
	v_max_i32_e32 v85, 0, v13
	v_fmac_f32_e32 v84, v61, v85
	v_max_i32_e32 v85, 0, v14
	s_cmp_eq_u32 s58, 10
	v_fmac_f32_e32 v84, v62, v85
	v_max_i32_e32 v85, 0, v15
	s_cselect_b64 s[66:67], -1, 0
	v_cmp_gt_i32_e32 vcc, v136, v203
	v_fmac_f32_e32 v84, v63, v85
	s_and_b64 vcc, s[66:67], vcc
	v_cndmask_b32_e32 v118, v84, v197, vcc
	s_branch .Lixj104
.Lixc103:
.LBB0_1198:
	v_cndmask_b32_e64 v80, 0, 1, s[64:65]
	v_cmp_ne_u32_e64 s[52:53], 1, v80
	s_andn2_b64 vcc, exec, s[64:65]
	v_mov_b32_e32 v119, 0xff800000
	s_cbranch_vccnz .LBB0_1200
	v_max_i32_e32 v80, 0, v16
	v_fma_f32 v80, v48, v80, 0
	v_max_i32_e32 v81, 0, v17
	v_fmac_f32_e32 v80, v49, v81
	v_max_i32_e32 v81, 0, v18
	v_fmac_f32_e32 v80, v50, v81
	v_max_i32_e32 v81, 0, v19
	v_fmac_f32_e32 v80, v51, v81
	v_max_i32_e32 v81, 0, v20
	v_fmac_f32_e32 v80, v52, v81
	v_max_i32_e32 v81, 0, v21
	v_fmac_f32_e32 v80, v53, v81
	v_max_i32_e32 v81, 0, v22
	v_fmac_f32_e32 v80, v54, v81
	v_max_i32_e32 v81, 0, v23
	v_fmac_f32_e32 v80, v55, v81
	v_max_i32_e32 v81, 0, v24
	v_fmac_f32_e32 v80, v56, v81
	v_max_i32_e32 v81, 0, v25
	v_fmac_f32_e32 v80, v57, v81
	v_max_i32_e32 v81, 0, v26
	v_fmac_f32_e32 v80, v58, v81
	v_max_i32_e32 v81, 0, v27
	v_fmac_f32_e32 v80, v59, v81
	v_max_i32_e32 v81, 0, v28
	v_fmac_f32_e32 v80, v60, v81
	v_max_i32_e32 v81, 0, v29
	v_fmac_f32_e32 v80, v61, v81
	v_max_i32_e32 v81, 0, v30
	s_cmp_eq_u32 s58, 11
	v_fmac_f32_e32 v80, v62, v81
	v_max_i32_e32 v81, 0, v31
	s_cselect_b64 s[64:65], -1, 0
	v_cmp_gt_i32_e32 vcc, v137, v203
	v_fmac_f32_e32 v80, v63, v81
	s_and_b64 vcc, s[64:65], vcc
	v_cndmask_b32_e32 v119, v80, v197, vcc
	s_branch .Lixj103
.Lixc102:
.LBB0_1204:
	v_cndmask_b32_e64 v84, 0, 1, s[66:67]
	v_cmp_ne_u32_e64 s[52:53], 1, v84
	s_andn2_b64 vcc, exec, s[66:67]
	v_mov_b32_e32 v205, 0xff800000
	s_cbranch_vccnz .LBB0_1206
	v_max_i32_e32 v84, 0, v0
	v_fma_f32 v84, v48, v84, 0
	v_max_i32_e32 v85, 0, v1
	v_fmac_f32_e32 v84, v49, v85
	v_max_i32_e32 v85, 0, v2
	v_fmac_f32_e32 v84, v50, v85
	v_max_i32_e32 v85, 0, v3
	v_fmac_f32_e32 v84, v51, v85
	v_max_i32_e32 v85, 0, v4
	v_fmac_f32_e32 v84, v52, v85
	v_max_i32_e32 v85, 0, v5
	v_fmac_f32_e32 v84, v53, v85
	v_max_i32_e32 v85, 0, v6
	v_fmac_f32_e32 v84, v54, v85
	v_max_i32_e32 v85, 0, v7
	v_fmac_f32_e32 v84, v55, v85
	v_max_i32_e32 v85, 0, v8
	v_fmac_f32_e32 v84, v56, v85
	v_max_i32_e32 v85, 0, v9
	v_fmac_f32_e32 v84, v57, v85
	v_max_i32_e32 v85, 0, v10
	v_fmac_f32_e32 v84, v58, v85
	v_max_i32_e32 v85, 0, v11
	v_fmac_f32_e32 v84, v59, v85
	v_max_i32_e32 v85, 0, v12
	v_fmac_f32_e32 v84, v60, v85
	v_max_i32_e32 v85, 0, v13
	v_fmac_f32_e32 v84, v61, v85
	v_max_i32_e32 v85, 0, v14
	s_cmp_eq_u32 s58, 12
	v_fmac_f32_e32 v84, v62, v85
	v_max_i32_e32 v85, 0, v15
	s_cselect_b64 s[66:67], -1, 0
	v_cmp_gt_i32_e32 vcc, v138, v203
	v_fmac_f32_e32 v84, v63, v85
	s_and_b64 vcc, s[66:67], vcc
	v_cndmask_b32_e32 v205, v84, v197, vcc
	s_branch .Lixj102
.Lixc101:
.LBB0_1210:
	v_cndmask_b32_e64 v80, 0, 1, s[64:65]
	v_cmp_ne_u32_e64 s[52:53], 1, v80
	s_andn2_b64 vcc, exec, s[64:65]
	v_mov_b32_e32 v206, 0xff800000
	s_cbranch_vccnz .LBB0_1212
	v_max_i32_e32 v80, 0, v16
	v_fma_f32 v80, v48, v80, 0
	v_max_i32_e32 v81, 0, v17
	v_fmac_f32_e32 v80, v49, v81
	v_max_i32_e32 v81, 0, v18
	v_fmac_f32_e32 v80, v50, v81
	v_max_i32_e32 v81, 0, v19
	v_fmac_f32_e32 v80, v51, v81
	v_max_i32_e32 v81, 0, v20
	v_fmac_f32_e32 v80, v52, v81
	v_max_i32_e32 v81, 0, v21
	v_fmac_f32_e32 v80, v53, v81
	v_max_i32_e32 v81, 0, v22
	v_fmac_f32_e32 v80, v54, v81
	v_max_i32_e32 v81, 0, v23
	v_fmac_f32_e32 v80, v55, v81
	v_max_i32_e32 v81, 0, v24
	v_fmac_f32_e32 v80, v56, v81
	v_max_i32_e32 v81, 0, v25
	v_fmac_f32_e32 v80, v57, v81
	v_max_i32_e32 v81, 0, v26
	v_fmac_f32_e32 v80, v58, v81
	v_max_i32_e32 v81, 0, v27
	v_fmac_f32_e32 v80, v59, v81
	v_max_i32_e32 v81, 0, v28
	v_fmac_f32_e32 v80, v60, v81
	v_max_i32_e32 v81, 0, v29
	v_fmac_f32_e32 v80, v61, v81
	v_max_i32_e32 v81, 0, v30
	s_cmp_eq_u32 s58, 13
	v_fmac_f32_e32 v80, v62, v81
	v_max_i32_e32 v81, 0, v31
	s_cselect_b64 s[64:65], -1, 0
	v_cmp_gt_i32_e32 vcc, v139, v203
	v_fmac_f32_e32 v80, v63, v81
	s_and_b64 vcc, s[64:65], vcc
	v_cndmask_b32_e32 v206, v80, v197, vcc
	s_branch .Lixj101
.Lixc100:
.LBB0_1216:
	v_cndmask_b32_e64 v84, 0, 1, s[66:67]
	v_cmp_ne_u32_e64 s[52:53], 1, v84
	s_andn2_b64 vcc, exec, s[66:67]
	v_mov_b32_e32 v207, 0xff800000
	s_cbranch_vccnz .LBB0_1218
	v_max_i32_e32 v84, 0, v0
	v_fma_f32 v84, v48, v84, 0
	v_max_i32_e32 v85, 0, v1
	v_fmac_f32_e32 v84, v49, v85
	v_max_i32_e32 v85, 0, v2
	v_fmac_f32_e32 v84, v50, v85
	v_max_i32_e32 v85, 0, v3
	v_fmac_f32_e32 v84, v51, v85
	v_max_i32_e32 v85, 0, v4
	v_fmac_f32_e32 v84, v52, v85
	v_max_i32_e32 v85, 0, v5
	v_fmac_f32_e32 v84, v53, v85
	v_max_i32_e32 v85, 0, v6
	v_fmac_f32_e32 v84, v54, v85
	v_max_i32_e32 v85, 0, v7
	v_fmac_f32_e32 v84, v55, v85
	v_max_i32_e32 v85, 0, v8
	v_fmac_f32_e32 v84, v56, v85
	v_max_i32_e32 v85, 0, v9
	v_fmac_f32_e32 v84, v57, v85
	v_max_i32_e32 v85, 0, v10
	v_fmac_f32_e32 v84, v58, v85
	v_max_i32_e32 v85, 0, v11
	v_fmac_f32_e32 v84, v59, v85
	v_max_i32_e32 v85, 0, v12
	v_fmac_f32_e32 v84, v60, v85
	v_max_i32_e32 v85, 0, v13
	v_fmac_f32_e32 v84, v61, v85
	v_max_i32_e32 v85, 0, v14
	s_cmp_eq_u32 s58, 14
	v_fmac_f32_e32 v84, v62, v85
	v_max_i32_e32 v85, 0, v15
	s_cselect_b64 s[66:67], -1, 0
	v_cmp_gt_i32_e32 vcc, v140, v203
	v_fmac_f32_e32 v84, v63, v85
	s_and_b64 vcc, s[66:67], vcc
	v_cndmask_b32_e32 v207, v84, v197, vcc
	s_branch .Lixj100
.Lixc99:
.LBB0_1222:
	v_cndmask_b32_e64 v80, 0, 1, s[64:65]
	v_cmp_ne_u32_e64 s[52:53], 1, v80
	s_andn2_b64 vcc, exec, s[64:65]
	v_mov_b32_e32 v208, 0xff800000
	s_cbranch_vccnz .LBB0_1224
	v_max_i32_e32 v16, 0, v16
	v_fma_f32 v16, v48, v16, 0
	v_max_i32_e32 v17, 0, v17
	v_fmac_f32_e32 v16, v49, v17
	v_max_i32_e32 v17, 0, v18
	v_fmac_f32_e32 v16, v50, v17
	v_max_i32_e32 v17, 0, v19
	v_fmac_f32_e32 v16, v51, v17
	v_max_i32_e32 v17, 0, v20
	v_fmac_f32_e32 v16, v52, v17
	v_max_i32_e32 v17, 0, v21
	v_fmac_f32_e32 v16, v53, v17
	v_max_i32_e32 v17, 0, v22
	v_fmac_f32_e32 v16, v54, v17
	v_max_i32_e32 v17, 0, v23
	v_fmac_f32_e32 v16, v55, v17
	v_max_i32_e32 v17, 0, v24
	v_fmac_f32_e32 v16, v56, v17
	v_max_i32_e32 v17, 0, v25
	v_fmac_f32_e32 v16, v57, v17
	v_max_i32_e32 v17, 0, v26
	v_fmac_f32_e32 v16, v58, v17
	v_max_i32_e32 v17, 0, v27
	v_fmac_f32_e32 v16, v59, v17
	v_max_i32_e32 v17, 0, v28
	v_fmac_f32_e32 v16, v60, v17
	v_max_i32_e32 v17, 0, v29
	v_fmac_f32_e32 v16, v61, v17
	v_max_i32_e32 v17, 0, v30
	s_cmp_eq_u32 s58, 15
	v_fmac_f32_e32 v16, v62, v17
	v_max_i32_e32 v17, 0, v31
	s_cselect_b64 s[64:65], -1, 0
	v_cmp_gt_i32_e32 vcc, v141, v203
	v_fmac_f32_e32 v16, v63, v17
	s_and_b64 vcc, s[64:65], vcc
	v_cndmask_b32_e32 v208, v16, v197, vcc
	s_branch .Lixj99
.Lixc98:
.LBB0_1234:
	s_nop 4
	v_max_i32_e32 v80, 0, v16
	v_fma_f32 v80, v48, v80, 0
	v_max_i32_e32 v81, 0, v17
	v_fmac_f32_e32 v80, v49, v81
	v_max_i32_e32 v81, 0, v18
	v_fmac_f32_e32 v80, v50, v81
	v_max_i32_e32 v81, 0, v19
	v_fmac_f32_e32 v80, v51, v81
	v_max_i32_e32 v81, 0, v20
	v_fmac_f32_e32 v80, v52, v81
	v_max_i32_e32 v81, 0, v21
	v_fmac_f32_e32 v80, v53, v81
	v_max_i32_e32 v81, 0, v22
	v_fmac_f32_e32 v80, v54, v81
	v_max_i32_e32 v81, 0, v23
	v_fmac_f32_e32 v80, v55, v81
	v_max_i32_e32 v81, 0, v24
	v_fmac_f32_e32 v80, v56, v81
	v_max_i32_e32 v81, 0, v25
	v_fmac_f32_e32 v80, v57, v81
	v_max_i32_e32 v81, 0, v26
	v_fmac_f32_e32 v80, v58, v81
	v_max_i32_e32 v81, 0, v27
	v_fmac_f32_e32 v80, v59, v81
	v_max_i32_e32 v81, 0, v28
	v_fmac_f32_e32 v80, v60, v81
	v_max_i32_e32 v81, 0, v29
	v_fmac_f32_e32 v80, v61, v81
	v_max_i32_e32 v81, 0, v30
	v_fmac_f32_e32 v80, v62, v81
	v_max_i32_e32 v81, 0, v31
	v_cmp_gt_i32_e32 vcc, v143, v203
	v_fmac_f32_e32 v80, v63, v81
	s_and_b64 vcc, s[52:53], vcc
	v_cndmask_b32_e32 v210, v80, v197, vcc
	s_branch .Lixj98
.Lixc97:
.LBB0_1236:
	v_cndmask_b32_e64 v84, 0, 1, s[66:67]
	v_cmp_ne_u32_e64 s[52:53], 1, v84
	s_andn2_b64 vcc, exec, s[66:67]
	v_mov_b32_e32 v211, 0xff800000
	s_cbranch_vccnz .LBB0_1238
	v_max_i32_e32 v84, 0, v0
	v_fma_f32 v84, v48, v84, 0
	v_max_i32_e32 v85, 0, v1
	v_fmac_f32_e32 v84, v49, v85
	v_max_i32_e32 v85, 0, v2
	v_fmac_f32_e32 v84, v50, v85
	v_max_i32_e32 v85, 0, v3
	v_fmac_f32_e32 v84, v51, v85
	v_max_i32_e32 v85, 0, v4
	v_fmac_f32_e32 v84, v52, v85
	v_max_i32_e32 v85, 0, v5
	v_fmac_f32_e32 v84, v53, v85
	v_max_i32_e32 v85, 0, v6
	v_fmac_f32_e32 v84, v54, v85
	v_max_i32_e32 v85, 0, v7
	v_fmac_f32_e32 v84, v55, v85
	v_max_i32_e32 v85, 0, v8
	v_fmac_f32_e32 v84, v56, v85
	v_max_i32_e32 v85, 0, v9
	v_fmac_f32_e32 v84, v57, v85
	v_max_i32_e32 v85, 0, v10
	v_fmac_f32_e32 v84, v58, v85
	v_max_i32_e32 v85, 0, v11
	v_fmac_f32_e32 v84, v59, v85
	v_max_i32_e32 v85, 0, v12
	v_fmac_f32_e32 v84, v60, v85
	v_max_i32_e32 v85, 0, v13
	v_fmac_f32_e32 v84, v61, v85
	v_max_i32_e32 v85, 0, v14
	s_cmp_eq_u32 s58, 18
	v_fmac_f32_e32 v84, v62, v85
	v_max_i32_e32 v85, 0, v15
	s_cselect_b64 s[66:67], -1, 0
	v_cmp_gt_i32_e32 vcc, v144, v203
	v_fmac_f32_e32 v84, v63, v85
	s_and_b64 vcc, s[66:67], vcc
	v_cndmask_b32_e32 v211, v84, v197, vcc
	s_branch .Lixj97
.Lixc96:
.LBB0_1242:
	v_cndmask_b32_e64 v80, 0, 1, s[64:65]
	v_cmp_ne_u32_e64 s[52:53], 1, v80
	s_andn2_b64 vcc, exec, s[64:65]
	v_mov_b32_e32 v212, 0xff800000
	s_cbranch_vccnz .LBB0_1244
	v_max_i32_e32 v80, 0, v16
	v_fma_f32 v80, v48, v80, 0
	v_max_i32_e32 v81, 0, v17
	v_fmac_f32_e32 v80, v49, v81
	v_max_i32_e32 v81, 0, v18
	v_fmac_f32_e32 v80, v50, v81
	v_max_i32_e32 v81, 0, v19
	v_fmac_f32_e32 v80, v51, v81
	v_max_i32_e32 v81, 0, v20
	v_fmac_f32_e32 v80, v52, v81
	v_max_i32_e32 v81, 0, v21
	v_fmac_f32_e32 v80, v53, v81
	v_max_i32_e32 v81, 0, v22
	v_fmac_f32_e32 v80, v54, v81
	v_max_i32_e32 v81, 0, v23
	v_fmac_f32_e32 v80, v55, v81
	v_max_i32_e32 v81, 0, v24
	v_fmac_f32_e32 v80, v56, v81
	v_max_i32_e32 v81, 0, v25
	v_fmac_f32_e32 v80, v57, v81
	v_max_i32_e32 v81, 0, v26
	v_fmac_f32_e32 v80, v58, v81
	v_max_i32_e32 v81, 0, v27
	v_fmac_f32_e32 v80, v59, v81
	v_max_i32_e32 v81, 0, v28
	v_fmac_f32_e32 v80, v60, v81
	v_max_i32_e32 v81, 0, v29
	v_fmac_f32_e32 v80, v61, v81
	v_max_i32_e32 v81, 0, v30
	s_cmp_eq_u32 s58, 19
	v_fmac_f32_e32 v80, v62, v81
	v_max_i32_e32 v81, 0, v31
	s_cselect_b64 s[64:65], -1, 0
	v_cmp_gt_i32_e32 vcc, v145, v203
	v_fmac_f32_e32 v80, v63, v81
	s_and_b64 vcc, s[64:65], vcc
	v_cndmask_b32_e32 v212, v80, v197, vcc
	s_branch .Lixj96
.Lixc95:
.LBB0_1248:
	v_cndmask_b32_e64 v84, 0, 1, s[66:67]
	v_cmp_ne_u32_e64 s[52:53], 1, v84
	s_andn2_b64 vcc, exec, s[66:67]
	v_mov_b32_e32 v213, 0xff800000
	s_cbranch_vccnz .LBB0_1250
	v_max_i32_e32 v84, 0, v0
	v_fma_f32 v84, v48, v84, 0
	v_max_i32_e32 v85, 0, v1
	v_fmac_f32_e32 v84, v49, v85
	v_max_i32_e32 v85, 0, v2
	v_fmac_f32_e32 v84, v50, v85
	v_max_i32_e32 v85, 0, v3
	v_fmac_f32_e32 v84, v51, v85
	v_max_i32_e32 v85, 0, v4
	v_fmac_f32_e32 v84, v52, v85
	v_max_i32_e32 v85, 0, v5
	v_fmac_f32_e32 v84, v53, v85
	v_max_i32_e32 v85, 0, v6
	v_fmac_f32_e32 v84, v54, v85
	v_max_i32_e32 v85, 0, v7
	v_fmac_f32_e32 v84, v55, v85
	v_max_i32_e32 v85, 0, v8
	v_fmac_f32_e32 v84, v56, v85
	v_max_i32_e32 v85, 0, v9
	v_fmac_f32_e32 v84, v57, v85
	v_max_i32_e32 v85, 0, v10
	v_fmac_f32_e32 v84, v58, v85
	v_max_i32_e32 v85, 0, v11
	v_fmac_f32_e32 v84, v59, v85
	v_max_i32_e32 v85, 0, v12
	v_fmac_f32_e32 v84, v60, v85
	v_max_i32_e32 v85, 0, v13
	v_fmac_f32_e32 v84, v61, v85
	v_max_i32_e32 v85, 0, v14
	s_cmp_eq_u32 s58, 20
	v_fmac_f32_e32 v84, v62, v85
	v_max_i32_e32 v85, 0, v15
	s_cselect_b64 s[66:67], -1, 0
	v_cmp_gt_i32_e32 vcc, v146, v203
	v_fmac_f32_e32 v84, v63, v85
	s_and_b64 vcc, s[66:67], vcc
	v_cndmask_b32_e32 v213, v84, v197, vcc
	s_branch .Lixj95
.Lixc94:
.LBB0_1254:
	v_cndmask_b32_e64 v80, 0, 1, s[64:65]
	v_cmp_ne_u32_e64 s[52:53], 1, v80
	s_andn2_b64 vcc, exec, s[64:65]
	v_mov_b32_e32 v214, 0xff800000
	s_cbranch_vccnz .LBB0_1256
	v_max_i32_e32 v80, 0, v16
	v_fma_f32 v80, v48, v80, 0
	v_max_i32_e32 v81, 0, v17
	v_fmac_f32_e32 v80, v49, v81
	v_max_i32_e32 v81, 0, v18
	v_fmac_f32_e32 v80, v50, v81
	v_max_i32_e32 v81, 0, v19
	v_fmac_f32_e32 v80, v51, v81
	v_max_i32_e32 v81, 0, v20
	v_fmac_f32_e32 v80, v52, v81
	v_max_i32_e32 v81, 0, v21
	v_fmac_f32_e32 v80, v53, v81
	v_max_i32_e32 v81, 0, v22
	v_fmac_f32_e32 v80, v54, v81
	v_max_i32_e32 v81, 0, v23
	v_fmac_f32_e32 v80, v55, v81
	v_max_i32_e32 v81, 0, v24
	v_fmac_f32_e32 v80, v56, v81
	v_max_i32_e32 v81, 0, v25
	v_fmac_f32_e32 v80, v57, v81
	v_max_i32_e32 v81, 0, v26
	v_fmac_f32_e32 v80, v58, v81
	v_max_i32_e32 v81, 0, v27
	v_fmac_f32_e32 v80, v59, v81
	v_max_i32_e32 v81, 0, v28
	v_fmac_f32_e32 v80, v60, v81
	v_max_i32_e32 v81, 0, v29
	v_fmac_f32_e32 v80, v61, v81
	v_max_i32_e32 v81, 0, v30
	s_cmp_eq_u32 s58, 21
	v_fmac_f32_e32 v80, v62, v81
	v_max_i32_e32 v81, 0, v31
	s_cselect_b64 s[64:65], -1, 0
	v_cmp_gt_i32_e32 vcc, v147, v203
	v_fmac_f32_e32 v80, v63, v81
	s_and_b64 vcc, s[64:65], vcc
	v_cndmask_b32_e32 v214, v80, v197, vcc
	s_branch .Lixj94
.Lixc93:
.LBB0_1260:
	v_cndmask_b32_e64 v84, 0, 1, s[66:67]
	v_cmp_ne_u32_e64 s[52:53], 1, v84
	s_andn2_b64 vcc, exec, s[66:67]
	v_mov_b32_e32 v216, 0xff800000
	s_cbranch_vccnz .LBB0_1262
	v_max_i32_e32 v84, 0, v0
	v_fma_f32 v84, v48, v84, 0
	v_max_i32_e32 v85, 0, v1
	v_fmac_f32_e32 v84, v49, v85
	v_max_i32_e32 v85, 0, v2
	v_fmac_f32_e32 v84, v50, v85
	v_max_i32_e32 v85, 0, v3
	v_fmac_f32_e32 v84, v51, v85
	v_max_i32_e32 v85, 0, v4
	v_fmac_f32_e32 v84, v52, v85
	v_max_i32_e32 v85, 0, v5
	v_fmac_f32_e32 v84, v53, v85
	v_max_i32_e32 v85, 0, v6
	v_fmac_f32_e32 v84, v54, v85
	v_max_i32_e32 v85, 0, v7
	v_fmac_f32_e32 v84, v55, v85
	v_max_i32_e32 v85, 0, v8
	v_fmac_f32_e32 v84, v56, v85
	v_max_i32_e32 v85, 0, v9
	v_fmac_f32_e32 v84, v57, v85
	v_max_i32_e32 v85, 0, v10
	v_fmac_f32_e32 v84, v58, v85
	v_max_i32_e32 v85, 0, v11
	v_fmac_f32_e32 v84, v59, v85
	v_max_i32_e32 v85, 0, v12
	v_fmac_f32_e32 v84, v60, v85
	v_max_i32_e32 v85, 0, v13
	v_fmac_f32_e32 v84, v61, v85
	v_max_i32_e32 v85, 0, v14
	s_cmp_eq_u32 s58, 22
	v_fmac_f32_e32 v84, v62, v85
	v_max_i32_e32 v85, 0, v15
	s_cselect_b64 s[66:67], -1, 0
	v_cmp_gt_i32_e32 vcc, v148, v203
	v_fmac_f32_e32 v84, v63, v85
	s_and_b64 vcc, s[66:67], vcc
	v_cndmask_b32_e32 v216, v84, v197, vcc
	s_branch .Lixj93
.Lixc92:
.LBB0_1266:
	v_cndmask_b32_e64 v80, 0, 1, s[64:65]
	v_cmp_ne_u32_e64 s[52:53], 1, v80
	s_andn2_b64 vcc, exec, s[64:65]
	v_mov_b32_e32 v217, 0xff800000
	s_cbranch_vccnz .LBB0_1268
	v_max_i32_e32 v16, 0, v16
	v_fma_f32 v16, v48, v16, 0
	v_max_i32_e32 v17, 0, v17
	v_fmac_f32_e32 v16, v49, v17
	v_max_i32_e32 v17, 0, v18
	v_fmac_f32_e32 v16, v50, v17
	v_max_i32_e32 v17, 0, v19
	v_fmac_f32_e32 v16, v51, v17
	v_max_i32_e32 v17, 0, v20
	v_fmac_f32_e32 v16, v52, v17
	v_max_i32_e32 v17, 0, v21
	v_fmac_f32_e32 v16, v53, v17
	v_max_i32_e32 v17, 0, v22
	v_fmac_f32_e32 v16, v54, v17
	v_max_i32_e32 v17, 0, v23
	v_fmac_f32_e32 v16, v55, v17
	v_max_i32_e32 v17, 0, v24
	v_fmac_f32_e32 v16, v56, v17
	v_max_i32_e32 v17, 0, v25
	v_fmac_f32_e32 v16, v57, v17
	v_max_i32_e32 v17, 0, v26
	v_fmac_f32_e32 v16, v58, v17
	v_max_i32_e32 v17, 0, v27
	v_fmac_f32_e32 v16, v59, v17
	v_max_i32_e32 v17, 0, v28
	v_fmac_f32_e32 v16, v60, v17
	v_max_i32_e32 v17, 0, v29
	v_fmac_f32_e32 v16, v61, v17
	v_max_i32_e32 v17, 0, v30
	s_cmp_eq_u32 s58, 23
	v_fmac_f32_e32 v16, v62, v17
	v_max_i32_e32 v17, 0, v31
	s_cselect_b64 s[64:65], -1, 0
	v_cmp_gt_i32_e32 vcc, v149, v203
	v_fmac_f32_e32 v16, v63, v17
	s_and_b64 vcc, s[64:65], vcc
	v_cndmask_b32_e32 v217, v16, v197, vcc
	s_branch .Lixj92
.Lixc91:
.LBB0_1278:
	s_nop 4
	v_max_i32_e32 v80, 0, v16
	v_fma_f32 v80, v48, v80, 0
	v_max_i32_e32 v81, 0, v17
	v_fmac_f32_e32 v80, v49, v81
	v_max_i32_e32 v81, 0, v18
	v_fmac_f32_e32 v80, v50, v81
	v_max_i32_e32 v81, 0, v19
	v_fmac_f32_e32 v80, v51, v81
	v_max_i32_e32 v81, 0, v20
	v_fmac_f32_e32 v80, v52, v81
	v_max_i32_e32 v81, 0, v21
	v_fmac_f32_e32 v80, v53, v81
	v_max_i32_e32 v81, 0, v22
	v_fmac_f32_e32 v80, v54, v81
	v_max_i32_e32 v81, 0, v23
	v_fmac_f32_e32 v80, v55, v81
	v_max_i32_e32 v81, 0, v24
	v_fmac_f32_e32 v80, v56, v81
	v_max_i32_e32 v81, 0, v25
	v_fmac_f32_e32 v80, v57, v81
	v_max_i32_e32 v81, 0, v26
	v_fmac_f32_e32 v80, v58, v81
	v_max_i32_e32 v81, 0, v27
	v_fmac_f32_e32 v80, v59, v81
	v_max_i32_e32 v81, 0, v28
	v_fmac_f32_e32 v80, v60, v81
	v_max_i32_e32 v81, 0, v29
	v_fmac_f32_e32 v80, v61, v81
	v_max_i32_e32 v81, 0, v30
	v_fmac_f32_e32 v80, v62, v81
	v_max_i32_e32 v81, 0, v31
	v_cmp_gt_i32_e32 vcc, v151, v203
	v_fmac_f32_e32 v80, v63, v81
	s_and_b64 vcc, s[52:53], vcc
	v_cndmask_b32_e32 v219, v80, v197, vcc
	s_branch .Lixj91
.Lixc90:
.LBB0_1280:
	v_cndmask_b32_e64 v84, 0, 1, s[66:67]
	v_cmp_ne_u32_e64 s[52:53], 1, v84
	s_andn2_b64 vcc, exec, s[66:67]
	v_mov_b32_e32 v220, 0xff800000
	s_cbranch_vccnz .LBB0_1282
	v_max_i32_e32 v84, 0, v0
	v_fma_f32 v84, v48, v84, 0
	v_max_i32_e32 v85, 0, v1
	v_fmac_f32_e32 v84, v49, v85
	v_max_i32_e32 v85, 0, v2
	v_fmac_f32_e32 v84, v50, v85
	v_max_i32_e32 v85, 0, v3
	v_fmac_f32_e32 v84, v51, v85
	v_max_i32_e32 v85, 0, v4
	v_fmac_f32_e32 v84, v52, v85
	v_max_i32_e32 v85, 0, v5
	v_fmac_f32_e32 v84, v53, v85
	v_max_i32_e32 v85, 0, v6
	v_fmac_f32_e32 v84, v54, v85
	v_max_i32_e32 v85, 0, v7
	v_fmac_f32_e32 v84, v55, v85
	v_max_i32_e32 v85, 0, v8
	v_fmac_f32_e32 v84, v56, v85
	v_max_i32_e32 v85, 0, v9
	v_fmac_f32_e32 v84, v57, v85
	v_max_i32_e32 v85, 0, v10
	v_fmac_f32_e32 v84, v58, v85
	v_max_i32_e32 v85, 0, v11
	v_fmac_f32_e32 v84, v59, v85
	v_max_i32_e32 v85, 0, v12
	v_fmac_f32_e32 v84, v60, v85
	v_max_i32_e32 v85, 0, v13
	v_fmac_f32_e32 v84, v61, v85
	v_max_i32_e32 v85, 0, v14
	s_cmp_eq_u32 s58, 26
	v_fmac_f32_e32 v84, v62, v85
	v_max_i32_e32 v85, 0, v15
	s_cselect_b64 s[66:67], -1, 0
	v_cmp_gt_i32_e32 vcc, v152, v203
	v_fmac_f32_e32 v84, v63, v85
	s_and_b64 vcc, s[66:67], vcc
	v_cndmask_b32_e32 v220, v84, v197, vcc
	s_branch .Lixj90
.Lixc89:
.LBB0_1286:
	v_cndmask_b32_e64 v80, 0, 1, s[64:65]
	v_cmp_ne_u32_e64 s[52:53], 1, v80
	s_andn2_b64 vcc, exec, s[64:65]
	v_mov_b32_e32 v221, 0xff800000
	s_cbranch_vccnz .LBB0_1288
	v_max_i32_e32 v80, 0, v16
	v_fma_f32 v80, v48, v80, 0
	v_max_i32_e32 v81, 0, v17
	v_fmac_f32_e32 v80, v49, v81
	v_max_i32_e32 v81, 0, v18
	v_fmac_f32_e32 v80, v50, v81
	v_max_i32_e32 v81, 0, v19
	v_fmac_f32_e32 v80, v51, v81
	v_max_i32_e32 v81, 0, v20
	v_fmac_f32_e32 v80, v52, v81
	v_max_i32_e32 v81, 0, v21
	v_fmac_f32_e32 v80, v53, v81
	v_max_i32_e32 v81, 0, v22
	v_fmac_f32_e32 v80, v54, v81
	v_max_i32_e32 v81, 0, v23
	v_fmac_f32_e32 v80, v55, v81
	v_max_i32_e32 v81, 0, v24
	v_fmac_f32_e32 v80, v56, v81
	v_max_i32_e32 v81, 0, v25
	v_fmac_f32_e32 v80, v57, v81
	v_max_i32_e32 v81, 0, v26
	v_fmac_f32_e32 v80, v58, v81
	v_max_i32_e32 v81, 0, v27
	v_fmac_f32_e32 v80, v59, v81
	v_max_i32_e32 v81, 0, v28
	v_fmac_f32_e32 v80, v60, v81
	v_max_i32_e32 v81, 0, v29
	v_fmac_f32_e32 v80, v61, v81
	v_max_i32_e32 v81, 0, v30
	s_cmp_eq_u32 s58, 27
	v_fmac_f32_e32 v80, v62, v81
	v_max_i32_e32 v81, 0, v31
	s_cselect_b64 s[64:65], -1, 0
	v_cmp_gt_i32_e32 vcc, v153, v203
	v_fmac_f32_e32 v80, v63, v81
	s_and_b64 vcc, s[64:65], vcc
	v_cndmask_b32_e32 v221, v80, v197, vcc
	s_branch .Lixj89
.Lixc88:
.LBB0_1292:
	v_cndmask_b32_e64 v84, 0, 1, s[66:67]
	v_cmp_ne_u32_e64 s[52:53], 1, v84
	s_andn2_b64 vcc, exec, s[66:67]
	v_mov_b32_e32 v222, 0xff800000
	s_cbranch_vccnz .LBB0_1294
	v_max_i32_e32 v84, 0, v0
	v_fma_f32 v84, v48, v84, 0
	v_max_i32_e32 v85, 0, v1
	v_fmac_f32_e32 v84, v49, v85
	v_max_i32_e32 v85, 0, v2
	v_fmac_f32_e32 v84, v50, v85
	v_max_i32_e32 v85, 0, v3
	v_fmac_f32_e32 v84, v51, v85
	v_max_i32_e32 v85, 0, v4
	v_fmac_f32_e32 v84, v52, v85
	v_max_i32_e32 v85, 0, v5
	v_fmac_f32_e32 v84, v53, v85
	v_max_i32_e32 v85, 0, v6
	v_fmac_f32_e32 v84, v54, v85
	v_max_i32_e32 v85, 0, v7
	v_fmac_f32_e32 v84, v55, v85
	v_max_i32_e32 v85, 0, v8
	v_fmac_f32_e32 v84, v56, v85
	v_max_i32_e32 v85, 0, v9
	v_fmac_f32_e32 v84, v57, v85
	v_max_i32_e32 v85, 0, v10
	v_fmac_f32_e32 v84, v58, v85
	v_max_i32_e32 v85, 0, v11
	v_fmac_f32_e32 v84, v59, v85
	v_max_i32_e32 v85, 0, v12
	v_fmac_f32_e32 v84, v60, v85
	v_max_i32_e32 v85, 0, v13
	v_fmac_f32_e32 v84, v61, v85
	v_max_i32_e32 v85, 0, v14
	s_cmp_eq_u32 s58, 28
	v_fmac_f32_e32 v84, v62, v85
	v_max_i32_e32 v85, 0, v15
	s_cselect_b64 s[66:67], -1, 0
	v_cmp_gt_i32_e32 vcc, v154, v203
	v_fmac_f32_e32 v84, v63, v85
	s_and_b64 vcc, s[66:67], vcc
	v_cndmask_b32_e32 v222, v84, v197, vcc
	s_branch .Lixj88
.Lixc87:
.LBB0_1298:
	v_cndmask_b32_e64 v80, 0, 1, s[64:65]
	v_cmp_ne_u32_e64 s[52:53], 1, v80
	s_andn2_b64 vcc, exec, s[64:65]
	v_mov_b32_e32 v223, 0xff800000
	s_cbranch_vccnz .LBB0_1300
	v_max_i32_e32 v80, 0, v16
	v_fma_f32 v80, v48, v80, 0
	v_max_i32_e32 v81, 0, v17
	v_fmac_f32_e32 v80, v49, v81
	v_max_i32_e32 v81, 0, v18
	v_fmac_f32_e32 v80, v50, v81
	v_max_i32_e32 v81, 0, v19
	v_fmac_f32_e32 v80, v51, v81
	v_max_i32_e32 v81, 0, v20
	v_fmac_f32_e32 v80, v52, v81
	v_max_i32_e32 v81, 0, v21
	v_fmac_f32_e32 v80, v53, v81
	v_max_i32_e32 v81, 0, v22
	v_fmac_f32_e32 v80, v54, v81
	v_max_i32_e32 v81, 0, v23
	v_fmac_f32_e32 v80, v55, v81
	v_max_i32_e32 v81, 0, v24
	v_fmac_f32_e32 v80, v56, v81
	v_max_i32_e32 v81, 0, v25
	v_fmac_f32_e32 v80, v57, v81
	v_max_i32_e32 v81, 0, v26
	v_fmac_f32_e32 v80, v58, v81
	v_max_i32_e32 v81, 0, v27
	v_fmac_f32_e32 v80, v59, v81
	v_max_i32_e32 v81, 0, v28
	v_fmac_f32_e32 v80, v60, v81
	v_max_i32_e32 v81, 0, v29
	v_fmac_f32_e32 v80, v61, v81
	v_max_i32_e32 v81, 0, v30
	s_cmp_eq_u32 s58, 29
	v_fmac_f32_e32 v80, v62, v81
	v_max_i32_e32 v81, 0, v31
	s_cselect_b64 s[64:65], -1, 0
	v_cmp_gt_i32_e32 vcc, v155, v203
	v_fmac_f32_e32 v80, v63, v81
	s_and_b64 vcc, s[64:65], vcc
	v_cndmask_b32_e32 v223, v80, v197, vcc
	s_branch .Lixj87
.Lixc86:
.LBB0_1304:
	v_cndmask_b32_e64 v84, 0, 1, s[66:67]
	v_cmp_ne_u32_e64 s[52:53], 1, v84
	s_andn2_b64 vcc, exec, s[66:67]
	v_mov_b32_e32 v224, 0xff800000
	s_cbranch_vccnz .LBB0_1306
	v_max_i32_e32 v84, 0, v0
	v_fma_f32 v84, v48, v84, 0
	v_max_i32_e32 v85, 0, v1
	v_fmac_f32_e32 v84, v49, v85
	v_max_i32_e32 v85, 0, v2
	v_fmac_f32_e32 v84, v50, v85
	v_max_i32_e32 v85, 0, v3
	v_fmac_f32_e32 v84, v51, v85
	v_max_i32_e32 v85, 0, v4
	v_fmac_f32_e32 v84, v52, v85
	v_max_i32_e32 v85, 0, v5
	v_fmac_f32_e32 v84, v53, v85
	v_max_i32_e32 v85, 0, v6
	v_fmac_f32_e32 v84, v54, v85
	v_max_i32_e32 v85, 0, v7
	v_fmac_f32_e32 v84, v55, v85
	v_max_i32_e32 v85, 0, v8
	v_fmac_f32_e32 v84, v56, v85
	v_max_i32_e32 v85, 0, v9
	v_fmac_f32_e32 v84, v57, v85
	v_max_i32_e32 v85, 0, v10
	v_fmac_f32_e32 v84, v58, v85
	v_max_i32_e32 v85, 0, v11
	v_fmac_f32_e32 v84, v59, v85
	v_max_i32_e32 v85, 0, v12
	v_fmac_f32_e32 v84, v60, v85
	v_max_i32_e32 v85, 0, v13
	v_fmac_f32_e32 v84, v61, v85
	v_max_i32_e32 v85, 0, v14
	s_cmp_eq_u32 s58, 30
	v_fmac_f32_e32 v84, v62, v85
	v_max_i32_e32 v85, 0, v15
	s_cselect_b64 s[66:67], -1, 0
	v_cmp_gt_i32_e32 vcc, v156, v203
	v_fmac_f32_e32 v84, v63, v85
	s_and_b64 vcc, s[66:67], vcc
	v_cndmask_b32_e32 v224, v84, v197, vcc
	s_branch .Lixj86
.Lixc85:
.LBB0_1310:
	v_cndmask_b32_e64 v80, 0, 1, s[64:65]
	v_cmp_ne_u32_e64 s[52:53], 1, v80
	s_andn2_b64 vcc, exec, s[64:65]
	v_mov_b32_e32 v225, 0xff800000
	s_cbranch_vccnz .LBB0_1312
	v_max_i32_e32 v16, 0, v16
	v_fma_f32 v16, v48, v16, 0
	v_max_i32_e32 v17, 0, v17
	v_fmac_f32_e32 v16, v49, v17
	v_max_i32_e32 v17, 0, v18
	v_fmac_f32_e32 v16, v50, v17
	v_max_i32_e32 v17, 0, v19
	v_fmac_f32_e32 v16, v51, v17
	v_max_i32_e32 v17, 0, v20
	v_fmac_f32_e32 v16, v52, v17
	v_max_i32_e32 v17, 0, v21
	v_fmac_f32_e32 v16, v53, v17
	v_max_i32_e32 v17, 0, v22
	v_fmac_f32_e32 v16, v54, v17
	v_max_i32_e32 v17, 0, v23
	v_fmac_f32_e32 v16, v55, v17
	v_max_i32_e32 v17, 0, v24
	v_fmac_f32_e32 v16, v56, v17
	v_max_i32_e32 v17, 0, v25
	v_fmac_f32_e32 v16, v57, v17
	v_max_i32_e32 v17, 0, v26
	v_fmac_f32_e32 v16, v58, v17
	v_max_i32_e32 v17, 0, v27
	v_fmac_f32_e32 v16, v59, v17
	v_max_i32_e32 v17, 0, v28
	v_fmac_f32_e32 v16, v60, v17
	v_max_i32_e32 v17, 0, v29
	v_fmac_f32_e32 v16, v61, v17
	v_max_i32_e32 v17, 0, v30
	s_cmp_eq_u32 s58, 31
	v_fmac_f32_e32 v16, v62, v17
	v_max_i32_e32 v17, 0, v31
	s_cselect_b64 s[64:65], -1, 0
	v_cmp_gt_i32_e32 vcc, v157, v203
	v_fmac_f32_e32 v16, v63, v17
	s_and_b64 vcc, s[64:65], vcc
	v_cndmask_b32_e32 v225, v16, v197, vcc
	s_branch .Lixj85
.Lixc84:
.LBB0_1322:
	s_nop 4
	v_max_i32_e32 v80, 0, v16
	v_fma_f32 v80, v48, v80, 0
	v_max_i32_e32 v81, 0, v17
	v_fmac_f32_e32 v80, v49, v81
	v_max_i32_e32 v81, 0, v18
	v_fmac_f32_e32 v80, v50, v81
	v_max_i32_e32 v81, 0, v19
	v_fmac_f32_e32 v80, v51, v81
	v_max_i32_e32 v81, 0, v20
	v_fmac_f32_e32 v80, v52, v81
	v_max_i32_e32 v81, 0, v21
	v_fmac_f32_e32 v80, v53, v81
	v_max_i32_e32 v81, 0, v22
	v_fmac_f32_e32 v80, v54, v81
	v_max_i32_e32 v81, 0, v23
	v_fmac_f32_e32 v80, v55, v81
	v_max_i32_e32 v81, 0, v24
	v_fmac_f32_e32 v80, v56, v81
	v_max_i32_e32 v81, 0, v25
	v_fmac_f32_e32 v80, v57, v81
	v_max_i32_e32 v81, 0, v26
	v_fmac_f32_e32 v80, v58, v81
	v_max_i32_e32 v81, 0, v27
	v_fmac_f32_e32 v80, v59, v81
	v_max_i32_e32 v81, 0, v28
	v_fmac_f32_e32 v80, v60, v81
	v_max_i32_e32 v81, 0, v29
	v_fmac_f32_e32 v80, v61, v81
	v_max_i32_e32 v81, 0, v30
	v_fmac_f32_e32 v80, v62, v81
	v_max_i32_e32 v81, 0, v31
	v_cmp_gt_i32_e32 vcc, v159, v203
	v_fmac_f32_e32 v80, v63, v81
	s_and_b64 vcc, s[52:53], vcc
	v_cndmask_b32_e32 v227, v80, v197, vcc
	s_branch .Lixj84
.Lixc83:
.LBB0_1324:
	v_cndmask_b32_e64 v84, 0, 1, s[66:67]
	v_cmp_ne_u32_e64 s[52:53], 1, v84
	s_andn2_b64 vcc, exec, s[66:67]
	v_mov_b32_e32 v228, 0xff800000
	s_cbranch_vccnz .LBB0_1326
	v_max_i32_e32 v84, 0, v0
	v_fma_f32 v84, v48, v84, 0
	v_max_i32_e32 v85, 0, v1
	v_fmac_f32_e32 v84, v49, v85
	v_max_i32_e32 v85, 0, v2
	v_fmac_f32_e32 v84, v50, v85
	v_max_i32_e32 v85, 0, v3
	v_fmac_f32_e32 v84, v51, v85
	v_max_i32_e32 v85, 0, v4
	v_fmac_f32_e32 v84, v52, v85
	v_max_i32_e32 v85, 0, v5
	v_fmac_f32_e32 v84, v53, v85
	v_max_i32_e32 v85, 0, v6
	v_fmac_f32_e32 v84, v54, v85
	v_max_i32_e32 v85, 0, v7
	v_fmac_f32_e32 v84, v55, v85
	v_max_i32_e32 v85, 0, v8
	v_fmac_f32_e32 v84, v56, v85
	v_max_i32_e32 v85, 0, v9
	v_fmac_f32_e32 v84, v57, v85
	v_max_i32_e32 v85, 0, v10
	v_fmac_f32_e32 v84, v58, v85
	v_max_i32_e32 v85, 0, v11
	v_fmac_f32_e32 v84, v59, v85
	v_max_i32_e32 v85, 0, v12
	v_fmac_f32_e32 v84, v60, v85
	v_max_i32_e32 v85, 0, v13
	v_fmac_f32_e32 v84, v61, v85
	v_max_i32_e32 v85, 0, v14
	s_cmp_eq_u32 s58, 34
	v_fmac_f32_e32 v84, v62, v85
	v_max_i32_e32 v85, 0, v15
	s_cselect_b64 s[66:67], -1, 0
	v_cmp_gt_i32_e32 vcc, v160, v203
	v_fmac_f32_e32 v84, v63, v85
	s_and_b64 vcc, s[66:67], vcc
	v_cndmask_b32_e32 v228, v84, v197, vcc
	s_branch .Lixj83
.Lixc82:
.LBB0_1330:
	v_cndmask_b32_e64 v80, 0, 1, s[64:65]
	v_cmp_ne_u32_e64 s[52:53], 1, v80
	s_andn2_b64 vcc, exec, s[64:65]
	v_mov_b32_e32 v229, 0xff800000
	s_cbranch_vccnz .LBB0_1332
	v_max_i32_e32 v80, 0, v16
	v_fma_f32 v80, v48, v80, 0
	v_max_i32_e32 v81, 0, v17
	v_fmac_f32_e32 v80, v49, v81
	v_max_i32_e32 v81, 0, v18
	v_fmac_f32_e32 v80, v50, v81
	v_max_i32_e32 v81, 0, v19
	v_fmac_f32_e32 v80, v51, v81
	v_max_i32_e32 v81, 0, v20
	v_fmac_f32_e32 v80, v52, v81
	v_max_i32_e32 v81, 0, v21
	v_fmac_f32_e32 v80, v53, v81
	v_max_i32_e32 v81, 0, v22
	v_fmac_f32_e32 v80, v54, v81
	v_max_i32_e32 v81, 0, v23
	v_fmac_f32_e32 v80, v55, v81
	v_max_i32_e32 v81, 0, v24
	v_fmac_f32_e32 v80, v56, v81
	v_max_i32_e32 v81, 0, v25
	v_fmac_f32_e32 v80, v57, v81
	v_max_i32_e32 v81, 0, v26
	v_fmac_f32_e32 v80, v58, v81
	v_max_i32_e32 v81, 0, v27
	v_fmac_f32_e32 v80, v59, v81
	v_max_i32_e32 v81, 0, v28
	v_fmac_f32_e32 v80, v60, v81
	v_max_i32_e32 v81, 0, v29
	v_fmac_f32_e32 v80, v61, v81
	v_max_i32_e32 v81, 0, v30
	s_cmp_eq_u32 s58, 35
	v_fmac_f32_e32 v80, v62, v81
	v_max_i32_e32 v81, 0, v31
	s_cselect_b64 s[64:65], -1, 0
	v_cmp_gt_i32_e32 vcc, v161, v203
	v_fmac_f32_e32 v80, v63, v81
	s_and_b64 vcc, s[64:65], vcc
	v_cndmask_b32_e32 v229, v80, v197, vcc
	s_branch .Lixj82
.Lixc81:
.LBB0_1336:
	v_cndmask_b32_e64 v84, 0, 1, s[66:67]
	v_cmp_ne_u32_e64 s[52:53], 1, v84
	s_andn2_b64 vcc, exec, s[66:67]
	v_mov_b32_e32 v230, 0xff800000
	s_cbranch_vccnz .LBB0_1338
	v_max_i32_e32 v84, 0, v0
	v_fma_f32 v84, v48, v84, 0
	v_max_i32_e32 v85, 0, v1
	v_fmac_f32_e32 v84, v49, v85
	v_max_i32_e32 v85, 0, v2
	v_fmac_f32_e32 v84, v50, v85
	v_max_i32_e32 v85, 0, v3
	v_fmac_f32_e32 v84, v51, v85
	v_max_i32_e32 v85, 0, v4
	v_fmac_f32_e32 v84, v52, v85
	v_max_i32_e32 v85, 0, v5
	v_fmac_f32_e32 v84, v53, v85
	v_max_i32_e32 v85, 0, v6
	v_fmac_f32_e32 v84, v54, v85
	v_max_i32_e32 v85, 0, v7
	v_fmac_f32_e32 v84, v55, v85
	v_max_i32_e32 v85, 0, v8
	v_fmac_f32_e32 v84, v56, v85
	v_max_i32_e32 v85, 0, v9
	v_fmac_f32_e32 v84, v57, v85
	v_max_i32_e32 v85, 0, v10
	v_fmac_f32_e32 v84, v58, v85
	v_max_i32_e32 v85, 0, v11
	v_fmac_f32_e32 v84, v59, v85
	v_max_i32_e32 v85, 0, v12
	v_fmac_f32_e32 v84, v60, v85
	v_max_i32_e32 v85, 0, v13
	v_fmac_f32_e32 v84, v61, v85
	v_max_i32_e32 v85, 0, v14
	s_cmp_eq_u32 s58, 36
	v_fmac_f32_e32 v84, v62, v85
	v_max_i32_e32 v85, 0, v15
	s_cselect_b64 s[66:67], -1, 0
	v_cmp_gt_i32_e32 vcc, v162, v203
	v_fmac_f32_e32 v84, v63, v85
	s_and_b64 vcc, s[66:67], vcc
	v_cndmask_b32_e32 v230, v84, v197, vcc
	s_branch .Lixj81
.Lixc80:
.LBB0_1342:
	v_cndmask_b32_e64 v80, 0, 1, s[64:65]
	v_cmp_ne_u32_e64 s[52:53], 1, v80
	s_andn2_b64 vcc, exec, s[64:65]
	v_mov_b32_e32 v231, 0xff800000
	s_cbranch_vccnz .LBB0_1344
	v_max_i32_e32 v80, 0, v16
	v_fma_f32 v80, v48, v80, 0
	v_max_i32_e32 v81, 0, v17
	v_fmac_f32_e32 v80, v49, v81
	v_max_i32_e32 v81, 0, v18
	v_fmac_f32_e32 v80, v50, v81
	v_max_i32_e32 v81, 0, v19
	v_fmac_f32_e32 v80, v51, v81
	v_max_i32_e32 v81, 0, v20
	v_fmac_f32_e32 v80, v52, v81
	v_max_i32_e32 v81, 0, v21
	v_fmac_f32_e32 v80, v53, v81
	v_max_i32_e32 v81, 0, v22
	v_fmac_f32_e32 v80, v54, v81
	v_max_i32_e32 v81, 0, v23
	v_fmac_f32_e32 v80, v55, v81
	v_max_i32_e32 v81, 0, v24
	v_fmac_f32_e32 v80, v56, v81
	v_max_i32_e32 v81, 0, v25
	v_fmac_f32_e32 v80, v57, v81
	v_max_i32_e32 v81, 0, v26
	v_fmac_f32_e32 v80, v58, v81
	v_max_i32_e32 v81, 0, v27
	v_fmac_f32_e32 v80, v59, v81
	v_max_i32_e32 v81, 0, v28
	v_fmac_f32_e32 v80, v60, v81
	v_max_i32_e32 v81, 0, v29
	v_fmac_f32_e32 v80, v61, v81
	v_max_i32_e32 v81, 0, v30
	s_cmp_eq_u32 s58, 37
	v_fmac_f32_e32 v80, v62, v81
	v_max_i32_e32 v81, 0, v31
	s_cselect_b64 s[64:65], -1, 0
	v_cmp_gt_i32_e32 vcc, v163, v203
	v_fmac_f32_e32 v80, v63, v81
	s_and_b64 vcc, s[64:65], vcc
	v_cndmask_b32_e32 v231, v80, v197, vcc
	s_branch .Lixj80
.Lixc79:
.LBB0_1348:
	v_cndmask_b32_e64 v84, 0, 1, s[66:67]
	v_cmp_ne_u32_e64 s[52:53], 1, v84
	s_andn2_b64 vcc, exec, s[66:67]
	v_mov_b32_e32 v232, 0xff800000
	s_cbranch_vccnz .LBB0_1350
	v_max_i32_e32 v84, 0, v0
	v_fma_f32 v84, v48, v84, 0
	v_max_i32_e32 v85, 0, v1
	v_fmac_f32_e32 v84, v49, v85
	v_max_i32_e32 v85, 0, v2
	v_fmac_f32_e32 v84, v50, v85
	v_max_i32_e32 v85, 0, v3
	v_fmac_f32_e32 v84, v51, v85
	v_max_i32_e32 v85, 0, v4
	v_fmac_f32_e32 v84, v52, v85
	v_max_i32_e32 v85, 0, v5
	v_fmac_f32_e32 v84, v53, v85
	v_max_i32_e32 v85, 0, v6
	v_fmac_f32_e32 v84, v54, v85
	v_max_i32_e32 v85, 0, v7
	v_fmac_f32_e32 v84, v55, v85
	v_max_i32_e32 v85, 0, v8
	v_fmac_f32_e32 v84, v56, v85
	v_max_i32_e32 v85, 0, v9
	v_fmac_f32_e32 v84, v57, v85
	v_max_i32_e32 v85, 0, v10
	v_fmac_f32_e32 v84, v58, v85
	v_max_i32_e32 v85, 0, v11
	v_fmac_f32_e32 v84, v59, v85
	v_max_i32_e32 v85, 0, v12
	v_fmac_f32_e32 v84, v60, v85
	v_max_i32_e32 v85, 0, v13
	v_fmac_f32_e32 v84, v61, v85
	v_max_i32_e32 v85, 0, v14
	s_cmp_eq_u32 s58, 38
	v_fmac_f32_e32 v84, v62, v85
	v_max_i32_e32 v85, 0, v15
	s_cselect_b64 s[66:67], -1, 0
	v_cmp_gt_i32_e32 vcc, v164, v203
	v_fmac_f32_e32 v84, v63, v85
	s_and_b64 vcc, s[66:67], vcc
	v_cndmask_b32_e32 v232, v84, v197, vcc
	s_branch .Lixj79
.Lixc78:
.LBB0_1354:
	v_cndmask_b32_e64 v80, 0, 1, s[64:65]
	v_cmp_ne_u32_e64 s[52:53], 1, v80
	s_andn2_b64 vcc, exec, s[64:65]
	v_mov_b32_e32 v233, 0xff800000
	s_cbranch_vccnz .LBB0_1356
	v_max_i32_e32 v16, 0, v16
	v_fma_f32 v16, v48, v16, 0
	v_max_i32_e32 v17, 0, v17
	v_fmac_f32_e32 v16, v49, v17
	v_max_i32_e32 v17, 0, v18
	v_fmac_f32_e32 v16, v50, v17
	v_max_i32_e32 v17, 0, v19
	v_fmac_f32_e32 v16, v51, v17
	v_max_i32_e32 v17, 0, v20
	v_fmac_f32_e32 v16, v52, v17
	v_max_i32_e32 v17, 0, v21
	v_fmac_f32_e32 v16, v53, v17
	v_max_i32_e32 v17, 0, v22
	v_fmac_f32_e32 v16, v54, v17
	v_max_i32_e32 v17, 0, v23
	v_fmac_f32_e32 v16, v55, v17
	v_max_i32_e32 v17, 0, v24
	v_fmac_f32_e32 v16, v56, v17
	v_max_i32_e32 v17, 0, v25
	v_fmac_f32_e32 v16, v57, v17
	v_max_i32_e32 v17, 0, v26
	v_fmac_f32_e32 v16, v58, v17
	v_max_i32_e32 v17, 0, v27
	v_fmac_f32_e32 v16, v59, v17
	v_max_i32_e32 v17, 0, v28
	v_fmac_f32_e32 v16, v60, v17
	v_max_i32_e32 v17, 0, v29
	v_fmac_f32_e32 v16, v61, v17
	v_max_i32_e32 v17, 0, v30
	s_cmp_eq_u32 s58, 39
	v_fmac_f32_e32 v16, v62, v17
	v_max_i32_e32 v17, 0, v31
	s_cselect_b64 s[64:65], -1, 0
	v_cmp_gt_i32_e32 vcc, v165, v203
	v_fmac_f32_e32 v16, v63, v17
	s_and_b64 vcc, s[64:65], vcc
	v_cndmask_b32_e32 v233, v16, v197, vcc
	s_branch .Lixj78
.Lixc77:
.LBB0_1366:
	s_nop 4
	v_max_i32_e32 v80, 0, v16
	v_fma_f32 v80, v48, v80, 0
	v_max_i32_e32 v81, 0, v17
	v_fmac_f32_e32 v80, v49, v81
	v_max_i32_e32 v81, 0, v18
	v_fmac_f32_e32 v80, v50, v81
	v_max_i32_e32 v81, 0, v19
	v_fmac_f32_e32 v80, v51, v81
	v_max_i32_e32 v81, 0, v20
	v_fmac_f32_e32 v80, v52, v81
	v_max_i32_e32 v81, 0, v21
	v_fmac_f32_e32 v80, v53, v81
	v_max_i32_e32 v81, 0, v22
	v_fmac_f32_e32 v80, v54, v81
	v_max_i32_e32 v81, 0, v23
	v_fmac_f32_e32 v80, v55, v81
	v_max_i32_e32 v81, 0, v24
	v_fmac_f32_e32 v80, v56, v81
	v_max_i32_e32 v81, 0, v25
	v_fmac_f32_e32 v80, v57, v81
	v_max_i32_e32 v81, 0, v26
	v_fmac_f32_e32 v80, v58, v81
	v_max_i32_e32 v81, 0, v27
	v_fmac_f32_e32 v80, v59, v81
	v_max_i32_e32 v81, 0, v28
	v_fmac_f32_e32 v80, v60, v81
	v_max_i32_e32 v81, 0, v29
	v_fmac_f32_e32 v80, v61, v81
	v_max_i32_e32 v81, 0, v30
	v_fmac_f32_e32 v80, v62, v81
	v_max_i32_e32 v81, 0, v31
	v_cmp_gt_i32_e32 vcc, v167, v203
	v_fmac_f32_e32 v80, v63, v81
	s_and_b64 vcc, s[52:53], vcc
	v_cndmask_b32_e32 v235, v80, v197, vcc
	s_branch .Lixj77
.Lixc76:
.LBB0_1368:
	v_cndmask_b32_e64 v84, 0, 1, s[66:67]
	v_cmp_ne_u32_e64 s[52:53], 1, v84
	s_andn2_b64 vcc, exec, s[66:67]
	v_mov_b32_e32 v236, 0xff800000
	s_cbranch_vccnz .LBB0_1370
	v_max_i32_e32 v84, 0, v0
	v_fma_f32 v84, v48, v84, 0
	v_max_i32_e32 v85, 0, v1
	v_fmac_f32_e32 v84, v49, v85
	v_max_i32_e32 v85, 0, v2
	v_fmac_f32_e32 v84, v50, v85
	v_max_i32_e32 v85, 0, v3
	v_fmac_f32_e32 v84, v51, v85
	v_max_i32_e32 v85, 0, v4
	v_fmac_f32_e32 v84, v52, v85
	v_max_i32_e32 v85, 0, v5
	v_fmac_f32_e32 v84, v53, v85
	v_max_i32_e32 v85, 0, v6
	v_fmac_f32_e32 v84, v54, v85
	v_max_i32_e32 v85, 0, v7
	v_fmac_f32_e32 v84, v55, v85
	v_max_i32_e32 v85, 0, v8
	v_fmac_f32_e32 v84, v56, v85
	v_max_i32_e32 v85, 0, v9
	v_fmac_f32_e32 v84, v57, v85
	v_max_i32_e32 v85, 0, v10
	v_fmac_f32_e32 v84, v58, v85
	v_max_i32_e32 v85, 0, v11
	v_fmac_f32_e32 v84, v59, v85
	v_max_i32_e32 v85, 0, v12
	v_fmac_f32_e32 v84, v60, v85
	v_max_i32_e32 v85, 0, v13
	v_fmac_f32_e32 v84, v61, v85
	v_max_i32_e32 v85, 0, v14
	s_cmp_eq_u32 s58, 42
	v_fmac_f32_e32 v84, v62, v85
	v_max_i32_e32 v85, 0, v15
	s_cselect_b64 s[66:67], -1, 0
	v_cmp_gt_i32_e32 vcc, v168, v203
	v_fmac_f32_e32 v84, v63, v85
	s_and_b64 vcc, s[66:67], vcc
	v_cndmask_b32_e32 v236, v84, v197, vcc
	s_branch .Lixj76
.Lixc75:
.LBB0_1374:
	v_cndmask_b32_e64 v80, 0, 1, s[64:65]
	v_cmp_ne_u32_e64 s[52:53], 1, v80
	s_andn2_b64 vcc, exec, s[64:65]
	v_mov_b32_e32 v237, 0xff800000
	s_cbranch_vccnz .LBB0_1376
	v_max_i32_e32 v80, 0, v16
	v_fma_f32 v80, v48, v80, 0
	v_max_i32_e32 v81, 0, v17
	v_fmac_f32_e32 v80, v49, v81
	v_max_i32_e32 v81, 0, v18
	v_fmac_f32_e32 v80, v50, v81
	v_max_i32_e32 v81, 0, v19
	v_fmac_f32_e32 v80, v51, v81
	v_max_i32_e32 v81, 0, v20
	v_fmac_f32_e32 v80, v52, v81
	v_max_i32_e32 v81, 0, v21
	v_fmac_f32_e32 v80, v53, v81
	v_max_i32_e32 v81, 0, v22
	v_fmac_f32_e32 v80, v54, v81
	v_max_i32_e32 v81, 0, v23
	v_fmac_f32_e32 v80, v55, v81
	v_max_i32_e32 v81, 0, v24
	v_fmac_f32_e32 v80, v56, v81
	v_max_i32_e32 v81, 0, v25
	v_fmac_f32_e32 v80, v57, v81
	v_max_i32_e32 v81, 0, v26
	v_fmac_f32_e32 v80, v58, v81
	v_max_i32_e32 v81, 0, v27
	v_fmac_f32_e32 v80, v59, v81
	v_max_i32_e32 v81, 0, v28
	v_fmac_f32_e32 v80, v60, v81
	v_max_i32_e32 v81, 0, v29
	v_fmac_f32_e32 v80, v61, v81
	v_max_i32_e32 v81, 0, v30
	s_cmp_eq_u32 s58, 43
	v_fmac_f32_e32 v80, v62, v81
	v_max_i32_e32 v81, 0, v31
	s_cselect_b64 s[64:65], -1, 0
	v_cmp_gt_i32_e32 vcc, v169, v203
	v_fmac_f32_e32 v80, v63, v81
	s_and_b64 vcc, s[64:65], vcc
	v_cndmask_b32_e32 v237, v80, v197, vcc
	s_branch .Lixj75
.Lixc74:
.LBB0_1380:
	v_cndmask_b32_e64 v84, 0, 1, s[66:67]
	v_cmp_ne_u32_e64 s[52:53], 1, v84
	s_andn2_b64 vcc, exec, s[66:67]
	v_mov_b32_e32 v238, 0xff800000
	s_cbranch_vccnz .LBB0_1382
	v_max_i32_e32 v84, 0, v0
	v_fma_f32 v84, v48, v84, 0
	v_max_i32_e32 v85, 0, v1
	v_fmac_f32_e32 v84, v49, v85
	v_max_i32_e32 v85, 0, v2
	v_fmac_f32_e32 v84, v50, v85
	v_max_i32_e32 v85, 0, v3
	v_fmac_f32_e32 v84, v51, v85
	v_max_i32_e32 v85, 0, v4
	v_fmac_f32_e32 v84, v52, v85
	v_max_i32_e32 v85, 0, v5
	v_fmac_f32_e32 v84, v53, v85
	v_max_i32_e32 v85, 0, v6
	v_fmac_f32_e32 v84, v54, v85
	v_max_i32_e32 v85, 0, v7
	v_fmac_f32_e32 v84, v55, v85
	v_max_i32_e32 v85, 0, v8
	v_fmac_f32_e32 v84, v56, v85
	v_max_i32_e32 v85, 0, v9
	v_fmac_f32_e32 v84, v57, v85
	v_max_i32_e32 v85, 0, v10
	v_fmac_f32_e32 v84, v58, v85
	v_max_i32_e32 v85, 0, v11
	v_fmac_f32_e32 v84, v59, v85
	v_max_i32_e32 v85, 0, v12
	v_fmac_f32_e32 v84, v60, v85
	v_max_i32_e32 v85, 0, v13
	v_fmac_f32_e32 v84, v61, v85
	v_max_i32_e32 v85, 0, v14
	s_cmp_eq_u32 s58, 44
	v_fmac_f32_e32 v84, v62, v85
	v_max_i32_e32 v85, 0, v15
	s_cselect_b64 s[66:67], -1, 0
	v_cmp_gt_i32_e32 vcc, v170, v203
	v_fmac_f32_e32 v84, v63, v85
	s_and_b64 vcc, s[66:67], vcc
	v_cndmask_b32_e32 v238, v84, v197, vcc
	s_branch .Lixj74
.Lixc73:
.LBB0_1386:
	v_cndmask_b32_e64 v80, 0, 1, s[64:65]
	v_cmp_ne_u32_e64 s[52:53], 1, v80
	s_andn2_b64 vcc, exec, s[64:65]
	v_mov_b32_e32 v239, 0xff800000
	s_cbranch_vccnz .LBB0_1388
	v_max_i32_e32 v80, 0, v16
	v_fma_f32 v80, v48, v80, 0
	v_max_i32_e32 v81, 0, v17
	v_fmac_f32_e32 v80, v49, v81
	v_max_i32_e32 v81, 0, v18
	v_fmac_f32_e32 v80, v50, v81
	v_max_i32_e32 v81, 0, v19
	v_fmac_f32_e32 v80, v51, v81
	v_max_i32_e32 v81, 0, v20
	v_fmac_f32_e32 v80, v52, v81
	v_max_i32_e32 v81, 0, v21
	v_fmac_f32_e32 v80, v53, v81
	v_max_i32_e32 v81, 0, v22
	v_fmac_f32_e32 v80, v54, v81
	v_max_i32_e32 v81, 0, v23
	v_fmac_f32_e32 v80, v55, v81
	v_max_i32_e32 v81, 0, v24
	v_fmac_f32_e32 v80, v56, v81
	v_max_i32_e32 v81, 0, v25
	v_fmac_f32_e32 v80, v57, v81
	v_max_i32_e32 v81, 0, v26
	v_fmac_f32_e32 v80, v58, v81
	v_max_i32_e32 v81, 0, v27
	v_fmac_f32_e32 v80, v59, v81
	v_max_i32_e32 v81, 0, v28
	v_fmac_f32_e32 v80, v60, v81
	v_max_i32_e32 v81, 0, v29
	v_fmac_f32_e32 v80, v61, v81
	v_max_i32_e32 v81, 0, v30
	s_cmp_eq_u32 s58, 45
	v_fmac_f32_e32 v80, v62, v81
	v_max_i32_e32 v81, 0, v31
	s_cselect_b64 s[64:65], -1, 0
	v_cmp_gt_i32_e32 vcc, v171, v203
	v_fmac_f32_e32 v80, v63, v81
	s_and_b64 vcc, s[64:65], vcc
	v_cndmask_b32_e32 v239, v80, v197, vcc
	s_branch .Lixj73
.Lixc72:
.LBB0_1392:
	v_cndmask_b32_e64 v84, 0, 1, s[66:67]
	v_cmp_ne_u32_e64 s[52:53], 1, v84
	s_andn2_b64 vcc, exec, s[66:67]
	v_mov_b32_e32 v240, 0xff800000
	s_cbranch_vccnz .LBB0_1394
	v_max_i32_e32 v84, 0, v0
	v_fma_f32 v84, v48, v84, 0
	v_max_i32_e32 v85, 0, v1
	v_fmac_f32_e32 v84, v49, v85
	v_max_i32_e32 v85, 0, v2
	v_fmac_f32_e32 v84, v50, v85
	v_max_i32_e32 v85, 0, v3
	v_fmac_f32_e32 v84, v51, v85
	v_max_i32_e32 v85, 0, v4
	v_fmac_f32_e32 v84, v52, v85
	v_max_i32_e32 v85, 0, v5
	v_fmac_f32_e32 v84, v53, v85
	v_max_i32_e32 v85, 0, v6
	v_fmac_f32_e32 v84, v54, v85
	v_max_i32_e32 v85, 0, v7
	v_fmac_f32_e32 v84, v55, v85
	v_max_i32_e32 v85, 0, v8
	v_fmac_f32_e32 v84, v56, v85
	v_max_i32_e32 v85, 0, v9
	v_fmac_f32_e32 v84, v57, v85
	v_max_i32_e32 v85, 0, v10
	v_fmac_f32_e32 v84, v58, v85
	v_max_i32_e32 v85, 0, v11
	v_fmac_f32_e32 v84, v59, v85
	v_max_i32_e32 v85, 0, v12
	v_fmac_f32_e32 v84, v60, v85
	v_max_i32_e32 v85, 0, v13
	v_fmac_f32_e32 v84, v61, v85
	v_max_i32_e32 v85, 0, v14
	s_cmp_eq_u32 s58, 46
	v_fmac_f32_e32 v84, v62, v85
	v_max_i32_e32 v85, 0, v15
	s_cselect_b64 s[66:67], -1, 0
	v_cmp_gt_i32_e32 vcc, v172, v203
	v_fmac_f32_e32 v84, v63, v85
	s_and_b64 vcc, s[66:67], vcc
	v_cndmask_b32_e32 v240, v84, v197, vcc
	s_branch .Lixj72
.Lixc71:
.LBB0_1398:
	v_cndmask_b32_e64 v80, 0, 1, s[64:65]
	v_cmp_ne_u32_e64 s[52:53], 1, v80
	s_andn2_b64 vcc, exec, s[64:65]
	v_mov_b32_e32 v241, 0xff800000
	s_cbranch_vccnz .LBB0_1400
	v_max_i32_e32 v16, 0, v16
	v_fma_f32 v16, v48, v16, 0
	v_max_i32_e32 v17, 0, v17
	v_fmac_f32_e32 v16, v49, v17
	v_max_i32_e32 v17, 0, v18
	v_fmac_f32_e32 v16, v50, v17
	v_max_i32_e32 v17, 0, v19
	v_fmac_f32_e32 v16, v51, v17
	v_max_i32_e32 v17, 0, v20
	v_fmac_f32_e32 v16, v52, v17
	v_max_i32_e32 v17, 0, v21
	v_fmac_f32_e32 v16, v53, v17
	v_max_i32_e32 v17, 0, v22
	v_fmac_f32_e32 v16, v54, v17
	v_max_i32_e32 v17, 0, v23
	v_fmac_f32_e32 v16, v55, v17
	v_max_i32_e32 v17, 0, v24
	v_fmac_f32_e32 v16, v56, v17
	v_max_i32_e32 v17, 0, v25
	v_fmac_f32_e32 v16, v57, v17
	v_max_i32_e32 v17, 0, v26
	v_fmac_f32_e32 v16, v58, v17
	v_max_i32_e32 v17, 0, v27
	v_fmac_f32_e32 v16, v59, v17
	v_max_i32_e32 v17, 0, v28
	v_fmac_f32_e32 v16, v60, v17
	v_max_i32_e32 v17, 0, v29
	v_fmac_f32_e32 v16, v61, v17
	v_max_i32_e32 v17, 0, v30
	s_cmp_eq_u32 s58, 47
	v_fmac_f32_e32 v16, v62, v17
	v_max_i32_e32 v17, 0, v31
	s_cselect_b64 s[64:65], -1, 0
	v_cmp_gt_i32_e32 vcc, v173, v203
	v_fmac_f32_e32 v16, v63, v17
	s_and_b64 vcc, s[64:65], vcc
	v_cndmask_b32_e32 v241, v16, v197, vcc
	s_branch .Lixj71
.Lixc70:
.LBB0_1410:
	s_nop 4
	v_max_i32_e32 v80, 0, v16
	v_fma_f32 v80, v48, v80, 0
	v_max_i32_e32 v81, 0, v17
	v_fmac_f32_e32 v80, v49, v81
	v_max_i32_e32 v81, 0, v18
	v_fmac_f32_e32 v80, v50, v81
	v_max_i32_e32 v81, 0, v19
	v_fmac_f32_e32 v80, v51, v81
	v_max_i32_e32 v81, 0, v20
	v_fmac_f32_e32 v80, v52, v81
	v_max_i32_e32 v81, 0, v21
	v_fmac_f32_e32 v80, v53, v81
	v_max_i32_e32 v81, 0, v22
	v_fmac_f32_e32 v80, v54, v81
	v_max_i32_e32 v81, 0, v23
	v_fmac_f32_e32 v80, v55, v81
	v_max_i32_e32 v81, 0, v24
	v_fmac_f32_e32 v80, v56, v81
	v_max_i32_e32 v81, 0, v25
	v_fmac_f32_e32 v80, v57, v81
	v_max_i32_e32 v81, 0, v26
	v_fmac_f32_e32 v80, v58, v81
	v_max_i32_e32 v81, 0, v27
	v_fmac_f32_e32 v80, v59, v81
	v_max_i32_e32 v81, 0, v28
	v_fmac_f32_e32 v80, v60, v81
	v_max_i32_e32 v81, 0, v29
	v_fmac_f32_e32 v80, v61, v81
	v_max_i32_e32 v81, 0, v30
	v_fmac_f32_e32 v80, v62, v81
	v_max_i32_e32 v81, 0, v31
	v_cmp_gt_i32_e32 vcc, v175, v203
	v_fmac_f32_e32 v80, v63, v81
	s_and_b64 vcc, s[52:53], vcc
	v_cndmask_b32_e32 v243, v80, v197, vcc
	s_branch .Lixj70
.Lixc69:
.LBB0_1412:
	v_cndmask_b32_e64 v84, 0, 1, s[64:65]
	v_cmp_ne_u32_e64 s[52:53], 1, v84
	s_andn2_b64 vcc, exec, s[64:65]
	v_mov_b32_e32 v244, 0xff800000
	s_cbranch_vccnz .LBB0_1414
	v_max_i32_e32 v84, 0, v0
	v_fma_f32 v84, v48, v84, 0
	v_max_i32_e32 v85, 0, v1
	v_fmac_f32_e32 v84, v49, v85
	v_max_i32_e32 v85, 0, v2
	v_fmac_f32_e32 v84, v50, v85
	v_max_i32_e32 v85, 0, v3
	v_fmac_f32_e32 v84, v51, v85
	v_max_i32_e32 v85, 0, v4
	v_fmac_f32_e32 v84, v52, v85
	v_max_i32_e32 v85, 0, v5
	v_fmac_f32_e32 v84, v53, v85
	v_max_i32_e32 v85, 0, v6
	v_fmac_f32_e32 v84, v54, v85
	v_max_i32_e32 v85, 0, v7
	v_fmac_f32_e32 v84, v55, v85
	v_max_i32_e32 v85, 0, v8
	v_fmac_f32_e32 v84, v56, v85
	v_max_i32_e32 v85, 0, v9
	v_fmac_f32_e32 v84, v57, v85
	v_max_i32_e32 v85, 0, v10
	v_fmac_f32_e32 v84, v58, v85
	v_max_i32_e32 v85, 0, v11
	v_fmac_f32_e32 v84, v59, v85
	v_max_i32_e32 v85, 0, v12
	v_fmac_f32_e32 v84, v60, v85
	v_max_i32_e32 v85, 0, v13
	v_fmac_f32_e32 v84, v61, v85
	v_max_i32_e32 v85, 0, v14
	s_cmp_eq_u32 s58, 50
	v_fmac_f32_e32 v84, v62, v85
	v_max_i32_e32 v85, 0, v15
	s_cselect_b64 s[64:65], -1, 0
	v_cmp_gt_i32_e32 vcc, v176, v203
	v_fmac_f32_e32 v84, v63, v85
	s_and_b64 vcc, s[64:65], vcc
	v_cndmask_b32_e32 v244, v84, v197, vcc
	s_branch .Lixj69
.Lixc68:
.LBB0_1418:
	v_cndmask_b32_e64 v80, 0, 1, s[60:61]
	v_cmp_ne_u32_e64 s[52:53], 1, v80
	s_andn2_b64 vcc, exec, s[60:61]
	v_mov_b32_e32 v245, 0xff800000
	s_cbranch_vccnz .LBB0_1420
	v_max_i32_e32 v80, 0, v16
	v_fma_f32 v80, v48, v80, 0
	v_max_i32_e32 v81, 0, v17
	v_fmac_f32_e32 v80, v49, v81
	v_max_i32_e32 v81, 0, v18
	v_fmac_f32_e32 v80, v50, v81
	v_max_i32_e32 v81, 0, v19
	v_fmac_f32_e32 v80, v51, v81
	v_max_i32_e32 v81, 0, v20
	v_fmac_f32_e32 v80, v52, v81
	v_max_i32_e32 v81, 0, v21
	v_fmac_f32_e32 v80, v53, v81
	v_max_i32_e32 v81, 0, v22
	v_fmac_f32_e32 v80, v54, v81
	v_max_i32_e32 v81, 0, v23
	v_fmac_f32_e32 v80, v55, v81
	v_max_i32_e32 v81, 0, v24
	v_fmac_f32_e32 v80, v56, v81
	v_max_i32_e32 v81, 0, v25
	v_fmac_f32_e32 v80, v57, v81
	v_max_i32_e32 v81, 0, v26
	v_fmac_f32_e32 v80, v58, v81
	v_max_i32_e32 v81, 0, v27
	v_fmac_f32_e32 v80, v59, v81
	v_max_i32_e32 v81, 0, v28
	v_fmac_f32_e32 v80, v60, v81
	v_max_i32_e32 v81, 0, v29
	v_fmac_f32_e32 v80, v61, v81
	v_max_i32_e32 v81, 0, v30
	s_cmp_eq_u32 s58, 51
	v_fmac_f32_e32 v80, v62, v81
	v_max_i32_e32 v81, 0, v31
	s_cselect_b64 s[60:61], -1, 0
	v_cmp_gt_i32_e32 vcc, v177, v203
	v_fmac_f32_e32 v80, v63, v81
	s_and_b64 vcc, s[60:61], vcc
	v_cndmask_b32_e32 v245, v80, v197, vcc
	s_branch .Lixj68
.Lixc67:
.LBB0_1424:
	v_cndmask_b32_e64 v84, 0, 1, s[64:65]
	v_cmp_ne_u32_e64 s[52:53], 1, v84
	s_andn2_b64 vcc, exec, s[64:65]
	v_mov_b32_e32 v246, 0xff800000
	s_cbranch_vccnz .LBB0_1426
	v_max_i32_e32 v84, 0, v0
	v_fma_f32 v84, v48, v84, 0
	v_max_i32_e32 v85, 0, v1
	v_fmac_f32_e32 v84, v49, v85
	v_max_i32_e32 v85, 0, v2
	v_fmac_f32_e32 v84, v50, v85
	v_max_i32_e32 v85, 0, v3
	v_fmac_f32_e32 v84, v51, v85
	v_max_i32_e32 v85, 0, v4
	v_fmac_f32_e32 v84, v52, v85
	v_max_i32_e32 v85, 0, v5
	v_fmac_f32_e32 v84, v53, v85
	v_max_i32_e32 v85, 0, v6
	v_fmac_f32_e32 v84, v54, v85
	v_max_i32_e32 v85, 0, v7
	v_fmac_f32_e32 v84, v55, v85
	v_max_i32_e32 v85, 0, v8
	v_fmac_f32_e32 v84, v56, v85
	v_max_i32_e32 v85, 0, v9
	v_fmac_f32_e32 v84, v57, v85
	v_max_i32_e32 v85, 0, v10
	v_fmac_f32_e32 v84, v58, v85
	v_max_i32_e32 v85, 0, v11
	v_fmac_f32_e32 v84, v59, v85
	v_max_i32_e32 v85, 0, v12
	v_fmac_f32_e32 v84, v60, v85
	v_max_i32_e32 v85, 0, v13
	v_fmac_f32_e32 v84, v61, v85
	v_max_i32_e32 v85, 0, v14
	s_cmp_eq_u32 s58, 52
	v_fmac_f32_e32 v84, v62, v85
	v_max_i32_e32 v85, 0, v15
	s_cselect_b64 s[64:65], -1, 0
	v_cmp_gt_i32_e32 vcc, v178, v203
	v_fmac_f32_e32 v84, v63, v85
	s_and_b64 vcc, s[64:65], vcc
	v_cndmask_b32_e32 v246, v84, v197, vcc
	s_branch .Lixj67
.Lixc66:
.LBB0_1430:
	v_cndmask_b32_e64 v80, 0, 1, s[60:61]
	v_cmp_ne_u32_e64 s[52:53], 1, v80
	s_andn2_b64 vcc, exec, s[60:61]
	v_mov_b32_e32 v247, 0xff800000
	s_cbranch_vccnz .LBB0_1432
	v_max_i32_e32 v80, 0, v16
	v_fma_f32 v80, v48, v80, 0
	v_max_i32_e32 v81, 0, v17
	v_fmac_f32_e32 v80, v49, v81
	v_max_i32_e32 v81, 0, v18
	v_fmac_f32_e32 v80, v50, v81
	v_max_i32_e32 v81, 0, v19
	v_fmac_f32_e32 v80, v51, v81
	v_max_i32_e32 v81, 0, v20
	v_fmac_f32_e32 v80, v52, v81
	v_max_i32_e32 v81, 0, v21
	v_fmac_f32_e32 v80, v53, v81
	v_max_i32_e32 v81, 0, v22
	v_fmac_f32_e32 v80, v54, v81
	v_max_i32_e32 v81, 0, v23
	v_fmac_f32_e32 v80, v55, v81
	v_max_i32_e32 v81, 0, v24
	v_fmac_f32_e32 v80, v56, v81
	v_max_i32_e32 v81, 0, v25
	v_fmac_f32_e32 v80, v57, v81
	v_max_i32_e32 v81, 0, v26
	v_fmac_f32_e32 v80, v58, v81
	v_max_i32_e32 v81, 0, v27
	v_fmac_f32_e32 v80, v59, v81
	v_max_i32_e32 v81, 0, v28
	v_fmac_f32_e32 v80, v60, v81
	v_max_i32_e32 v81, 0, v29
	v_fmac_f32_e32 v80, v61, v81
	v_max_i32_e32 v81, 0, v30
	s_cmp_eq_u32 s58, 53
	v_fmac_f32_e32 v80, v62, v81
	v_max_i32_e32 v81, 0, v31
	s_cselect_b64 s[60:61], -1, 0
	v_cmp_gt_i32_e32 vcc, v179, v203
	v_fmac_f32_e32 v80, v63, v81
	s_and_b64 vcc, s[60:61], vcc
	v_cndmask_b32_e32 v247, v80, v197, vcc
	s_branch .Lixj66
.Lixc65:
.LBB0_1436:
	v_cndmask_b32_e64 v84, 0, 1, s[64:65]
	v_cmp_ne_u32_e64 s[52:53], 1, v84
	s_andn2_b64 vcc, exec, s[64:65]
	v_mov_b32_e32 v248, 0xff800000
	s_cbranch_vccnz .LBB0_1438
	v_max_i32_e32 v84, 0, v0
	v_fma_f32 v84, v48, v84, 0
	v_max_i32_e32 v85, 0, v1
	v_fmac_f32_e32 v84, v49, v85
	v_max_i32_e32 v85, 0, v2
	v_fmac_f32_e32 v84, v50, v85
	v_max_i32_e32 v85, 0, v3
	v_fmac_f32_e32 v84, v51, v85
	v_max_i32_e32 v85, 0, v4
	v_fmac_f32_e32 v84, v52, v85
	v_max_i32_e32 v85, 0, v5
	v_fmac_f32_e32 v84, v53, v85
	v_max_i32_e32 v85, 0, v6
	v_fmac_f32_e32 v84, v54, v85
	v_max_i32_e32 v85, 0, v7
	v_fmac_f32_e32 v84, v55, v85
	v_max_i32_e32 v85, 0, v8
	v_fmac_f32_e32 v84, v56, v85
	v_max_i32_e32 v85, 0, v9
	v_fmac_f32_e32 v84, v57, v85
	v_max_i32_e32 v85, 0, v10
	v_fmac_f32_e32 v84, v58, v85
	v_max_i32_e32 v85, 0, v11
	v_fmac_f32_e32 v84, v59, v85
	v_max_i32_e32 v85, 0, v12
	v_fmac_f32_e32 v84, v60, v85
	v_max_i32_e32 v85, 0, v13
	v_fmac_f32_e32 v84, v61, v85
	v_max_i32_e32 v85, 0, v14
	s_cmp_eq_u32 s58, 54
	v_fmac_f32_e32 v84, v62, v85
	v_max_i32_e32 v85, 0, v15
	s_cselect_b64 s[64:65], -1, 0
	v_cmp_gt_i32_e32 vcc, v180, v203
	v_fmac_f32_e32 v84, v63, v85
	s_and_b64 vcc, s[64:65], vcc
	v_cndmask_b32_e32 v248, v84, v197, vcc
	s_branch .Lixj65
.Lixc64:
.LBB0_1442:
	v_cndmask_b32_e64 v80, 0, 1, s[60:61]
	v_cmp_ne_u32_e64 s[52:53], 1, v80
	s_andn2_b64 vcc, exec, s[60:61]
	v_mov_b32_e32 v249, 0xff800000
	s_cbranch_vccnz .LBB0_1444
	v_max_i32_e32 v16, 0, v16
	v_fma_f32 v16, v48, v16, 0
	v_max_i32_e32 v17, 0, v17
	v_fmac_f32_e32 v16, v49, v17
	v_max_i32_e32 v17, 0, v18
	v_fmac_f32_e32 v16, v50, v17
	v_max_i32_e32 v17, 0, v19
	v_fmac_f32_e32 v16, v51, v17
	v_max_i32_e32 v17, 0, v20
	v_fmac_f32_e32 v16, v52, v17
	v_max_i32_e32 v17, 0, v21
	v_fmac_f32_e32 v16, v53, v17
	v_max_i32_e32 v17, 0, v22
	v_fmac_f32_e32 v16, v54, v17
	v_max_i32_e32 v17, 0, v23
	v_fmac_f32_e32 v16, v55, v17
	v_max_i32_e32 v17, 0, v24
	v_fmac_f32_e32 v16, v56, v17
	v_max_i32_e32 v17, 0, v25
	v_fmac_f32_e32 v16, v57, v17
	v_max_i32_e32 v17, 0, v26
	v_fmac_f32_e32 v16, v58, v17
	v_max_i32_e32 v17, 0, v27
	v_fmac_f32_e32 v16, v59, v17
	v_max_i32_e32 v17, 0, v28
	v_fmac_f32_e32 v16, v60, v17
	v_max_i32_e32 v17, 0, v29
	v_fmac_f32_e32 v16, v61, v17
	v_max_i32_e32 v17, 0, v30
	s_cmp_eq_u32 s58, 55
	v_fmac_f32_e32 v16, v62, v17
	v_max_i32_e32 v17, 0, v31
	s_cselect_b64 s[60:61], -1, 0
	v_cmp_gt_i32_e32 vcc, v181, v203
	v_fmac_f32_e32 v16, v63, v17
	s_and_b64 vcc, s[60:61], vcc
	v_cndmask_b32_e32 v249, v16, v197, vcc
	s_branch .Lixj64
.Lixc63:
.LBB0_1452:
	s_nop 4
	v_max_i32_e32 v80, 0, v16
	v_fma_f32 v80, v48, v80, 0
	v_max_i32_e32 v81, 0, v17
	v_fmac_f32_e32 v80, v49, v81
	v_max_i32_e32 v81, 0, v18
	v_fmac_f32_e32 v80, v50, v81
	v_max_i32_e32 v81, 0, v19
	v_fmac_f32_e32 v80, v51, v81
	v_max_i32_e32 v81, 0, v20
	v_fmac_f32_e32 v80, v52, v81
	v_max_i32_e32 v81, 0, v21
	v_fmac_f32_e32 v80, v53, v81
	v_max_i32_e32 v81, 0, v22
	v_fmac_f32_e32 v80, v54, v81
	v_max_i32_e32 v81, 0, v23
	v_fmac_f32_e32 v80, v55, v81
	v_max_i32_e32 v81, 0, v24
	v_fmac_f32_e32 v80, v56, v81
	v_max_i32_e32 v81, 0, v25
	v_fmac_f32_e32 v80, v57, v81
	v_max_i32_e32 v81, 0, v26
	v_fmac_f32_e32 v80, v58, v81
	v_max_i32_e32 v81, 0, v27
	v_fmac_f32_e32 v80, v59, v81
	v_max_i32_e32 v81, 0, v28
	v_fmac_f32_e32 v80, v60, v81
	v_max_i32_e32 v81, 0, v29
	v_fmac_f32_e32 v80, v61, v81
	v_max_i32_e32 v81, 0, v30
	v_fmac_f32_e32 v80, v62, v81
	v_max_i32_e32 v81, 0, v31
	v_cmp_gt_i32_e32 vcc, v183, v203
	v_fmac_f32_e32 v80, v63, v81
	s_and_b64 vcc, s[52:53], vcc
	v_cndmask_b32_e32 v251, v80, v197, vcc
	s_branch .Lixj63
.Lixc62:
.LBB0_1454:
	v_cndmask_b32_e64 v84, 0, 1, s[62:63]
	v_cmp_ne_u32_e64 s[52:53], 1, v84
	s_andn2_b64 vcc, exec, s[62:63]
	v_mov_b32_e32 v252, 0xff800000
	s_cbranch_vccnz .LBB0_1456
	v_max_i32_e32 v84, 0, v0
	v_fma_f32 v84, v48, v84, 0
	v_max_i32_e32 v85, 0, v1
	v_fmac_f32_e32 v84, v49, v85
	v_max_i32_e32 v85, 0, v2
	v_fmac_f32_e32 v84, v50, v85
	v_max_i32_e32 v85, 0, v3
	v_fmac_f32_e32 v84, v51, v85
	v_max_i32_e32 v85, 0, v4
	v_fmac_f32_e32 v84, v52, v85
	v_max_i32_e32 v85, 0, v5
	v_fmac_f32_e32 v84, v53, v85
	v_max_i32_e32 v85, 0, v6
	v_fmac_f32_e32 v84, v54, v85
	v_max_i32_e32 v85, 0, v7
	v_fmac_f32_e32 v84, v55, v85
	v_max_i32_e32 v85, 0, v8
	v_fmac_f32_e32 v84, v56, v85
	v_max_i32_e32 v85, 0, v9
	v_fmac_f32_e32 v84, v57, v85
	v_max_i32_e32 v85, 0, v10
	v_fmac_f32_e32 v84, v58, v85
	v_max_i32_e32 v85, 0, v11
	v_fmac_f32_e32 v84, v59, v85
	v_max_i32_e32 v85, 0, v12
	v_fmac_f32_e32 v84, v60, v85
	v_max_i32_e32 v85, 0, v13
	v_fmac_f32_e32 v84, v61, v85
	v_max_i32_e32 v85, 0, v14
	s_cmp_eq_u32 s58, 58
	v_fmac_f32_e32 v84, v62, v85
	v_max_i32_e32 v85, 0, v15
	s_cselect_b64 s[62:63], -1, 0
	v_cmp_gt_i32_e32 vcc, v184, v203
	v_fmac_f32_e32 v84, v63, v85
	s_and_b64 vcc, s[62:63], vcc
	v_cndmask_b32_e32 v252, v84, v197, vcc
	s_branch .Lixj62
.Lixc61:
.LBB0_1460:
	v_cndmask_b32_e64 v80, 0, 1, s[60:61]
	v_cmp_ne_u32_e64 s[52:53], 1, v80
	s_andn2_b64 vcc, exec, s[60:61]
	v_mov_b32_e32 v253, 0xff800000
	s_cbranch_vccnz .LBB0_1462
	v_max_i32_e32 v80, 0, v16
	v_fma_f32 v80, v48, v80, 0
	v_max_i32_e32 v81, 0, v17
	v_fmac_f32_e32 v80, v49, v81
	v_max_i32_e32 v81, 0, v18
	v_fmac_f32_e32 v80, v50, v81
	v_max_i32_e32 v81, 0, v19
	v_fmac_f32_e32 v80, v51, v81
	v_max_i32_e32 v81, 0, v20
	v_fmac_f32_e32 v80, v52, v81
	v_max_i32_e32 v81, 0, v21
	v_fmac_f32_e32 v80, v53, v81
	v_max_i32_e32 v81, 0, v22
	v_fmac_f32_e32 v80, v54, v81
	v_max_i32_e32 v81, 0, v23
	v_fmac_f32_e32 v80, v55, v81
	v_max_i32_e32 v81, 0, v24
	v_fmac_f32_e32 v80, v56, v81
	v_max_i32_e32 v81, 0, v25
	v_fmac_f32_e32 v80, v57, v81
	v_max_i32_e32 v81, 0, v26
	v_fmac_f32_e32 v80, v58, v81
	v_max_i32_e32 v81, 0, v27
	v_fmac_f32_e32 v80, v59, v81
	v_max_i32_e32 v81, 0, v28
	v_fmac_f32_e32 v80, v60, v81
	v_max_i32_e32 v81, 0, v29
	v_fmac_f32_e32 v80, v61, v81
	v_max_i32_e32 v81, 0, v30
	s_cmp_eq_u32 s58, 59
	v_fmac_f32_e32 v80, v62, v81
	v_max_i32_e32 v81, 0, v31
	s_cselect_b64 s[60:61], -1, 0
	v_cmp_gt_i32_e32 vcc, v185, v203
	v_fmac_f32_e32 v80, v63, v81
	s_and_b64 vcc, s[60:61], vcc
	v_cndmask_b32_e32 v253, v80, v197, vcc
	s_branch .Lixj61
.Lixc60:
.LBB0_1466:
	v_cndmask_b32_e64 v84, 0, 1, s[62:63]
	v_cmp_ne_u32_e64 s[52:53], 1, v84
	s_andn2_b64 vcc, exec, s[62:63]
	v_mov_b32_e32 v215, 0xff800000
	s_cbranch_vccnz .LBB0_1468
	v_max_i32_e32 v84, 0, v0
	v_fma_f32 v84, v48, v84, 0
	v_max_i32_e32 v85, 0, v1
	v_fmac_f32_e32 v84, v49, v85
	v_max_i32_e32 v85, 0, v2
	v_fmac_f32_e32 v84, v50, v85
	v_max_i32_e32 v85, 0, v3
	v_fmac_f32_e32 v84, v51, v85
	v_max_i32_e32 v85, 0, v4
	v_fmac_f32_e32 v84, v52, v85
	v_max_i32_e32 v85, 0, v5
	v_fmac_f32_e32 v84, v53, v85
	v_max_i32_e32 v85, 0, v6
	v_fmac_f32_e32 v84, v54, v85
	v_max_i32_e32 v85, 0, v7
	v_fmac_f32_e32 v84, v55, v85
	v_max_i32_e32 v85, 0, v8
	v_fmac_f32_e32 v84, v56, v85
	v_max_i32_e32 v85, 0, v9
	v_fmac_f32_e32 v84, v57, v85
	v_max_i32_e32 v85, 0, v10
	v_fmac_f32_e32 v84, v58, v85
	v_max_i32_e32 v85, 0, v11
	v_fmac_f32_e32 v84, v59, v85
	v_max_i32_e32 v85, 0, v12
	v_fmac_f32_e32 v84, v60, v85
	v_max_i32_e32 v85, 0, v13
	v_fmac_f32_e32 v84, v61, v85
	v_max_i32_e32 v85, 0, v14
	s_cmp_eq_u32 s58, 60
	v_fmac_f32_e32 v84, v62, v85
	v_max_i32_e32 v85, 0, v15
	s_cselect_b64 s[62:63], -1, 0
	v_cmp_gt_i32_e32 vcc, v186, v203
	v_fmac_f32_e32 v84, v63, v85
	s_and_b64 vcc, s[62:63], vcc
	v_cndmask_b32_e32 v215, v84, v197, vcc
	s_branch .Lixj60
.Lixc59:
.LBB0_1472:
	v_cndmask_b32_e64 v80, 0, 1, s[60:61]
	v_cmp_ne_u32_e64 s[52:53], 1, v80
	s_andn2_b64 vcc, exec, s[60:61]
	v_mov_b32_e32 v133, 0xff800000
	s_cbranch_vccnz .LBB0_1474
	v_max_i32_e32 v80, 0, v16
	v_fma_f32 v80, v48, v80, 0
	v_max_i32_e32 v81, 0, v17
	v_fmac_f32_e32 v80, v49, v81
	v_max_i32_e32 v81, 0, v18
	v_fmac_f32_e32 v80, v50, v81
	v_max_i32_e32 v81, 0, v19
	v_fmac_f32_e32 v80, v51, v81
	v_max_i32_e32 v81, 0, v20
	v_fmac_f32_e32 v80, v52, v81
	v_max_i32_e32 v81, 0, v21
	v_fmac_f32_e32 v80, v53, v81
	v_max_i32_e32 v81, 0, v22
	v_fmac_f32_e32 v80, v54, v81
	v_max_i32_e32 v81, 0, v23
	v_fmac_f32_e32 v80, v55, v81
	v_max_i32_e32 v81, 0, v24
	v_fmac_f32_e32 v80, v56, v81
	v_max_i32_e32 v81, 0, v25
	v_fmac_f32_e32 v80, v57, v81
	v_max_i32_e32 v81, 0, v26
	v_fmac_f32_e32 v80, v58, v81
	v_max_i32_e32 v81, 0, v27
	v_fmac_f32_e32 v80, v59, v81
	v_max_i32_e32 v81, 0, v28
	v_fmac_f32_e32 v80, v60, v81
	v_max_i32_e32 v81, 0, v29
	v_fmac_f32_e32 v80, v61, v81
	v_max_i32_e32 v81, 0, v30
	s_cmp_eq_u32 s58, 61
	v_fmac_f32_e32 v80, v62, v81
	v_max_i32_e32 v81, 0, v31
	s_cselect_b64 s[60:61], -1, 0
	v_cmp_gt_i32_e32 vcc, v187, v203
	v_fmac_f32_e32 v80, v63, v81
	s_and_b64 vcc, s[60:61], vcc
	v_cndmask_b32_e32 v133, v80, v197, vcc
	s_branch .Lixj59
.Lixc58:
.LBB0_1478:
	v_cndmask_b32_e64 v84, 0, 1, s[62:63]
	v_cmp_ne_u32_e64 s[52:53], 1, v84
	s_andn2_b64 vcc, exec, s[62:63]
	v_mov_b32_e32 v84, 0xff800000
	s_cbranch_vccnz .LBB0_1480
	v_max_i32_e32 v84, 0, v0
	v_fma_f32 v84, v48, v84, 0
	v_max_i32_e32 v85, 0, v1
	v_fmac_f32_e32 v84, v49, v85
	v_max_i32_e32 v85, 0, v2
	v_fmac_f32_e32 v84, v50, v85
	v_max_i32_e32 v85, 0, v3
	v_fmac_f32_e32 v84, v51, v85
	v_max_i32_e32 v85, 0, v4
	v_fmac_f32_e32 v84, v52, v85
	v_max_i32_e32 v85, 0, v5
	v_fmac_f32_e32 v84, v53, v85
	v_max_i32_e32 v85, 0, v6
	v_fmac_f32_e32 v84, v54, v85
	v_max_i32_e32 v85, 0, v7
	v_fmac_f32_e32 v84, v55, v85
	v_max_i32_e32 v85, 0, v8
	v_fmac_f32_e32 v84, v56, v85
	v_max_i32_e32 v85, 0, v9
	v_fmac_f32_e32 v84, v57, v85
	v_max_i32_e32 v85, 0, v10
	v_fmac_f32_e32 v84, v58, v85
	v_max_i32_e32 v85, 0, v11
	v_fmac_f32_e32 v84, v59, v85
	v_max_i32_e32 v85, 0, v12
	v_fmac_f32_e32 v84, v60, v85
	v_max_i32_e32 v85, 0, v13
	v_fmac_f32_e32 v84, v61, v85
	v_max_i32_e32 v85, 0, v14
	s_cmp_eq_u32 s58, 62
	v_fmac_f32_e32 v84, v62, v85
	v_max_i32_e32 v85, 0, v15
	s_cselect_b64 s[62:63], -1, 0
	v_cmp_gt_i32_e32 vcc, v188, v203
	v_fmac_f32_e32 v84, v63, v85
	s_and_b64 vcc, s[62:63], vcc
	v_cndmask_b32_e32 v84, v84, v197, vcc
	s_branch .Lixj58
.Lixc57:
.LBB0_1484:
	v_cndmask_b32_e64 v80, 0, 1, s[60:61]
	v_cmp_ne_u32_e64 s[52:53], 1, v80
	s_andn2_b64 vcc, exec, s[60:61]
	v_mov_b32_e32 v80, 0xff800000
	s_cbranch_vccnz .LBB0_1486
	v_max_i32_e32 v16, 0, v16
	v_fma_f32 v16, v48, v16, 0
	v_max_i32_e32 v17, 0, v17
	v_fmac_f32_e32 v16, v49, v17
	v_max_i32_e32 v17, 0, v18
	v_fmac_f32_e32 v16, v50, v17
	v_max_i32_e32 v17, 0, v19
	v_fmac_f32_e32 v16, v51, v17
	v_max_i32_e32 v17, 0, v20
	v_fmac_f32_e32 v16, v52, v17
	v_max_i32_e32 v17, 0, v21
	v_fmac_f32_e32 v16, v53, v17
	v_max_i32_e32 v17, 0, v22
	v_fmac_f32_e32 v16, v54, v17
	v_max_i32_e32 v17, 0, v23
	v_fmac_f32_e32 v16, v55, v17
	v_max_i32_e32 v17, 0, v24
	v_fmac_f32_e32 v16, v56, v17
	v_max_i32_e32 v17, 0, v25
	v_fmac_f32_e32 v16, v57, v17
	v_max_i32_e32 v17, 0, v26
	v_fmac_f32_e32 v16, v58, v17
	v_max_i32_e32 v17, 0, v27
	v_fmac_f32_e32 v16, v59, v17
	v_max_i32_e32 v17, 0, v28
	v_fmac_f32_e32 v16, v60, v17
	v_max_i32_e32 v17, 0, v29
	v_fmac_f32_e32 v16, v61, v17
	v_max_i32_e32 v17, 0, v30
	s_cmp_eq_u32 s58, 63
	v_fmac_f32_e32 v16, v62, v17
	v_max_i32_e32 v17, 0, v31
	s_cselect_b64 s[60:61], -1, 0
	v_cmp_gt_i32_e32 vcc, v189, v203
	v_fmac_f32_e32 v16, v63, v17
	s_and_b64 vcc, s[60:61], vcc
	v_cndmask_b32_e32 v80, v16, v197, vcc
	s_branch .Lixj57

.LBB0_1744:
	ds_read_b128 v[0:3], v131 offset:0
	ds_read_b128 v[4:7], v131 offset:32
	ds_read_b128 v[10:13], v131 offset:64
	ds_read_b128 v[80:83], v131 offset:0x60
	s_cmp_lt_u32 s94, 2
	s_waitcnt lgkmcnt(0)
	ds_read_b128 v[108:111], v131 offset:0x1200
	ds_read_b128 v[104:107], v131 offset:0x1220
	ds_read_b128 v[100:103], v131 offset:0x1240
	ds_read_b128 v[96:99], v131 offset:0x1260
	s_cselect_b64 s[50:51], -1, 0
	v_mfma_f32_32x32x16_bf16 v[16:31], v[32:35], v[0:3], 0
	s_cmp_gt_u32 s94, 1
	v_mov_b32_e32 v0, 0
	v_mov_b32_e32 v1, 0
	v_mov_b32_e32 v2, 0
	v_mov_b32_e32 v3, 0
	v_mov_b32_e32 v8, 0
	v_mov_b32_e32 v9, 0
	v_mfma_f32_32x32x16_bf16 v[16:31], v[36:39], v[4:7], v[16:31]
	v_mov_b32_e32 v4, 0
	v_mov_b32_e32 v5, 0
	v_mov_b32_e32 v6, 0
	v_mov_b32_e32 v7, 0
	s_cselect_b64 s[52:53], -1, 0
	s_and_b64 vcc, exec, s[50:51]
	v_mov_b32_e32 v14, 0
	v_mfma_f32_32x32x16_bf16 v[16:31], v[40:43], v[10:13], v[16:31]
	v_mov_b32_e32 v10, 0
	v_mov_b32_e32 v11, 0
	v_mov_b32_e32 v12, 0
	v_mov_b32_e32 v13, 0
	v_mov_b32_e32 v15, 0
	v_mfma_f32_32x32x16_bf16 v[16:31], v[44:47], v[80:83], v[16:31]
	s_waitcnt lgkmcnt(0)
	ds_read_b128 v[92:95], v131 offset:0x2400
	ds_read_b128 v[88:91], v131 offset:0x2420
	ds_read_b128 v[84:87], v131 offset:0x2440
	ds_read_b128 v[80:83], v131 offset:0x2460
	s_cbranch_vccnz .Lixc56
	v_mfma_f32_32x32x16_bf16 v[0:15], v[32:35], v[108:111], 0
	s_nop 5
	v_max_i32_e32 v109, 0, v16
	v_fma_f32 v110, v48, v109, 0
	v_max_i32_e32 v109, 0, v17
	v_fmac_f32_e32 v110, v49, v109
	v_max_i32_e32 v109, 0, v18
	v_fmac_f32_e32 v110, v50, v109
	v_max_i32_e32 v109, 0, v19
	v_fmac_f32_e32 v110, v51, v109
	v_max_i32_e32 v109, 0, v20
	v_fmac_f32_e32 v110, v52, v109
	v_mfma_f32_32x32x16_bf16 v[0:15], v[36:39], v[104:107], v[0:15]
	v_max_i32_e32 v109, 0, v21
	v_fmac_f32_e32 v110, v53, v109
	v_max_i32_e32 v109, 0, v22
	v_fmac_f32_e32 v110, v54, v109
	v_max_i32_e32 v109, 0, v23
	v_fmac_f32_e32 v110, v55, v109
	v_max_i32_e32 v109, 0, v24
	v_fmac_f32_e32 v110, v56, v109
	v_max_i32_e32 v109, 0, v25
	v_fmac_f32_e32 v110, v57, v109
	v_mfma_f32_32x32x16_bf16 v[0:15], v[40:43], v[100:103], v[0:15]
	v_max_i32_e32 v109, 0, v26
	s_ashr_i32 s1, s60, 5
	v_fmac_f32_e32 v110, v58, v109
	v_max_i32_e32 v109, 0, v27
	s_lshl_b32 s0, s94, 4
	s_and_b32 s95, s1, -2
	v_fmac_f32_e32 v110, v59, v109
	v_max_i32_e32 v109, 0, v28
	s_add_i32 s95, s95, s0
	v_fmac_f32_e32 v110, v60, v109
	v_max_i32_e32 v109, 0, v29
	v_or_b32_e32 v203, s95, v129
	v_fmac_f32_e32 v110, v61, v109
	v_mfma_f32_32x32x16_bf16 v[0:15], v[44:47], v[96:99], v[0:15]
	v_max_i32_e32 v109, 0, v30
	v_fmac_f32_e32 v110, v62, v109
	v_max_i32_e32 v109, 0, v31
	v_cmp_gt_i32_e32 vcc, v130, v203
	v_fmac_f32_e32 v110, v63, v109
	s_and_b64 vcc, s[50:51], vcc
	v_cndmask_b32_e32 v200, v110, v197, vcc
.Lixj56:
	s_waitcnt lgkmcnt(0)
	ds_read_b128 v[104:107], v131 offset:0x3600
	ds_read_b128 v[100:103], v131 offset:0x3620
	ds_read_b128 v[96:99], v131 offset:0x3640
	ds_read_b128 v[108:111], v131 offset:0x3660
	s_cmp_gt_u32 s94, 3
	s_cselect_b64 s[66:67], -1, 0
	s_cmp_lt_u32 s94, 4
	s_cbranch_scc1 .Lixc55
	v_mfma_f32_32x32x16_bf16 v[16:31], v[32:35], v[92:95], 0
	s_lshr_b32 s60, s94, 1
	v_cndmask_b32_e64 v93, 0, 1, s[52:53]
	s_add_i32 s60, s60, 1
	v_cmp_ne_u32_e64 s[50:51], 1, v93
	s_andn2_b64 vcc, exec, s[52:53]
	v_max_i32_e32 v93, 0, v0
	v_fma_f32 v94, v48, v93, 0
	v_max_i32_e32 v93, 0, v1
	v_fmac_f32_e32 v94, v49, v93
	v_max_i32_e32 v93, 0, v2
	v_fmac_f32_e32 v94, v50, v93
	v_max_i32_e32 v93, 0, v3
	v_fmac_f32_e32 v94, v51, v93
	v_max_i32_e32 v93, 0, v4
	v_fmac_f32_e32 v94, v52, v93
	v_mfma_f32_32x32x16_bf16 v[16:31], v[36:39], v[88:91], v[16:31]
	v_max_i32_e32 v93, 0, v5
	v_fmac_f32_e32 v94, v53, v93
	v_max_i32_e32 v93, 0, v6
	v_fmac_f32_e32 v94, v54, v93
	v_max_i32_e32 v93, 0, v7
	v_fmac_f32_e32 v94, v55, v93
	v_max_i32_e32 v93, 0, v8
	v_fmac_f32_e32 v94, v56, v93
	v_max_i32_e32 v93, 0, v9
	v_fmac_f32_e32 v94, v57, v93
	v_mfma_f32_32x32x16_bf16 v[16:31], v[40:43], v[84:87], v[16:31]
	v_max_i32_e32 v93, 0, v10
	v_fmac_f32_e32 v94, v58, v93
	v_max_i32_e32 v93, 0, v11
	v_fmac_f32_e32 v94, v59, v93
	v_max_i32_e32 v93, 0, v12
	v_fmac_f32_e32 v94, v60, v93
	v_max_i32_e32 v93, 0, v13
	v_fmac_f32_e32 v94, v61, v93
	v_mfma_f32_32x32x16_bf16 v[16:31], v[44:47], v[80:83], v[16:31]
	v_max_i32_e32 v93, 0, v14
	v_fmac_f32_e32 v94, v62, v93
	v_max_i32_e32 v93, 0, v15
	v_fmac_f32_e32 v94, v63, v93
	s_cmp_eq_u32 s60, 2
	v_or_b32_e32 v93, 32, v130
	s_cselect_b64 s[0:1], -1, 0
	v_cmp_gt_i32_e32 vcc, v93, v203
	s_and_b64 vcc, s[0:1], vcc
	s_nop 0
	v_cndmask_b32_e32 v201, v94, v197, vcc

.LBB0_1791:
	ds_read_b128 v[16:19], v134 offset:0
	ds_read_b128 v[80:83], v134 offset:32
	ds_read_b128 v[84:87], v134 offset:64
	ds_read_b128 v[92:95], v134 offset:0x60
	v_max_i32_e32 v88, 0, v0
	s_waitcnt lgkmcnt(0)
	v_max_i32_e32 v89, 0, v1
	v_mfma_f32_32x32x16_bf16 v[16:31], v[32:35], v[16:19], 0
	v_fma_f32 v116, v48, v88, 0
	v_max_i32_e32 v90, 0, v2
	v_fmac_f32_e32 v116, v49, v89
	v_max_i32_e32 v91, 0, v3
	v_fmac_f32_e32 v116, v50, v90
	v_max_i32_e32 v96, 0, v4
	v_fmac_f32_e32 v116, v51, v91
	v_mfma_f32_32x32x16_bf16 v[16:31], v[36:39], v[80:83], v[16:31]
	v_max_i32_e32 v97, 0, v5
	v_fmac_f32_e32 v116, v52, v96
	v_max_i32_e32 v98, 0, v6
	v_fmac_f32_e32 v116, v53, v97
	v_max_i32_e32 v99, 0, v7
	v_fmac_f32_e32 v116, v54, v98
	v_max_i32_e32 v100, 0, v8
	v_mfma_f32_32x32x16_bf16 v[16:31], v[40:43], v[84:87], v[16:31]
	v_fmac_f32_e32 v116, v55, v99
	v_max_i32_e32 v101, 0, v9
	v_fmac_f32_e32 v116, v56, v100
	v_max_i32_e32 v102, 0, v10
	v_fmac_f32_e32 v116, v57, v101
	v_max_i32_e32 v103, 0, v11
	v_fmac_f32_e32 v116, v58, v102
	v_fmac_f32_e32 v116, v59, v103
	v_max_i32_e32 v84, 0, v12
	ds_read_b128 v[80:83], v134 offset:0x1200
	v_fmac_f32_e32 v116, v60, v84
	v_max_i32_e32 v84, 0, v13
	ds_read_b128 v[88:91], v134 offset:0x1220
	v_fmac_f32_e32 v116, v61, v84
	v_max_i32_e32 v84, 0, v14
	ds_read_b128 v[96:99], v134 offset:0x1240
	v_fmac_f32_e32 v116, v62, v84
	v_max_i32_e32 v84, 0, v15
	ds_read_b128 v[104:107], v134 offset:0x1260
	v_mfma_f32_32x32x16_bf16 v[16:31], v[44:47], v[92:95], v[16:31]
	v_fmac_f32_e32 v116, v63, v84
	s_waitcnt lgkmcnt(0)
	ds_read_b128 v[108:111], v134 offset:0x2400
	ds_read_b128 v[100:103], v134 offset:0x2420
	ds_read_b128 v[92:95], v134 offset:0x2440
	ds_read_b128 v[84:87], v134 offset:0x2460
	s_cmp_eq_u32 s60, 9
	s_cselect_b64 s[54:55], -1, 0
	s_cmp_lg_u32 s60, 9
	s_cselect_b64 s[0:1], -1, 0
	s_and_b64 vcc, exec, s[54:55]
	s_cbranch_vccnz .Lixc49
	v_mfma_f32_32x32x16_bf16 v[0:15], v[32:35], v[80:83], 0
	v_max_i32_e32 v81, 0, v16
	v_fma_f32 v82, v48, v81, 0
	v_max_i32_e32 v81, 0, v17
	v_fmac_f32_e32 v82, v49, v81
	v_max_i32_e32 v81, 0, v18
	v_fmac_f32_e32 v82, v50, v81
	v_max_i32_e32 v81, 0, v19
	v_fmac_f32_e32 v82, v51, v81
	v_max_i32_e32 v81, 0, v20
	v_fmac_f32_e32 v82, v52, v81
	v_mfma_f32_32x32x16_bf16 v[0:15], v[36:39], v[88:91], v[0:15]
	v_max_i32_e32 v81, 0, v21
	v_fmac_f32_e32 v82, v53, v81
	v_max_i32_e32 v81, 0, v22
	v_fmac_f32_e32 v82, v54, v81
	v_max_i32_e32 v81, 0, v23
	v_fmac_f32_e32 v82, v55, v81
	v_max_i32_e32 v81, 0, v24
	v_fmac_f32_e32 v82, v56, v81
	v_max_i32_e32 v81, 0, v25
	v_fmac_f32_e32 v82, v57, v81
	v_mfma_f32_32x32x16_bf16 v[0:15], v[40:43], v[96:99], v[0:15]
	v_max_i32_e32 v81, 0, v26
	v_fmac_f32_e32 v82, v58, v81
	v_max_i32_e32 v81, 0, v27
	v_fmac_f32_e32 v82, v59, v81
	v_max_i32_e32 v81, 0, v28
	v_fmac_f32_e32 v82, v60, v81
	v_max_i32_e32 v81, 0, v29
	v_fmac_f32_e32 v82, v61, v81
	v_mfma_f32_32x32x16_bf16 v[0:15], v[44:47], v[104:107], v[0:15]
	v_max_i32_e32 v81, 0, v30
	v_fmac_f32_e32 v82, v62, v81
	v_max_i32_e32 v81, 0, v31
	v_cmp_gt_i32_e32 vcc, v135, v203
	v_fmac_f32_e32 v82, v63, v81
	s_and_b64 vcc, s[54:55], vcc
	v_cndmask_b32_e32 v117, v82, v197, vcc
.Lixj49:
	s_waitcnt lgkmcnt(0)
	ds_read_b128 v[96:99], v134 offset:0x3600
	ds_read_b128 v[88:91], v134 offset:0x3620
	ds_read_b128 v[80:83], v134 offset:0x3640
	ds_read_b128 v[104:107], v134 offset:0x3660
	s_cmp_gt_u32 s94, 19
	s_cselect_b64 s[66:67], -1, 0
	s_cmp_lt_u32 s94, 20
	s_cbranch_scc1 .Lixc48
	v_mfma_f32_32x32x16_bf16 v[16:31], v[32:35], v[108:111], 0
	v_cndmask_b32_e64 v109, 0, 1, s[0:1]
	v_cmp_ne_u32_e64 s[54:55], 1, v109
	s_andn2_b64 vcc, exec, s[0:1]
	v_max_i32_e32 v109, 0, v0
	v_fma_f32 v110, v48, v109, 0
	v_max_i32_e32 v109, 0, v1
	v_fmac_f32_e32 v110, v49, v109
	v_max_i32_e32 v109, 0, v2
	v_fmac_f32_e32 v110, v50, v109
	v_max_i32_e32 v109, 0, v3
	v_fmac_f32_e32 v110, v51, v109
	v_max_i32_e32 v109, 0, v4
	v_fmac_f32_e32 v110, v52, v109
	v_mfma_f32_32x32x16_bf16 v[16:31], v[36:39], v[100:103], v[16:31]
	v_max_i32_e32 v109, 0, v5
	v_fmac_f32_e32 v110, v53, v109
	v_max_i32_e32 v109, 0, v6
	v_fmac_f32_e32 v110, v54, v109
	v_max_i32_e32 v109, 0, v7
	v_fmac_f32_e32 v110, v55, v109
	v_max_i32_e32 v109, 0, v8
	v_fmac_f32_e32 v110, v56, v109
	v_max_i32_e32 v109, 0, v9
	v_fmac_f32_e32 v110, v57, v109
	v_mfma_f32_32x32x16_bf16 v[16:31], v[40:43], v[92:95], v[16:31]
	v_max_i32_e32 v109, 0, v10
	v_fmac_f32_e32 v110, v58, v109
	v_max_i32_e32 v109, 0, v11
	v_fmac_f32_e32 v110, v59, v109
	v_max_i32_e32 v109, 0, v12
	v_fmac_f32_e32 v110, v60, v109
	v_max_i32_e32 v109, 0, v13
	v_fmac_f32_e32 v110, v61, v109
	v_mfma_f32_32x32x16_bf16 v[16:31], v[44:47], v[84:87], v[16:31]
	v_max_i32_e32 v109, 0, v14
	s_cmp_eq_u32 s60, 10
	v_fmac_f32_e32 v110, v62, v109
	v_max_i32_e32 v109, 0, v15
	s_cselect_b64 s[0:1], -1, 0
	v_cmp_gt_i32_e32 vcc, v136, v203
	v_fmac_f32_e32 v110, v63, v109
	s_and_b64 vcc, s[0:1], vcc
	v_cndmask_b32_e32 v118, v110, v197, vcc
.Lixj48:
.LBB0_1797:
	s_and_b64 vcc, exec, s[54:55]
	s_cbranch_vccnz .LBB0_1799

.LBB0_1835:
	ds_read_b128 v[16:19], v131 offset:0
	ds_read_b128 v[80:83], v131 offset:32
	ds_read_b128 v[84:87], v131 offset:64
	ds_read_b128 v[92:95], v131 offset:0x60
	v_max_i32_e32 v88, 0, v0
	s_waitcnt lgkmcnt(0)
	v_max_i32_e32 v89, 0, v1
	v_mfma_f32_32x32x16_bf16 v[16:31], v[32:35], v[16:19], 0
	v_fma_f32 v209, v48, v88, 0
	v_max_i32_e32 v90, 0, v2
	v_fmac_f32_e32 v209, v49, v89
	v_max_i32_e32 v91, 0, v3
	v_fmac_f32_e32 v209, v50, v90
	v_max_i32_e32 v96, 0, v4
	v_fmac_f32_e32 v209, v51, v91
	v_mfma_f32_32x32x16_bf16 v[16:31], v[36:39], v[80:83], v[16:31]
	v_max_i32_e32 v97, 0, v5
	v_fmac_f32_e32 v209, v52, v96
	v_max_i32_e32 v98, 0, v6
	v_fmac_f32_e32 v209, v53, v97
	v_max_i32_e32 v99, 0, v7
	v_fmac_f32_e32 v209, v54, v98
	v_max_i32_e32 v100, 0, v8
	v_mfma_f32_32x32x16_bf16 v[16:31], v[40:43], v[84:87], v[16:31]
	v_fmac_f32_e32 v209, v55, v99
	v_max_i32_e32 v101, 0, v9
	v_fmac_f32_e32 v209, v56, v100
	v_max_i32_e32 v102, 0, v10
	v_fmac_f32_e32 v209, v57, v101
	v_max_i32_e32 v103, 0, v11
	v_fmac_f32_e32 v209, v58, v102
	v_fmac_f32_e32 v209, v59, v103
	v_max_i32_e32 v84, 0, v12
	ds_read_b128 v[80:83], v131 offset:0x1200
	v_fmac_f32_e32 v209, v60, v84
	v_max_i32_e32 v84, 0, v13
	ds_read_b128 v[88:91], v131 offset:0x1220
	v_fmac_f32_e32 v209, v61, v84
	v_max_i32_e32 v84, 0, v14
	ds_read_b128 v[96:99], v131 offset:0x1240
	v_fmac_f32_e32 v209, v62, v84
	v_max_i32_e32 v84, 0, v15
	ds_read_b128 v[104:107], v131 offset:0x1260
	v_mfma_f32_32x32x16_bf16 v[16:31], v[44:47], v[92:95], v[16:31]
	v_fmac_f32_e32 v209, v63, v84
	s_waitcnt lgkmcnt(0)
	ds_read_b128 v[108:111], v131 offset:0x2400
	ds_read_b128 v[100:103], v131 offset:0x2420
	ds_read_b128 v[92:95], v131 offset:0x2440
	ds_read_b128 v[84:87], v131 offset:0x2460
	s_cmp_eq_u32 s60, 17
	s_cselect_b64 s[54:55], -1, 0
	s_cmp_lg_u32 s60, 17
	s_cselect_b64 s[0:1], -1, 0
	s_and_b64 vcc, exec, s[54:55]
	s_cbranch_vccnz .Lixc42
	v_mfma_f32_32x32x16_bf16 v[0:15], v[32:35], v[80:83], 0
	v_max_i32_e32 v81, 0, v16
	v_fma_f32 v82, v48, v81, 0
	v_max_i32_e32 v81, 0, v17
	v_fmac_f32_e32 v82, v49, v81
	v_max_i32_e32 v81, 0, v18
	v_fmac_f32_e32 v82, v50, v81
	v_max_i32_e32 v81, 0, v19
	v_fmac_f32_e32 v82, v51, v81
	v_max_i32_e32 v81, 0, v20
	v_fmac_f32_e32 v82, v52, v81
	v_mfma_f32_32x32x16_bf16 v[0:15], v[36:39], v[88:91], v[0:15]
	v_max_i32_e32 v81, 0, v21
	v_fmac_f32_e32 v82, v53, v81
	v_max_i32_e32 v81, 0, v22
	v_fmac_f32_e32 v82, v54, v81
	v_max_i32_e32 v81, 0, v23
	v_fmac_f32_e32 v82, v55, v81
	v_max_i32_e32 v81, 0, v24
	v_fmac_f32_e32 v82, v56, v81
	v_max_i32_e32 v81, 0, v25
	v_fmac_f32_e32 v82, v57, v81
	v_mfma_f32_32x32x16_bf16 v[0:15], v[40:43], v[96:99], v[0:15]
	v_max_i32_e32 v81, 0, v26
	v_fmac_f32_e32 v82, v58, v81
	v_max_i32_e32 v81, 0, v27
	v_fmac_f32_e32 v82, v59, v81
	v_max_i32_e32 v81, 0, v28
	v_fmac_f32_e32 v82, v60, v81
	v_max_i32_e32 v81, 0, v29
	v_fmac_f32_e32 v82, v61, v81
	v_mfma_f32_32x32x16_bf16 v[0:15], v[44:47], v[104:107], v[0:15]
	v_max_i32_e32 v81, 0, v30
	v_fmac_f32_e32 v82, v62, v81
	v_max_i32_e32 v81, 0, v31
	v_cmp_gt_i32_e32 vcc, v143, v203
	v_fmac_f32_e32 v82, v63, v81
	s_and_b64 vcc, s[54:55], vcc
	v_cndmask_b32_e32 v210, v82, v197, vcc
.Lixj42:
	s_waitcnt lgkmcnt(0)
	ds_read_b128 v[96:99], v131 offset:0x3600
	ds_read_b128 v[88:91], v131 offset:0x3620
	ds_read_b128 v[80:83], v131 offset:0x3640
	ds_read_b128 v[104:107], v131 offset:0x3660
	s_cmp_gt_u32 s94, 35
	s_cselect_b64 s[66:67], -1, 0
	s_cmp_lt_u32 s94, 36
	s_cbranch_scc1 .Lixc41
	v_mfma_f32_32x32x16_bf16 v[16:31], v[32:35], v[108:111], 0
	v_cndmask_b32_e64 v109, 0, 1, s[0:1]
	v_cmp_ne_u32_e64 s[54:55], 1, v109
	s_andn2_b64 vcc, exec, s[0:1]
	v_max_i32_e32 v109, 0, v0
	v_fma_f32 v110, v48, v109, 0
	v_max_i32_e32 v109, 0, v1
	v_fmac_f32_e32 v110, v49, v109
	v_max_i32_e32 v109, 0, v2
	v_fmac_f32_e32 v110, v50, v109
	v_max_i32_e32 v109, 0, v3
	v_fmac_f32_e32 v110, v51, v109
	v_max_i32_e32 v109, 0, v4
	v_fmac_f32_e32 v110, v52, v109
	v_mfma_f32_32x32x16_bf16 v[16:31], v[36:39], v[100:103], v[16:31]
	v_max_i32_e32 v109, 0, v5
	v_fmac_f32_e32 v110, v53, v109
	v_max_i32_e32 v109, 0, v6
	v_fmac_f32_e32 v110, v54, v109
	v_max_i32_e32 v109, 0, v7
	v_fmac_f32_e32 v110, v55, v109
	v_max_i32_e32 v109, 0, v8
	v_fmac_f32_e32 v110, v56, v109
	v_max_i32_e32 v109, 0, v9
	v_fmac_f32_e32 v110, v57, v109
	v_mfma_f32_32x32x16_bf16 v[16:31], v[40:43], v[92:95], v[16:31]
	v_max_i32_e32 v109, 0, v10
	v_fmac_f32_e32 v110, v58, v109
	v_max_i32_e32 v109, 0, v11
	v_fmac_f32_e32 v110, v59, v109
	v_max_i32_e32 v109, 0, v12
	v_fmac_f32_e32 v110, v60, v109
	v_max_i32_e32 v109, 0, v13
	v_fmac_f32_e32 v110, v61, v109
	v_mfma_f32_32x32x16_bf16 v[16:31], v[44:47], v[84:87], v[16:31]
	v_max_i32_e32 v109, 0, v14
	s_cmp_eq_u32 s60, 18
	v_fmac_f32_e32 v110, v62, v109
	v_max_i32_e32 v109, 0, v15
	s_cselect_b64 s[0:1], -1, 0
	v_cmp_gt_i32_e32 vcc, v144, v203
	v_fmac_f32_e32 v110, v63, v109
	s_and_b64 vcc, s[0:1], vcc
	v_cndmask_b32_e32 v211, v110, v197, vcc

.LBB0_1879:
	ds_read_b128 v[16:19], v134 offset:0
	ds_read_b128 v[80:83], v134 offset:32
	ds_read_b128 v[84:87], v134 offset:64
	ds_read_b128 v[92:95], v134 offset:0x60
	v_max_i32_e32 v88, 0, v0
	s_waitcnt lgkmcnt(0)
	v_max_i32_e32 v89, 0, v1
	v_mfma_f32_32x32x16_bf16 v[16:31], v[32:35], v[16:19], 0
	v_fma_f32 v218, v48, v88, 0
	v_max_i32_e32 v90, 0, v2
	v_fmac_f32_e32 v218, v49, v89
	v_max_i32_e32 v91, 0, v3
	v_fmac_f32_e32 v218, v50, v90
	v_max_i32_e32 v96, 0, v4
	v_fmac_f32_e32 v218, v51, v91
	v_mfma_f32_32x32x16_bf16 v[16:31], v[36:39], v[80:83], v[16:31]
	v_max_i32_e32 v97, 0, v5
	v_fmac_f32_e32 v218, v52, v96
	v_max_i32_e32 v98, 0, v6
	v_fmac_f32_e32 v218, v53, v97
	v_max_i32_e32 v99, 0, v7
	v_fmac_f32_e32 v218, v54, v98
	v_max_i32_e32 v100, 0, v8
	v_mfma_f32_32x32x16_bf16 v[16:31], v[40:43], v[84:87], v[16:31]
	v_fmac_f32_e32 v218, v55, v99
	v_max_i32_e32 v101, 0, v9
	v_fmac_f32_e32 v218, v56, v100
	v_max_i32_e32 v102, 0, v10
	v_fmac_f32_e32 v218, v57, v101
	v_max_i32_e32 v103, 0, v11
	v_fmac_f32_e32 v218, v58, v102
	v_fmac_f32_e32 v218, v59, v103
	v_max_i32_e32 v84, 0, v12
	ds_read_b128 v[80:83], v134 offset:0x1200
	v_fmac_f32_e32 v218, v60, v84
	v_max_i32_e32 v84, 0, v13
	ds_read_b128 v[88:91], v134 offset:0x1220
	v_fmac_f32_e32 v218, v61, v84
	v_max_i32_e32 v84, 0, v14
	ds_read_b128 v[96:99], v134 offset:0x1240
	v_fmac_f32_e32 v218, v62, v84
	v_max_i32_e32 v84, 0, v15
	ds_read_b128 v[104:107], v134 offset:0x1260
	v_mfma_f32_32x32x16_bf16 v[16:31], v[44:47], v[92:95], v[16:31]
	v_fmac_f32_e32 v218, v63, v84
	s_waitcnt lgkmcnt(0)
	ds_read_b128 v[108:111], v134 offset:0x2400
	ds_read_b128 v[100:103], v134 offset:0x2420
	ds_read_b128 v[92:95], v134 offset:0x2440
	ds_read_b128 v[84:87], v134 offset:0x2460
	s_cmp_eq_u32 s60, 25
	s_cselect_b64 s[54:55], -1, 0
	s_cmp_lg_u32 s60, 25
	s_cselect_b64 s[0:1], -1, 0
	s_and_b64 vcc, exec, s[54:55]
	s_cbranch_vccnz .Lixc35
	v_mfma_f32_32x32x16_bf16 v[0:15], v[32:35], v[80:83], 0
	v_max_i32_e32 v81, 0, v16
	v_fma_f32 v82, v48, v81, 0
	v_max_i32_e32 v81, 0, v17
	v_fmac_f32_e32 v82, v49, v81
	v_max_i32_e32 v81, 0, v18
	v_fmac_f32_e32 v82, v50, v81
	v_max_i32_e32 v81, 0, v19
	v_fmac_f32_e32 v82, v51, v81
	v_max_i32_e32 v81, 0, v20
	v_fmac_f32_e32 v82, v52, v81
	v_mfma_f32_32x32x16_bf16 v[0:15], v[36:39], v[88:91], v[0:15]
	v_max_i32_e32 v81, 0, v21
	v_fmac_f32_e32 v82, v53, v81
	v_max_i32_e32 v81, 0, v22
	v_fmac_f32_e32 v82, v54, v81
	v_max_i32_e32 v81, 0, v23
	v_fmac_f32_e32 v82, v55, v81
	v_max_i32_e32 v81, 0, v24
	v_fmac_f32_e32 v82, v56, v81
	v_max_i32_e32 v81, 0, v25
	v_fmac_f32_e32 v82, v57, v81
	v_mfma_f32_32x32x16_bf16 v[0:15], v[40:43], v[96:99], v[0:15]
	v_max_i32_e32 v81, 0, v26
	v_fmac_f32_e32 v82, v58, v81
	v_max_i32_e32 v81, 0, v27
	v_fmac_f32_e32 v82, v59, v81
	v_max_i32_e32 v81, 0, v28
	v_fmac_f32_e32 v82, v60, v81
	v_max_i32_e32 v81, 0, v29
	v_fmac_f32_e32 v82, v61, v81
	v_mfma_f32_32x32x16_bf16 v[0:15], v[44:47], v[104:107], v[0:15]
	v_max_i32_e32 v81, 0, v30
	v_fmac_f32_e32 v82, v62, v81
	v_max_i32_e32 v81, 0, v31
	v_cmp_gt_i32_e32 vcc, v151, v203
	v_fmac_f32_e32 v82, v63, v81
	s_and_b64 vcc, s[54:55], vcc
	v_cndmask_b32_e32 v219, v82, v197, vcc
.Lixj35:
	s_waitcnt lgkmcnt(0)
	ds_read_b128 v[96:99], v134 offset:0x3600
	ds_read_b128 v[88:91], v134 offset:0x3620
	ds_read_b128 v[80:83], v134 offset:0x3640
	ds_read_b128 v[104:107], v134 offset:0x3660
	s_cmp_gt_u32 s94, 51
	s_cselect_b64 s[66:67], -1, 0
	s_cmp_lt_u32 s94, 52
	s_cbranch_scc1 .Lixc34
	v_mfma_f32_32x32x16_bf16 v[16:31], v[32:35], v[108:111], 0
	v_cndmask_b32_e64 v109, 0, 1, s[0:1]
	v_cmp_ne_u32_e64 s[54:55], 1, v109
	s_andn2_b64 vcc, exec, s[0:1]
	v_max_i32_e32 v109, 0, v0
	v_fma_f32 v110, v48, v109, 0
	v_max_i32_e32 v109, 0, v1
	v_fmac_f32_e32 v110, v49, v109
	v_max_i32_e32 v109, 0, v2
	v_fmac_f32_e32 v110, v50, v109
	v_max_i32_e32 v109, 0, v3
	v_fmac_f32_e32 v110, v51, v109
	v_max_i32_e32 v109, 0, v4
	v_fmac_f32_e32 v110, v52, v109
	v_mfma_f32_32x32x16_bf16 v[16:31], v[36:39], v[100:103], v[16:31]
	v_max_i32_e32 v109, 0, v5
	v_fmac_f32_e32 v110, v53, v109
	v_max_i32_e32 v109, 0, v6
	v_fmac_f32_e32 v110, v54, v109
	v_max_i32_e32 v109, 0, v7
	v_fmac_f32_e32 v110, v55, v109
	v_max_i32_e32 v109, 0, v8
	v_fmac_f32_e32 v110, v56, v109
	v_max_i32_e32 v109, 0, v9
	v_fmac_f32_e32 v110, v57, v109
	v_mfma_f32_32x32x16_bf16 v[16:31], v[40:43], v[92:95], v[16:31]
	v_max_i32_e32 v109, 0, v10
	v_fmac_f32_e32 v110, v58, v109
	v_max_i32_e32 v109, 0, v11
	v_fmac_f32_e32 v110, v59, v109
	v_max_i32_e32 v109, 0, v12
	v_fmac_f32_e32 v110, v60, v109
	v_max_i32_e32 v109, 0, v13
	v_fmac_f32_e32 v110, v61, v109
	v_mfma_f32_32x32x16_bf16 v[16:31], v[44:47], v[84:87], v[16:31]
	v_max_i32_e32 v109, 0, v14
	s_cmp_eq_u32 s60, 26
	v_fmac_f32_e32 v110, v62, v109
	v_max_i32_e32 v109, 0, v15
	s_cselect_b64 s[0:1], -1, 0
	v_cmp_gt_i32_e32 vcc, v152, v203
	v_fmac_f32_e32 v110, v63, v109
	s_and_b64 vcc, s[0:1], vcc
	v_cndmask_b32_e32 v220, v110, v197, vcc

.LBB0_1923:
	ds_read_b128 v[16:19], v131 offset:0
	ds_read_b128 v[80:83], v131 offset:32
	ds_read_b128 v[84:87], v131 offset:64
	ds_read_b128 v[92:95], v131 offset:0x60
	v_max_i32_e32 v88, 0, v0
	s_waitcnt lgkmcnt(0)
	v_max_i32_e32 v89, 0, v1
	v_mfma_f32_32x32x16_bf16 v[16:31], v[32:35], v[16:19], 0
	v_fma_f32 v226, v48, v88, 0
	v_max_i32_e32 v90, 0, v2
	v_fmac_f32_e32 v226, v49, v89
	v_max_i32_e32 v91, 0, v3
	v_fmac_f32_e32 v226, v50, v90
	v_max_i32_e32 v96, 0, v4
	v_fmac_f32_e32 v226, v51, v91
	v_mfma_f32_32x32x16_bf16 v[16:31], v[36:39], v[80:83], v[16:31]
	v_max_i32_e32 v97, 0, v5
	v_fmac_f32_e32 v226, v52, v96
	v_max_i32_e32 v98, 0, v6
	v_fmac_f32_e32 v226, v53, v97
	v_max_i32_e32 v99, 0, v7
	v_fmac_f32_e32 v226, v54, v98
	v_max_i32_e32 v100, 0, v8
	v_mfma_f32_32x32x16_bf16 v[16:31], v[40:43], v[84:87], v[16:31]
	v_fmac_f32_e32 v226, v55, v99
	v_max_i32_e32 v101, 0, v9
	v_fmac_f32_e32 v226, v56, v100
	v_max_i32_e32 v102, 0, v10
	v_fmac_f32_e32 v226, v57, v101
	v_max_i32_e32 v103, 0, v11
	v_fmac_f32_e32 v226, v58, v102
	v_fmac_f32_e32 v226, v59, v103
	v_max_i32_e32 v84, 0, v12
	ds_read_b128 v[80:83], v131 offset:0x1200
	v_fmac_f32_e32 v226, v60, v84
	v_max_i32_e32 v84, 0, v13
	ds_read_b128 v[88:91], v131 offset:0x1220
	v_fmac_f32_e32 v226, v61, v84
	v_max_i32_e32 v84, 0, v14
	ds_read_b128 v[96:99], v131 offset:0x1240
	v_fmac_f32_e32 v226, v62, v84
	v_max_i32_e32 v84, 0, v15
	ds_read_b128 v[104:107], v131 offset:0x1260
	v_mfma_f32_32x32x16_bf16 v[16:31], v[44:47], v[92:95], v[16:31]
	v_fmac_f32_e32 v226, v63, v84
	s_waitcnt lgkmcnt(0)
	ds_read_b128 v[108:111], v131 offset:0x2400
	ds_read_b128 v[100:103], v131 offset:0x2420
	ds_read_b128 v[92:95], v131 offset:0x2440
	ds_read_b128 v[84:87], v131 offset:0x2460
	s_cmp_eq_u32 s60, 33
	s_cselect_b64 s[54:55], -1, 0
	s_cmp_lg_u32 s60, 33
	s_cselect_b64 s[0:1], -1, 0
	s_and_b64 vcc, exec, s[54:55]
	s_cbranch_vccnz .Lixc28
	v_mfma_f32_32x32x16_bf16 v[0:15], v[32:35], v[80:83], 0
	v_max_i32_e32 v81, 0, v16
	v_fma_f32 v82, v48, v81, 0
	v_max_i32_e32 v81, 0, v17
	v_fmac_f32_e32 v82, v49, v81
	v_max_i32_e32 v81, 0, v18
	v_fmac_f32_e32 v82, v50, v81
	v_max_i32_e32 v81, 0, v19
	v_fmac_f32_e32 v82, v51, v81
	v_max_i32_e32 v81, 0, v20
	v_fmac_f32_e32 v82, v52, v81
	v_mfma_f32_32x32x16_bf16 v[0:15], v[36:39], v[88:91], v[0:15]
	v_max_i32_e32 v81, 0, v21
	v_fmac_f32_e32 v82, v53, v81
	v_max_i32_e32 v81, 0, v22
	v_fmac_f32_e32 v82, v54, v81
	v_max_i32_e32 v81, 0, v23
	v_fmac_f32_e32 v82, v55, v81
	v_max_i32_e32 v81, 0, v24
	v_fmac_f32_e32 v82, v56, v81
	v_max_i32_e32 v81, 0, v25
	v_fmac_f32_e32 v82, v57, v81
	v_mfma_f32_32x32x16_bf16 v[0:15], v[40:43], v[96:99], v[0:15]
	v_max_i32_e32 v81, 0, v26
	v_fmac_f32_e32 v82, v58, v81
	v_max_i32_e32 v81, 0, v27
	v_fmac_f32_e32 v82, v59, v81
	v_max_i32_e32 v81, 0, v28
	v_fmac_f32_e32 v82, v60, v81
	v_max_i32_e32 v81, 0, v29
	v_fmac_f32_e32 v82, v61, v81
	v_mfma_f32_32x32x16_bf16 v[0:15], v[44:47], v[104:107], v[0:15]
	v_max_i32_e32 v81, 0, v30
	v_fmac_f32_e32 v82, v62, v81
	v_max_i32_e32 v81, 0, v31
	v_cmp_gt_i32_e32 vcc, v159, v203
	v_fmac_f32_e32 v82, v63, v81
	s_and_b64 vcc, s[54:55], vcc
	v_cndmask_b32_e32 v227, v82, v197, vcc
.Lixj28:
	s_waitcnt lgkmcnt(0)
	ds_read_b128 v[96:99], v131 offset:0x3600
	ds_read_b128 v[88:91], v131 offset:0x3620
	ds_read_b128 v[80:83], v131 offset:0x3640
	ds_read_b128 v[104:107], v131 offset:0x3660
	s_cmpk_gt_u32 s94, 0x43
	s_cselect_b64 s[66:67], -1, 0
	s_cmpk_lt_u32 s94, 0x44
	s_cbranch_scc1 .Lixc27
	v_mfma_f32_32x32x16_bf16 v[16:31], v[32:35], v[108:111], 0
	v_cndmask_b32_e64 v109, 0, 1, s[0:1]
	v_cmp_ne_u32_e64 s[54:55], 1, v109
	s_andn2_b64 vcc, exec, s[0:1]
	v_max_i32_e32 v109, 0, v0
	v_fma_f32 v110, v48, v109, 0
	v_max_i32_e32 v109, 0, v1
	v_fmac_f32_e32 v110, v49, v109
	v_max_i32_e32 v109, 0, v2
	v_fmac_f32_e32 v110, v50, v109
	v_max_i32_e32 v109, 0, v3
	v_fmac_f32_e32 v110, v51, v109
	v_max_i32_e32 v109, 0, v4
	v_fmac_f32_e32 v110, v52, v109
	v_mfma_f32_32x32x16_bf16 v[16:31], v[36:39], v[100:103], v[16:31]
	v_max_i32_e32 v109, 0, v5
	v_fmac_f32_e32 v110, v53, v109
	v_max_i32_e32 v109, 0, v6
	v_fmac_f32_e32 v110, v54, v109
	v_max_i32_e32 v109, 0, v7
	v_fmac_f32_e32 v110, v55, v109
	v_max_i32_e32 v109, 0, v8
	v_fmac_f32_e32 v110, v56, v109
	v_max_i32_e32 v109, 0, v9
	v_fmac_f32_e32 v110, v57, v109
	v_mfma_f32_32x32x16_bf16 v[16:31], v[40:43], v[92:95], v[16:31]
	v_max_i32_e32 v109, 0, v10
	v_fmac_f32_e32 v110, v58, v109
	v_max_i32_e32 v109, 0, v11
	v_fmac_f32_e32 v110, v59, v109
	v_max_i32_e32 v109, 0, v12
	v_fmac_f32_e32 v110, v60, v109
	v_max_i32_e32 v109, 0, v13
	v_fmac_f32_e32 v110, v61, v109
	v_mfma_f32_32x32x16_bf16 v[16:31], v[44:47], v[84:87], v[16:31]
	v_max_i32_e32 v109, 0, v14
	s_cmp_eq_u32 s60, 34
	v_fmac_f32_e32 v110, v62, v109
	v_max_i32_e32 v109, 0, v15
	s_cselect_b64 s[0:1], -1, 0
	v_cmp_gt_i32_e32 vcc, v160, v203
	v_fmac_f32_e32 v110, v63, v109
	s_and_b64 vcc, s[0:1], vcc
	v_cndmask_b32_e32 v228, v110, v197, vcc

.LBB0_1967:
	ds_read_b128 v[16:19], v134 offset:0
	ds_read_b128 v[80:83], v134 offset:32
	ds_read_b128 v[84:87], v134 offset:64
	ds_read_b128 v[92:95], v134 offset:0x60
	v_max_i32_e32 v88, 0, v0
	s_waitcnt lgkmcnt(0)
	v_max_i32_e32 v89, 0, v1
	v_mfma_f32_32x32x16_bf16 v[16:31], v[32:35], v[16:19], 0
	v_fma_f32 v234, v48, v88, 0
	v_max_i32_e32 v90, 0, v2
	v_fmac_f32_e32 v234, v49, v89
	v_max_i32_e32 v91, 0, v3
	v_fmac_f32_e32 v234, v50, v90
	v_max_i32_e32 v96, 0, v4
	v_fmac_f32_e32 v234, v51, v91
	v_mfma_f32_32x32x16_bf16 v[16:31], v[36:39], v[80:83], v[16:31]
	v_max_i32_e32 v97, 0, v5
	v_fmac_f32_e32 v234, v52, v96
	v_max_i32_e32 v98, 0, v6
	v_fmac_f32_e32 v234, v53, v97
	v_max_i32_e32 v99, 0, v7
	v_fmac_f32_e32 v234, v54, v98
	v_max_i32_e32 v100, 0, v8
	v_mfma_f32_32x32x16_bf16 v[16:31], v[40:43], v[84:87], v[16:31]
	v_fmac_f32_e32 v234, v55, v99
	v_max_i32_e32 v101, 0, v9
	v_fmac_f32_e32 v234, v56, v100
	v_max_i32_e32 v102, 0, v10
	v_fmac_f32_e32 v234, v57, v101
	v_max_i32_e32 v103, 0, v11
	v_fmac_f32_e32 v234, v58, v102
	v_fmac_f32_e32 v234, v59, v103
	v_max_i32_e32 v84, 0, v12
	ds_read_b128 v[80:83], v134 offset:0x1200
	v_fmac_f32_e32 v234, v60, v84
	v_max_i32_e32 v84, 0, v13
	ds_read_b128 v[88:91], v134 offset:0x1220
	v_fmac_f32_e32 v234, v61, v84
	v_max_i32_e32 v84, 0, v14
	ds_read_b128 v[96:99], v134 offset:0x1240
	v_fmac_f32_e32 v234, v62, v84
	v_max_i32_e32 v84, 0, v15
	ds_read_b128 v[104:107], v134 offset:0x1260
	v_mfma_f32_32x32x16_bf16 v[16:31], v[44:47], v[92:95], v[16:31]
	v_fmac_f32_e32 v234, v63, v84
	s_waitcnt lgkmcnt(0)
	ds_read_b128 v[108:111], v134 offset:0x2400
	ds_read_b128 v[100:103], v134 offset:0x2420
	ds_read_b128 v[92:95], v134 offset:0x2440
	ds_read_b128 v[84:87], v134 offset:0x2460
	s_cmp_eq_u32 s60, 41
	s_cselect_b64 s[54:55], -1, 0
	s_cmp_lg_u32 s60, 41
	s_cselect_b64 s[0:1], -1, 0
	s_and_b64 vcc, exec, s[54:55]
	s_cbranch_vccnz .Lixc21
	v_mfma_f32_32x32x16_bf16 v[0:15], v[32:35], v[80:83], 0
	v_max_i32_e32 v81, 0, v16
	v_fma_f32 v82, v48, v81, 0
	v_max_i32_e32 v81, 0, v17
	v_fmac_f32_e32 v82, v49, v81
	v_max_i32_e32 v81, 0, v18
	v_fmac_f32_e32 v82, v50, v81
	v_max_i32_e32 v81, 0, v19
	v_fmac_f32_e32 v82, v51, v81
	v_max_i32_e32 v81, 0, v20
	v_fmac_f32_e32 v82, v52, v81
	v_mfma_f32_32x32x16_bf16 v[0:15], v[36:39], v[88:91], v[0:15]
	v_max_i32_e32 v81, 0, v21
	v_fmac_f32_e32 v82, v53, v81
	v_max_i32_e32 v81, 0, v22
	v_fmac_f32_e32 v82, v54, v81
	v_max_i32_e32 v81, 0, v23
	v_fmac_f32_e32 v82, v55, v81
	v_max_i32_e32 v81, 0, v24
	v_fmac_f32_e32 v82, v56, v81
	v_max_i32_e32 v81, 0, v25
	v_fmac_f32_e32 v82, v57, v81
	v_mfma_f32_32x32x16_bf16 v[0:15], v[40:43], v[96:99], v[0:15]
	v_max_i32_e32 v81, 0, v26
	v_fmac_f32_e32 v82, v58, v81
	v_max_i32_e32 v81, 0, v27
	v_fmac_f32_e32 v82, v59, v81
	v_max_i32_e32 v81, 0, v28
	v_fmac_f32_e32 v82, v60, v81
	v_max_i32_e32 v81, 0, v29
	v_fmac_f32_e32 v82, v61, v81
	v_mfma_f32_32x32x16_bf16 v[0:15], v[44:47], v[104:107], v[0:15]
	v_max_i32_e32 v81, 0, v30
	v_fmac_f32_e32 v82, v62, v81
	v_max_i32_e32 v81, 0, v31
	v_cmp_gt_i32_e32 vcc, v167, v203
	v_fmac_f32_e32 v82, v63, v81
	s_and_b64 vcc, s[54:55], vcc
	v_cndmask_b32_e32 v235, v82, v197, vcc
.Lixj21:
	s_waitcnt lgkmcnt(0)
	ds_read_b128 v[96:99], v134 offset:0x3600
	ds_read_b128 v[88:91], v134 offset:0x3620
	ds_read_b128 v[80:83], v134 offset:0x3640
	ds_read_b128 v[104:107], v134 offset:0x3660
	s_cmpk_gt_u32 s94, 0x53
	s_cselect_b64 s[66:67], -1, 0
	s_cmpk_lt_u32 s94, 0x54
	s_cbranch_scc1 .Lixc20
	v_mfma_f32_32x32x16_bf16 v[16:31], v[32:35], v[108:111], 0
	v_cndmask_b32_e64 v109, 0, 1, s[0:1]
	v_cmp_ne_u32_e64 s[54:55], 1, v109
	s_andn2_b64 vcc, exec, s[0:1]
	v_max_i32_e32 v109, 0, v0
	v_fma_f32 v110, v48, v109, 0
	v_max_i32_e32 v109, 0, v1
	v_fmac_f32_e32 v110, v49, v109
	v_max_i32_e32 v109, 0, v2
	v_fmac_f32_e32 v110, v50, v109
	v_max_i32_e32 v109, 0, v3
	v_fmac_f32_e32 v110, v51, v109
	v_max_i32_e32 v109, 0, v4
	v_fmac_f32_e32 v110, v52, v109
	v_mfma_f32_32x32x16_bf16 v[16:31], v[36:39], v[100:103], v[16:31]
	v_max_i32_e32 v109, 0, v5
	v_fmac_f32_e32 v110, v53, v109
	v_max_i32_e32 v109, 0, v6
	v_fmac_f32_e32 v110, v54, v109
	v_max_i32_e32 v109, 0, v7
	v_fmac_f32_e32 v110, v55, v109
	v_max_i32_e32 v109, 0, v8
	v_fmac_f32_e32 v110, v56, v109
	v_max_i32_e32 v109, 0, v9
	v_fmac_f32_e32 v110, v57, v109
	v_mfma_f32_32x32x16_bf16 v[16:31], v[40:43], v[92:95], v[16:31]
	v_max_i32_e32 v109, 0, v10
	v_fmac_f32_e32 v110, v58, v109
	v_max_i32_e32 v109, 0, v11
	v_fmac_f32_e32 v110, v59, v109
	v_max_i32_e32 v109, 0, v12
	v_fmac_f32_e32 v110, v60, v109
	v_max_i32_e32 v109, 0, v13
	v_fmac_f32_e32 v110, v61, v109
	v_mfma_f32_32x32x16_bf16 v[16:31], v[44:47], v[84:87], v[16:31]
	v_max_i32_e32 v109, 0, v14
	s_cmp_eq_u32 s60, 42
	v_fmac_f32_e32 v110, v62, v109
	v_max_i32_e32 v109, 0, v15
	s_cselect_b64 s[0:1], -1, 0
	v_cmp_gt_i32_e32 vcc, v168, v203
	v_fmac_f32_e32 v110, v63, v109
	s_and_b64 vcc, s[0:1], vcc
	v_cndmask_b32_e32 v236, v110, v197, vcc

.LBB0_2011:
	ds_read_b128 v[16:19], v131 offset:0
	ds_read_b128 v[80:83], v131 offset:32
	ds_read_b128 v[84:87], v131 offset:64
	ds_read_b128 v[92:95], v131 offset:0x60
	v_max_i32_e32 v88, 0, v0
	s_waitcnt lgkmcnt(0)
	v_max_i32_e32 v89, 0, v1
	v_mfma_f32_32x32x16_bf16 v[16:31], v[32:35], v[16:19], 0
	v_fma_f32 v242, v48, v88, 0
	v_max_i32_e32 v90, 0, v2
	v_fmac_f32_e32 v242, v49, v89
	v_max_i32_e32 v91, 0, v3
	v_fmac_f32_e32 v242, v50, v90
	v_max_i32_e32 v96, 0, v4
	v_fmac_f32_e32 v242, v51, v91
	v_mfma_f32_32x32x16_bf16 v[16:31], v[36:39], v[80:83], v[16:31]
	v_max_i32_e32 v97, 0, v5
	v_fmac_f32_e32 v242, v52, v96
	v_max_i32_e32 v98, 0, v6
	v_fmac_f32_e32 v242, v53, v97
	v_max_i32_e32 v99, 0, v7
	v_fmac_f32_e32 v242, v54, v98
	v_max_i32_e32 v100, 0, v8
	v_mfma_f32_32x32x16_bf16 v[16:31], v[40:43], v[84:87], v[16:31]
	v_fmac_f32_e32 v242, v55, v99
	v_max_i32_e32 v101, 0, v9
	v_fmac_f32_e32 v242, v56, v100
	v_max_i32_e32 v102, 0, v10
	v_fmac_f32_e32 v242, v57, v101
	v_max_i32_e32 v103, 0, v11
	v_fmac_f32_e32 v242, v58, v102
	v_fmac_f32_e32 v242, v59, v103
	v_max_i32_e32 v84, 0, v12
	ds_read_b128 v[80:83], v131 offset:0x1200
	v_fmac_f32_e32 v242, v60, v84
	v_max_i32_e32 v84, 0, v13
	ds_read_b128 v[88:91], v131 offset:0x1220
	v_fmac_f32_e32 v242, v61, v84
	v_max_i32_e32 v84, 0, v14
	ds_read_b128 v[96:99], v131 offset:0x1240
	v_fmac_f32_e32 v242, v62, v84
	v_max_i32_e32 v84, 0, v15
	ds_read_b128 v[104:107], v131 offset:0x1260
	v_mfma_f32_32x32x16_bf16 v[16:31], v[44:47], v[92:95], v[16:31]
	v_fmac_f32_e32 v242, v63, v84
	s_waitcnt lgkmcnt(0)
	ds_read_b128 v[108:111], v131 offset:0x2400
	ds_read_b128 v[100:103], v131 offset:0x2420
	ds_read_b128 v[92:95], v131 offset:0x2440
	ds_read_b128 v[84:87], v131 offset:0x2460
	s_cmp_eq_u32 s60, 49
	s_cselect_b64 s[54:55], -1, 0
	s_cmp_lg_u32 s60, 49
	s_cselect_b64 s[0:1], -1, 0
	s_and_b64 vcc, exec, s[54:55]
	s_cbranch_vccnz .Lixc14
	v_mfma_f32_32x32x16_bf16 v[0:15], v[32:35], v[80:83], 0
	v_max_i32_e32 v81, 0, v16
	v_fma_f32 v82, v48, v81, 0
	v_max_i32_e32 v81, 0, v17
	v_fmac_f32_e32 v82, v49, v81
	v_max_i32_e32 v81, 0, v18
	v_fmac_f32_e32 v82, v50, v81
	v_max_i32_e32 v81, 0, v19
	v_fmac_f32_e32 v82, v51, v81
	v_max_i32_e32 v81, 0, v20
	v_fmac_f32_e32 v82, v52, v81
	v_mfma_f32_32x32x16_bf16 v[0:15], v[36:39], v[88:91], v[0:15]
	v_max_i32_e32 v81, 0, v21
	v_fmac_f32_e32 v82, v53, v81
	v_max_i32_e32 v81, 0, v22
	v_fmac_f32_e32 v82, v54, v81
	v_max_i32_e32 v81, 0, v23
	v_fmac_f32_e32 v82, v55, v81
	v_max_i32_e32 v81, 0, v24
	v_fmac_f32_e32 v82, v56, v81
	v_max_i32_e32 v81, 0, v25
	v_fmac_f32_e32 v82, v57, v81
	v_mfma_f32_32x32x16_bf16 v[0:15], v[40:43], v[96:99], v[0:15]
	v_max_i32_e32 v81, 0, v26
	v_fmac_f32_e32 v82, v58, v81
	v_max_i32_e32 v81, 0, v27
	v_fmac_f32_e32 v82, v59, v81
	v_max_i32_e32 v81, 0, v28
	v_fmac_f32_e32 v82, v60, v81
	v_max_i32_e32 v81, 0, v29
	v_fmac_f32_e32 v82, v61, v81
	v_mfma_f32_32x32x16_bf16 v[0:15], v[44:47], v[104:107], v[0:15]
	v_max_i32_e32 v81, 0, v30
	v_fmac_f32_e32 v82, v62, v81
	v_max_i32_e32 v81, 0, v31
	v_cmp_gt_i32_e32 vcc, v175, v203
	v_fmac_f32_e32 v82, v63, v81
	s_and_b64 vcc, s[54:55], vcc
	v_cndmask_b32_e32 v243, v82, v197, vcc
.Lixj14:
	s_waitcnt lgkmcnt(0)
	ds_read_b128 v[96:99], v131 offset:0x3600
	ds_read_b128 v[88:91], v131 offset:0x3620
	ds_read_b128 v[80:83], v131 offset:0x3640
	ds_read_b128 v[104:107], v131 offset:0x3660
	s_cmpk_gt_u32 s94, 0x63
	s_cselect_b64 s[62:63], -1, 0
	s_cmpk_lt_u32 s94, 0x64
	s_cbranch_scc1 .Lixc13
	v_mfma_f32_32x32x16_bf16 v[16:31], v[32:35], v[108:111], 0
	v_cndmask_b32_e64 v109, 0, 1, s[0:1]
	v_cmp_ne_u32_e64 s[54:55], 1, v109
	s_andn2_b64 vcc, exec, s[0:1]
	v_max_i32_e32 v109, 0, v0
	v_fma_f32 v110, v48, v109, 0
	v_max_i32_e32 v109, 0, v1
	v_fmac_f32_e32 v110, v49, v109
	v_max_i32_e32 v109, 0, v2
	v_fmac_f32_e32 v110, v50, v109
	v_max_i32_e32 v109, 0, v3
	v_fmac_f32_e32 v110, v51, v109
	v_max_i32_e32 v109, 0, v4
	v_fmac_f32_e32 v110, v52, v109
	v_mfma_f32_32x32x16_bf16 v[16:31], v[36:39], v[100:103], v[16:31]
	v_max_i32_e32 v109, 0, v5
	v_fmac_f32_e32 v110, v53, v109
	v_max_i32_e32 v109, 0, v6
	v_fmac_f32_e32 v110, v54, v109
	v_max_i32_e32 v109, 0, v7
	v_fmac_f32_e32 v110, v55, v109
	v_max_i32_e32 v109, 0, v8
	v_fmac_f32_e32 v110, v56, v109
	v_max_i32_e32 v109, 0, v9
	v_fmac_f32_e32 v110, v57, v109
	v_mfma_f32_32x32x16_bf16 v[16:31], v[40:43], v[92:95], v[16:31]
	v_max_i32_e32 v109, 0, v10
	v_fmac_f32_e32 v110, v58, v109
	v_max_i32_e32 v109, 0, v11
	v_fmac_f32_e32 v110, v59, v109
	v_max_i32_e32 v109, 0, v12
	v_fmac_f32_e32 v110, v60, v109
	v_max_i32_e32 v109, 0, v13
	v_fmac_f32_e32 v110, v61, v109
	v_mfma_f32_32x32x16_bf16 v[16:31], v[44:47], v[84:87], v[16:31]
	v_max_i32_e32 v109, 0, v14
	s_cmp_eq_u32 s60, 50
	v_fmac_f32_e32 v110, v62, v109
	v_max_i32_e32 v109, 0, v15
	s_cselect_b64 s[0:1], -1, 0
	v_cmp_gt_i32_e32 vcc, v176, v203
	v_fmac_f32_e32 v110, v63, v109
	s_and_b64 vcc, s[0:1], vcc
	v_cndmask_b32_e32 v244, v110, v197, vcc

.LBB0_2053:
	ds_read_b128 v[16:19], v134 offset:0
	ds_read_b128 v[80:83], v134 offset:32
	ds_read_b128 v[84:87], v134 offset:64
	ds_read_b128 v[92:95], v134 offset:0x60
	v_max_i32_e32 v88, 0, v0
	s_waitcnt lgkmcnt(0)
	v_max_i32_e32 v89, 0, v1
	v_mfma_f32_32x32x16_bf16 v[16:31], v[32:35], v[16:19], 0
	v_fma_f32 v250, v48, v88, 0
	v_max_i32_e32 v90, 0, v2
	v_fmac_f32_e32 v250, v49, v89
	v_max_i32_e32 v91, 0, v3
	v_fmac_f32_e32 v250, v50, v90
	v_max_i32_e32 v96, 0, v4
	v_fmac_f32_e32 v250, v51, v91
	v_mfma_f32_32x32x16_bf16 v[16:31], v[36:39], v[80:83], v[16:31]
	v_max_i32_e32 v97, 0, v5
	v_fmac_f32_e32 v250, v52, v96
	v_max_i32_e32 v98, 0, v6
	v_fmac_f32_e32 v250, v53, v97
	v_max_i32_e32 v99, 0, v7
	v_fmac_f32_e32 v250, v54, v98
	v_max_i32_e32 v100, 0, v8
	v_mfma_f32_32x32x16_bf16 v[16:31], v[40:43], v[84:87], v[16:31]
	v_fmac_f32_e32 v250, v55, v99
	v_max_i32_e32 v101, 0, v9
	v_fmac_f32_e32 v250, v56, v100
	v_max_i32_e32 v102, 0, v10
	v_fmac_f32_e32 v250, v57, v101
	v_max_i32_e32 v103, 0, v11
	v_fmac_f32_e32 v250, v58, v102
	v_fmac_f32_e32 v250, v59, v103
	v_max_i32_e32 v84, 0, v12
	ds_read_b128 v[80:83], v134 offset:0x1200
	v_fmac_f32_e32 v250, v60, v84
	v_max_i32_e32 v84, 0, v13
	ds_read_b128 v[88:91], v134 offset:0x1220
	v_fmac_f32_e32 v250, v61, v84
	v_max_i32_e32 v84, 0, v14
	ds_read_b128 v[96:99], v134 offset:0x1240
	v_fmac_f32_e32 v250, v62, v84
	v_max_i32_e32 v84, 0, v15
	ds_read_b128 v[104:107], v134 offset:0x1260
	v_mfma_f32_32x32x16_bf16 v[16:31], v[44:47], v[92:95], v[16:31]
	v_fmac_f32_e32 v250, v63, v84
	s_waitcnt lgkmcnt(0)
	ds_read_b128 v[108:111], v134 offset:0x2400
	ds_read_b128 v[100:103], v134 offset:0x2420
	ds_read_b128 v[92:95], v134 offset:0x2440
	ds_read_b128 v[84:87], v134 offset:0x2460
	s_cmp_eq_u32 s60, 57
	s_cselect_b64 s[54:55], -1, 0
	s_cmp_lg_u32 s60, 57
	s_cselect_b64 s[0:1], -1, 0
	s_and_b64 vcc, exec, s[54:55]
	s_cbranch_vccnz .Lixc7
	v_mfma_f32_32x32x16_bf16 v[0:15], v[32:35], v[80:83], 0
	v_max_i32_e32 v81, 0, v16
	v_fma_f32 v82, v48, v81, 0
	v_max_i32_e32 v81, 0, v17
	v_fmac_f32_e32 v82, v49, v81
	v_max_i32_e32 v81, 0, v18
	v_fmac_f32_e32 v82, v50, v81
	v_max_i32_e32 v81, 0, v19
	v_fmac_f32_e32 v82, v51, v81
	v_max_i32_e32 v81, 0, v20
	v_fmac_f32_e32 v82, v52, v81
	v_mfma_f32_32x32x16_bf16 v[0:15], v[36:39], v[88:91], v[0:15]
	v_max_i32_e32 v81, 0, v21
	v_fmac_f32_e32 v82, v53, v81
	v_max_i32_e32 v81, 0, v22
	v_fmac_f32_e32 v82, v54, v81
	v_max_i32_e32 v81, 0, v23
	v_fmac_f32_e32 v82, v55, v81
	v_max_i32_e32 v81, 0, v24
	v_fmac_f32_e32 v82, v56, v81
	v_max_i32_e32 v81, 0, v25
	v_fmac_f32_e32 v82, v57, v81
	v_mfma_f32_32x32x16_bf16 v[0:15], v[40:43], v[96:99], v[0:15]
	v_max_i32_e32 v81, 0, v26
	v_fmac_f32_e32 v82, v58, v81
	v_max_i32_e32 v81, 0, v27
	v_fmac_f32_e32 v82, v59, v81
	v_max_i32_e32 v81, 0, v28
	v_fmac_f32_e32 v82, v60, v81
	v_max_i32_e32 v81, 0, v29
	v_fmac_f32_e32 v82, v61, v81
	v_mfma_f32_32x32x16_bf16 v[0:15], v[44:47], v[104:107], v[0:15]
	v_max_i32_e32 v81, 0, v30
	v_fmac_f32_e32 v82, v62, v81
	v_max_i32_e32 v81, 0, v31
	v_cmp_gt_i32_e32 vcc, v183, v203
	v_fmac_f32_e32 v82, v63, v81
	s_and_b64 vcc, s[54:55], vcc
	v_cndmask_b32_e32 v251, v82, v197, vcc
.Lixj7:
	s_waitcnt lgkmcnt(0)
	ds_read_b128 v[96:99], v134 offset:0x3600
	ds_read_b128 v[88:91], v134 offset:0x3620
	ds_read_b128 v[80:83], v134 offset:0x3640
	ds_read_b128 v[104:107], v134 offset:0x3660
	s_cmpk_gt_u32 s94, 0x73
	s_cselect_b64 s[62:63], -1, 0
	s_cmpk_lt_u32 s94, 0x74
	s_cbranch_scc1 .Lixc6
	v_mfma_f32_32x32x16_bf16 v[16:31], v[32:35], v[108:111], 0
	v_cndmask_b32_e64 v109, 0, 1, s[0:1]
	v_cmp_ne_u32_e64 s[54:55], 1, v109
	s_andn2_b64 vcc, exec, s[0:1]
	v_max_i32_e32 v109, 0, v0
	v_fma_f32 v110, v48, v109, 0
	v_max_i32_e32 v109, 0, v1
	v_fmac_f32_e32 v110, v49, v109
	v_max_i32_e32 v109, 0, v2
	v_fmac_f32_e32 v110, v50, v109
	v_max_i32_e32 v109, 0, v3
	v_fmac_f32_e32 v110, v51, v109
	v_max_i32_e32 v109, 0, v4
	v_fmac_f32_e32 v110, v52, v109
	v_mfma_f32_32x32x16_bf16 v[16:31], v[36:39], v[100:103], v[16:31]
	v_max_i32_e32 v109, 0, v5
	v_fmac_f32_e32 v110, v53, v109
	v_max_i32_e32 v109, 0, v6
	v_fmac_f32_e32 v110, v54, v109
	v_max_i32_e32 v109, 0, v7
	v_fmac_f32_e32 v110, v55, v109
	v_max_i32_e32 v109, 0, v8
	v_fmac_f32_e32 v110, v56, v109
	v_max_i32_e32 v109, 0, v9
	v_fmac_f32_e32 v110, v57, v109
	v_mfma_f32_32x32x16_bf16 v[16:31], v[40:43], v[92:95], v[16:31]
	v_max_i32_e32 v109, 0, v10
	v_fmac_f32_e32 v110, v58, v109
	v_max_i32_e32 v109, 0, v11
	v_fmac_f32_e32 v110, v59, v109
	v_max_i32_e32 v109, 0, v12
	v_fmac_f32_e32 v110, v60, v109
	v_max_i32_e32 v109, 0, v13
	v_fmac_f32_e32 v110, v61, v109
	v_mfma_f32_32x32x16_bf16 v[16:31], v[44:47], v[84:87], v[16:31]
	v_max_i32_e32 v109, 0, v14
	s_cmp_eq_u32 s60, 58
	v_fmac_f32_e32 v110, v62, v109
	v_max_i32_e32 v109, 0, v15
	s_cselect_b64 s[0:1], -1, 0
	v_cmp_gt_i32_e32 vcc, v184, v203
	v_fmac_f32_e32 v110, v63, v109
	s_and_b64 vcc, s[0:1], vcc
	v_cndmask_b32_e32 v252, v110, v197, vcc

.Lixc56:
.LBB0_1746:
	s_nop 10
	v_max_i32_e32 v96, 0, v16
	v_fma_f32 v96, v48, v96, 0
	v_max_i32_e32 v97, 0, v17
	v_fmac_f32_e32 v96, v49, v97
	v_max_i32_e32 v97, 0, v18
	v_fmac_f32_e32 v96, v50, v97
	v_max_i32_e32 v97, 0, v19
	v_fmac_f32_e32 v96, v51, v97
	v_max_i32_e32 v97, 0, v20
	v_fmac_f32_e32 v96, v52, v97
	v_max_i32_e32 v97, 0, v21
	v_fmac_f32_e32 v96, v53, v97
	v_max_i32_e32 v97, 0, v22
	v_fmac_f32_e32 v96, v54, v97
	v_max_i32_e32 v97, 0, v23
	v_fmac_f32_e32 v96, v55, v97
	v_max_i32_e32 v97, 0, v24
	v_fmac_f32_e32 v96, v56, v97
	v_max_i32_e32 v97, 0, v25
	v_fmac_f32_e32 v96, v57, v97
	v_max_i32_e32 v97, 0, v26
	s_ashr_i32 s1, s60, 5
	v_fmac_f32_e32 v96, v58, v97
	v_max_i32_e32 v97, 0, v27
	s_lshl_b32 s0, s94, 4
	s_and_b32 s95, s1, -2
	v_fmac_f32_e32 v96, v59, v97
	v_max_i32_e32 v97, 0, v28
	s_add_i32 s95, s95, s0
	v_fmac_f32_e32 v96, v60, v97
	v_max_i32_e32 v97, 0, v29
	v_or_b32_e32 v203, s95, v129
	v_fmac_f32_e32 v96, v61, v97
	v_max_i32_e32 v97, 0, v30
	v_fmac_f32_e32 v96, v62, v97
	v_max_i32_e32 v97, 0, v31
	v_cmp_gt_i32_e32 vcc, v130, v203
	v_fmac_f32_e32 v96, v63, v97
	s_and_b64 vcc, s[50:51], vcc
	v_cndmask_b32_e32 v200, v96, v197, vcc
	s_branch .Lixj56
.Lixc55:
.LBB0_1748:
	s_lshr_b32 s60, s94, 1
	v_cndmask_b32_e64 v80, 0, 1, s[52:53]
	s_add_i32 s60, s60, 1
	v_cmp_ne_u32_e64 s[50:51], 1, v80
	s_andn2_b64 vcc, exec, s[52:53]
	v_mov_b32_e32 v201, 0xff800000
	s_cbranch_vccnz .LBB0_1750
	v_max_i32_e32 v80, 0, v0
	v_fma_f32 v80, v48, v80, 0
	v_max_i32_e32 v81, 0, v1
	v_fmac_f32_e32 v80, v49, v81
	v_max_i32_e32 v81, 0, v2
	v_fmac_f32_e32 v80, v50, v81
	v_max_i32_e32 v81, 0, v3
	v_fmac_f32_e32 v80, v51, v81
	v_max_i32_e32 v81, 0, v4
	v_fmac_f32_e32 v80, v52, v81
	v_max_i32_e32 v81, 0, v5
	v_fmac_f32_e32 v80, v53, v81
	v_max_i32_e32 v81, 0, v6
	v_fmac_f32_e32 v80, v54, v81
	v_max_i32_e32 v81, 0, v7
	v_fmac_f32_e32 v80, v55, v81
	v_max_i32_e32 v81, 0, v8
	v_fmac_f32_e32 v80, v56, v81
	v_max_i32_e32 v81, 0, v9
	v_fmac_f32_e32 v80, v57, v81
	v_max_i32_e32 v81, 0, v10
	v_fmac_f32_e32 v80, v58, v81
	v_max_i32_e32 v81, 0, v11
	v_fmac_f32_e32 v80, v59, v81
	v_max_i32_e32 v81, 0, v12
	v_fmac_f32_e32 v80, v60, v81
	v_max_i32_e32 v81, 0, v13
	v_fmac_f32_e32 v80, v61, v81
	v_max_i32_e32 v81, 0, v14
	v_fmac_f32_e32 v80, v62, v81
	v_max_i32_e32 v81, 0, v15
	v_fmac_f32_e32 v80, v63, v81
	s_cmp_eq_u32 s60, 2
	v_or_b32_e32 v81, 32, v130
	s_cselect_b64 s[0:1], -1, 0
	v_cmp_gt_i32_e32 vcc, v81, v203
	s_and_b64 vcc, s[0:1], vcc
	s_nop 0
	v_cndmask_b32_e32 v201, v80, v197, vcc
	s_branch .Lixj55
.Lixc54:
.LBB0_1754:
	v_cndmask_b32_e64 v84, 0, 1, s[66:67]
	v_cmp_ne_u32_e64 s[52:53], 1, v84
	s_andn2_b64 vcc, exec, s[66:67]
	v_mov_b32_e32 v202, 0xff800000
	s_cbranch_vccnz .LBB0_1756
	v_max_i32_e32 v84, 0, v16
	v_fma_f32 v84, v48, v84, 0
	v_max_i32_e32 v85, 0, v17
	v_fmac_f32_e32 v84, v49, v85
	v_max_i32_e32 v85, 0, v18
	v_fmac_f32_e32 v84, v50, v85
	v_max_i32_e32 v85, 0, v19
	v_fmac_f32_e32 v84, v51, v85
	v_max_i32_e32 v85, 0, v20
	v_fmac_f32_e32 v84, v52, v85
	v_max_i32_e32 v85, 0, v21
	v_fmac_f32_e32 v84, v53, v85
	v_max_i32_e32 v85, 0, v22
	v_fmac_f32_e32 v84, v54, v85
	v_max_i32_e32 v85, 0, v23
	v_fmac_f32_e32 v84, v55, v85
	v_max_i32_e32 v85, 0, v24
	v_fmac_f32_e32 v84, v56, v85
	v_max_i32_e32 v85, 0, v25
	v_fmac_f32_e32 v84, v57, v85
	v_max_i32_e32 v85, 0, v26
	v_fmac_f32_e32 v84, v58, v85
	v_max_i32_e32 v85, 0, v27
	v_fmac_f32_e32 v84, v59, v85
	v_max_i32_e32 v85, 0, v28
	v_fmac_f32_e32 v84, v60, v85
	v_max_i32_e32 v85, 0, v29
	v_fmac_f32_e32 v84, v61, v85
	v_max_i32_e32 v85, 0, v30
	v_fmac_f32_e32 v84, v62, v85
	v_max_i32_e32 v85, 0, v31
	v_fmac_f32_e32 v84, v63, v85
	s_cmp_eq_u32 s60, 3
	v_or_b32_e32 v85, 64, v130
	s_cselect_b64 s[0:1], -1, 0
	v_cmp_gt_i32_e32 vcc, v85, v203
	s_and_b64 vcc, s[0:1], vcc
	s_nop 0
	v_cndmask_b32_e32 v202, v84, v197, vcc
	s_branch .Lixj54
.Lixc53:
.LBB0_1760:
	v_cndmask_b32_e64 v80, 0, 1, s[68:69]
	v_cmp_ne_u32_e64 s[52:53], 1, v80
	s_andn2_b64 vcc, exec, s[68:69]
	v_mov_b32_e32 v112, 0xff800000
	s_cbranch_vccnz .LBB0_1762
	v_max_i32_e32 v80, 0, v0
	v_fma_f32 v80, v48, v80, 0
	v_max_i32_e32 v81, 0, v1
	v_fmac_f32_e32 v80, v49, v81
	v_max_i32_e32 v81, 0, v2
	v_fmac_f32_e32 v80, v50, v81
	v_max_i32_e32 v81, 0, v3
	v_fmac_f32_e32 v80, v51, v81
	v_max_i32_e32 v81, 0, v4
	v_fmac_f32_e32 v80, v52, v81
	v_max_i32_e32 v81, 0, v5
	v_fmac_f32_e32 v80, v53, v81
	v_max_i32_e32 v81, 0, v6
	v_fmac_f32_e32 v80, v54, v81
	v_max_i32_e32 v81, 0, v7
	v_fmac_f32_e32 v80, v55, v81
	v_max_i32_e32 v81, 0, v8
	v_fmac_f32_e32 v80, v56, v81
	v_max_i32_e32 v81, 0, v9
	v_fmac_f32_e32 v80, v57, v81
	v_max_i32_e32 v81, 0, v10
	v_fmac_f32_e32 v80, v58, v81
	v_max_i32_e32 v81, 0, v11
	v_fmac_f32_e32 v80, v59, v81
	v_max_i32_e32 v81, 0, v12
	v_fmac_f32_e32 v80, v60, v81
	v_max_i32_e32 v81, 0, v13
	v_fmac_f32_e32 v80, v61, v81
	v_max_i32_e32 v81, 0, v14
	v_fmac_f32_e32 v80, v62, v81
	v_max_i32_e32 v81, 0, v15
	v_fmac_f32_e32 v80, v63, v81
	s_cmp_eq_u32 s60, 4
	v_or_b32_e32 v81, 0x60, v130
	s_cselect_b64 s[0:1], -1, 0
	v_cmp_gt_i32_e32 vcc, v81, v203
	s_and_b64 vcc, s[0:1], vcc
	s_nop 0
	v_cndmask_b32_e32 v112, v80, v197, vcc
	s_branch .Lixj53
.Lixc52:
.LBB0_1766:
	v_cndmask_b32_e64 v84, 0, 1, s[66:67]
	v_cmp_ne_u32_e64 s[52:53], 1, v84
	s_andn2_b64 vcc, exec, s[66:67]
	v_mov_b32_e32 v113, 0xff800000
	s_cbranch_vccnz .LBB0_1768
	v_max_i32_e32 v84, 0, v16
	v_fma_f32 v84, v48, v84, 0
	v_max_i32_e32 v85, 0, v17
	v_fmac_f32_e32 v84, v49, v85
	v_max_i32_e32 v85, 0, v18
	v_fmac_f32_e32 v84, v50, v85
	v_max_i32_e32 v85, 0, v19
	v_fmac_f32_e32 v84, v51, v85
	v_max_i32_e32 v85, 0, v20
	v_fmac_f32_e32 v84, v52, v85
	v_max_i32_e32 v85, 0, v21
	v_fmac_f32_e32 v84, v53, v85
	v_max_i32_e32 v85, 0, v22
	v_fmac_f32_e32 v84, v54, v85
	v_max_i32_e32 v85, 0, v23
	v_fmac_f32_e32 v84, v55, v85
	v_max_i32_e32 v85, 0, v24
	v_fmac_f32_e32 v84, v56, v85
	v_max_i32_e32 v85, 0, v25
	v_fmac_f32_e32 v84, v57, v85
	v_max_i32_e32 v85, 0, v26
	v_fmac_f32_e32 v84, v58, v85
	v_max_i32_e32 v85, 0, v27
	v_fmac_f32_e32 v84, v59, v85
	v_max_i32_e32 v85, 0, v28
	v_fmac_f32_e32 v84, v60, v85
	v_max_i32_e32 v85, 0, v29
	v_fmac_f32_e32 v84, v61, v85
	v_max_i32_e32 v85, 0, v30
	v_fmac_f32_e32 v84, v62, v85
	v_max_i32_e32 v85, 0, v31
	v_fmac_f32_e32 v84, v63, v85
	s_cmp_eq_u32 s60, 5
	v_or_b32_e32 v85, 0x80, v130
	s_cselect_b64 s[0:1], -1, 0
	v_cmp_gt_i32_e32 vcc, v85, v203
	s_and_b64 vcc, s[0:1], vcc
	s_nop 0
	v_cndmask_b32_e32 v113, v84, v197, vcc
	s_branch .Lixj52
.Lixc51:
.LBB0_1772:
	v_cndmask_b32_e64 v80, 0, 1, s[68:69]
	v_cmp_ne_u32_e64 s[52:53], 1, v80
	s_andn2_b64 vcc, exec, s[68:69]
	v_mov_b32_e32 v114, 0xff800000
	s_cbranch_vccnz .LBB0_1774
	v_max_i32_e32 v80, 0, v0
	v_fma_f32 v80, v48, v80, 0
	v_max_i32_e32 v81, 0, v1
	v_fmac_f32_e32 v80, v49, v81
	v_max_i32_e32 v81, 0, v2
	v_fmac_f32_e32 v80, v50, v81
	v_max_i32_e32 v81, 0, v3
	v_fmac_f32_e32 v80, v51, v81
	v_max_i32_e32 v81, 0, v4
	v_fmac_f32_e32 v80, v52, v81
	v_max_i32_e32 v81, 0, v5
	v_fmac_f32_e32 v80, v53, v81
	v_max_i32_e32 v81, 0, v6
	v_fmac_f32_e32 v80, v54, v81
	v_max_i32_e32 v81, 0, v7
	v_fmac_f32_e32 v80, v55, v81
	v_max_i32_e32 v81, 0, v8
	v_fmac_f32_e32 v80, v56, v81
	v_max_i32_e32 v81, 0, v9
	v_fmac_f32_e32 v80, v57, v81
	v_max_i32_e32 v81, 0, v10
	v_fmac_f32_e32 v80, v58, v81
	v_max_i32_e32 v81, 0, v11
	v_fmac_f32_e32 v80, v59, v81
	v_max_i32_e32 v81, 0, v12
	v_fmac_f32_e32 v80, v60, v81
	v_max_i32_e32 v81, 0, v13
	v_fmac_f32_e32 v80, v61, v81
	v_max_i32_e32 v81, 0, v14
	v_fmac_f32_e32 v80, v62, v81
	v_max_i32_e32 v81, 0, v15
	v_fmac_f32_e32 v80, v63, v81
	s_cmp_eq_u32 s60, 6
	v_or_b32_e32 v81, 0xa0, v130
	s_cselect_b64 s[0:1], -1, 0
	v_cmp_gt_i32_e32 vcc, v81, v203
	s_and_b64 vcc, s[0:1], vcc
	s_nop 0
	v_cndmask_b32_e32 v114, v80, v197, vcc
	s_branch .Lixj51
.Lixc50:
.LBB0_1778:
	v_cndmask_b32_e64 v80, 0, 1, s[66:67]
	v_cmp_ne_u32_e64 s[52:53], 1, v80
	s_andn2_b64 vcc, exec, s[66:67]
	v_mov_b32_e32 v115, 0xff800000
	s_cbranch_vccnz .LBB0_1780
	v_max_i32_e32 v16, 0, v16
	v_fma_f32 v16, v48, v16, 0
	v_max_i32_e32 v17, 0, v17
	v_fmac_f32_e32 v16, v49, v17
	v_max_i32_e32 v17, 0, v18
	v_fmac_f32_e32 v16, v50, v17
	v_max_i32_e32 v17, 0, v19
	v_fmac_f32_e32 v16, v51, v17
	v_max_i32_e32 v17, 0, v20
	v_fmac_f32_e32 v16, v52, v17
	v_max_i32_e32 v17, 0, v21
	v_fmac_f32_e32 v16, v53, v17
	v_max_i32_e32 v17, 0, v22
	v_fmac_f32_e32 v16, v54, v17
	v_max_i32_e32 v17, 0, v23
	v_fmac_f32_e32 v16, v55, v17
	v_max_i32_e32 v17, 0, v24
	v_fmac_f32_e32 v16, v56, v17
	v_max_i32_e32 v17, 0, v25
	v_fmac_f32_e32 v16, v57, v17
	v_max_i32_e32 v17, 0, v26
	v_fmac_f32_e32 v16, v58, v17
	v_max_i32_e32 v17, 0, v27
	v_fmac_f32_e32 v16, v59, v17
	v_max_i32_e32 v17, 0, v28
	v_fmac_f32_e32 v16, v60, v17
	v_max_i32_e32 v17, 0, v29
	v_fmac_f32_e32 v16, v61, v17
	v_max_i32_e32 v17, 0, v30
	s_cmp_eq_u32 s60, 7
	v_fmac_f32_e32 v16, v62, v17
	v_max_i32_e32 v17, 0, v31
	s_cselect_b64 s[0:1], -1, 0
	v_cmp_gt_i32_e32 vcc, v132, v203
	v_fmac_f32_e32 v16, v63, v17
	s_and_b64 vcc, s[0:1], vcc
	v_cndmask_b32_e32 v115, v16, v197, vcc
	s_branch .Lixj50
.Lixc49:
.LBB0_1793:
	s_nop 4
	v_max_i32_e32 v80, 0, v16
	v_fma_f32 v80, v48, v80, 0
	v_max_i32_e32 v81, 0, v17
	v_fmac_f32_e32 v80, v49, v81
	v_max_i32_e32 v81, 0, v18
	v_fmac_f32_e32 v80, v50, v81
	v_max_i32_e32 v81, 0, v19
	v_fmac_f32_e32 v80, v51, v81
	v_max_i32_e32 v81, 0, v20
	v_fmac_f32_e32 v80, v52, v81
	v_max_i32_e32 v81, 0, v21
	v_fmac_f32_e32 v80, v53, v81
	v_max_i32_e32 v81, 0, v22
	v_fmac_f32_e32 v80, v54, v81
	v_max_i32_e32 v81, 0, v23
	v_fmac_f32_e32 v80, v55, v81
	v_max_i32_e32 v81, 0, v24
	v_fmac_f32_e32 v80, v56, v81
	v_max_i32_e32 v81, 0, v25
	v_fmac_f32_e32 v80, v57, v81
	v_max_i32_e32 v81, 0, v26
	v_fmac_f32_e32 v80, v58, v81
	v_max_i32_e32 v81, 0, v27
	v_fmac_f32_e32 v80, v59, v81
	v_max_i32_e32 v81, 0, v28
	v_fmac_f32_e32 v80, v60, v81
	v_max_i32_e32 v81, 0, v29
	v_fmac_f32_e32 v80, v61, v81
	v_max_i32_e32 v81, 0, v30
	v_fmac_f32_e32 v80, v62, v81
	v_max_i32_e32 v81, 0, v31
	v_cmp_gt_i32_e32 vcc, v135, v203
	v_fmac_f32_e32 v80, v63, v81
	s_and_b64 vcc, s[54:55], vcc
	v_cndmask_b32_e32 v117, v80, v197, vcc
	s_branch .Lixj49
.Lixc48:
.LBB0_1795:
	v_cndmask_b32_e64 v84, 0, 1, s[0:1]
	v_cmp_ne_u32_e64 s[54:55], 1, v84
	s_andn2_b64 vcc, exec, s[0:1]
	v_mov_b32_e32 v118, 0xff800000
	s_cbranch_vccnz .LBB0_1797
	v_max_i32_e32 v84, 0, v0
	v_fma_f32 v84, v48, v84, 0
	v_max_i32_e32 v85, 0, v1
	v_fmac_f32_e32 v84, v49, v85
	v_max_i32_e32 v85, 0, v2
	v_fmac_f32_e32 v84, v50, v85
	v_max_i32_e32 v85, 0, v3
	v_fmac_f32_e32 v84, v51, v85
	v_max_i32_e32 v85, 0, v4
	v_fmac_f32_e32 v84, v52, v85
	v_max_i32_e32 v85, 0, v5
	v_fmac_f32_e32 v84, v53, v85
	v_max_i32_e32 v85, 0, v6
	v_fmac_f32_e32 v84, v54, v85
	v_max_i32_e32 v85, 0, v7
	v_fmac_f32_e32 v84, v55, v85
	v_max_i32_e32 v85, 0, v8
	v_fmac_f32_e32 v84, v56, v85
	v_max_i32_e32 v85, 0, v9
	v_fmac_f32_e32 v84, v57, v85
	v_max_i32_e32 v85, 0, v10
	v_fmac_f32_e32 v84, v58, v85
	v_max_i32_e32 v85, 0, v11
	v_fmac_f32_e32 v84, v59, v85
	v_max_i32_e32 v85, 0, v12
	v_fmac_f32_e32 v84, v60, v85
	v_max_i32_e32 v85, 0, v13
	v_fmac_f32_e32 v84, v61, v85
	v_max_i32_e32 v85, 0, v14
	s_cmp_eq_u32 s60, 10
	v_fmac_f32_e32 v84, v62, v85
	v_max_i32_e32 v85, 0, v15
	s_cselect_b64 s[0:1], -1, 0
	v_cmp_gt_i32_e32 vcc, v136, v203
	v_fmac_f32_e32 v84, v63, v85
	s_and_b64 vcc, s[0:1], vcc
	v_cndmask_b32_e32 v118, v84, v197, vcc
	s_branch .Lixj48
.Lixc47:
.LBB0_1801:
	v_cndmask_b32_e64 v80, 0, 1, s[66:67]
	v_cmp_ne_u32_e64 s[54:55], 1, v80
	s_andn2_b64 vcc, exec, s[66:67]
	v_mov_b32_e32 v119, 0xff800000
	s_cbranch_vccnz .LBB0_1803
	v_max_i32_e32 v80, 0, v16
	v_fma_f32 v80, v48, v80, 0
	v_max_i32_e32 v81, 0, v17
	v_fmac_f32_e32 v80, v49, v81
	v_max_i32_e32 v81, 0, v18
	v_fmac_f32_e32 v80, v50, v81
	v_max_i32_e32 v81, 0, v19
	v_fmac_f32_e32 v80, v51, v81
	v_max_i32_e32 v81, 0, v20
	v_fmac_f32_e32 v80, v52, v81
	v_max_i32_e32 v81, 0, v21
	v_fmac_f32_e32 v80, v53, v81
	v_max_i32_e32 v81, 0, v22
	v_fmac_f32_e32 v80, v54, v81
	v_max_i32_e32 v81, 0, v23
	v_fmac_f32_e32 v80, v55, v81
	v_max_i32_e32 v81, 0, v24
	v_fmac_f32_e32 v80, v56, v81
	v_max_i32_e32 v81, 0, v25
	v_fmac_f32_e32 v80, v57, v81
	v_max_i32_e32 v81, 0, v26
	v_fmac_f32_e32 v80, v58, v81
	v_max_i32_e32 v81, 0, v27
	v_fmac_f32_e32 v80, v59, v81
	v_max_i32_e32 v81, 0, v28
	v_fmac_f32_e32 v80, v60, v81
	v_max_i32_e32 v81, 0, v29
	v_fmac_f32_e32 v80, v61, v81
	v_max_i32_e32 v81, 0, v30
	s_cmp_eq_u32 s60, 11
	v_fmac_f32_e32 v80, v62, v81
	v_max_i32_e32 v81, 0, v31
	s_cselect_b64 s[0:1], -1, 0
	v_cmp_gt_i32_e32 vcc, v137, v203
	v_fmac_f32_e32 v80, v63, v81
	s_and_b64 vcc, s[0:1], vcc
	v_cndmask_b32_e32 v119, v80, v197, vcc
	s_branch .Lixj47
.Lixc46:
.LBB0_1807:
	v_cndmask_b32_e64 v84, 0, 1, s[68:69]
	v_cmp_ne_u32_e64 s[54:55], 1, v84
	s_andn2_b64 vcc, exec, s[68:69]
	v_mov_b32_e32 v205, 0xff800000
	s_cbranch_vccnz .LBB0_1809
	v_max_i32_e32 v84, 0, v0
	v_fma_f32 v84, v48, v84, 0
	v_max_i32_e32 v85, 0, v1
	v_fmac_f32_e32 v84, v49, v85
	v_max_i32_e32 v85, 0, v2
	v_fmac_f32_e32 v84, v50, v85
	v_max_i32_e32 v85, 0, v3
	v_fmac_f32_e32 v84, v51, v85
	v_max_i32_e32 v85, 0, v4
	v_fmac_f32_e32 v84, v52, v85
	v_max_i32_e32 v85, 0, v5
	v_fmac_f32_e32 v84, v53, v85
	v_max_i32_e32 v85, 0, v6
	v_fmac_f32_e32 v84, v54, v85
	v_max_i32_e32 v85, 0, v7
	v_fmac_f32_e32 v84, v55, v85
	v_max_i32_e32 v85, 0, v8
	v_fmac_f32_e32 v84, v56, v85
	v_max_i32_e32 v85, 0, v9
	v_fmac_f32_e32 v84, v57, v85
	v_max_i32_e32 v85, 0, v10
	v_fmac_f32_e32 v84, v58, v85
	v_max_i32_e32 v85, 0, v11
	v_fmac_f32_e32 v84, v59, v85
	v_max_i32_e32 v85, 0, v12
	v_fmac_f32_e32 v84, v60, v85
	v_max_i32_e32 v85, 0, v13
	v_fmac_f32_e32 v84, v61, v85
	v_max_i32_e32 v85, 0, v14
	s_cmp_eq_u32 s60, 12
	v_fmac_f32_e32 v84, v62, v85
	v_max_i32_e32 v85, 0, v15
	s_cselect_b64 s[0:1], -1, 0
	v_cmp_gt_i32_e32 vcc, v138, v203
	v_fmac_f32_e32 v84, v63, v85
	s_and_b64 vcc, s[0:1], vcc
	v_cndmask_b32_e32 v205, v84, v197, vcc
	s_branch .Lixj46
.Lixc45:
.LBB0_1813:
	v_cndmask_b32_e64 v80, 0, 1, s[66:67]
	v_cmp_ne_u32_e64 s[54:55], 1, v80
	s_andn2_b64 vcc, exec, s[66:67]
	v_mov_b32_e32 v206, 0xff800000
	s_cbranch_vccnz .LBB0_1815
	v_max_i32_e32 v80, 0, v16
	v_fma_f32 v80, v48, v80, 0
	v_max_i32_e32 v81, 0, v17
	v_fmac_f32_e32 v80, v49, v81
	v_max_i32_e32 v81, 0, v18
	v_fmac_f32_e32 v80, v50, v81
	v_max_i32_e32 v81, 0, v19
	v_fmac_f32_e32 v80, v51, v81
	v_max_i32_e32 v81, 0, v20
	v_fmac_f32_e32 v80, v52, v81
	v_max_i32_e32 v81, 0, v21
	v_fmac_f32_e32 v80, v53, v81
	v_max_i32_e32 v81, 0, v22
	v_fmac_f32_e32 v80, v54, v81
	v_max_i32_e32 v81, 0, v23
	v_fmac_f32_e32 v80, v55, v81
	v_max_i32_e32 v81, 0, v24
	v_fmac_f32_e32 v80, v56, v81
	v_max_i32_e32 v81, 0, v25
	v_fmac_f32_e32 v80, v57, v81
	v_max_i32_e32 v81, 0, v26
	v_fmac_f32_e32 v80, v58, v81
	v_max_i32_e32 v81, 0, v27
	v_fmac_f32_e32 v80, v59, v81
	v_max_i32_e32 v81, 0, v28
	v_fmac_f32_e32 v80, v60, v81
	v_max_i32_e32 v81, 0, v29
	v_fmac_f32_e32 v80, v61, v81
	v_max_i32_e32 v81, 0, v30
	s_cmp_eq_u32 s60, 13
	v_fmac_f32_e32 v80, v62, v81
	v_max_i32_e32 v81, 0, v31
	s_cselect_b64 s[0:1], -1, 0
	v_cmp_gt_i32_e32 vcc, v139, v203
	v_fmac_f32_e32 v80, v63, v81
	s_and_b64 vcc, s[0:1], vcc
	v_cndmask_b32_e32 v206, v80, v197, vcc
	s_branch .Lixj45
.Lixc44:
.LBB0_1819:
	v_cndmask_b32_e64 v84, 0, 1, s[68:69]
	v_cmp_ne_u32_e64 s[54:55], 1, v84
	s_andn2_b64 vcc, exec, s[68:69]
	v_mov_b32_e32 v207, 0xff800000
	s_cbranch_vccnz .LBB0_1821
	v_max_i32_e32 v84, 0, v0
	v_fma_f32 v84, v48, v84, 0
	v_max_i32_e32 v85, 0, v1
	v_fmac_f32_e32 v84, v49, v85
	v_max_i32_e32 v85, 0, v2
	v_fmac_f32_e32 v84, v50, v85
	v_max_i32_e32 v85, 0, v3
	v_fmac_f32_e32 v84, v51, v85
	v_max_i32_e32 v85, 0, v4
	v_fmac_f32_e32 v84, v52, v85
	v_max_i32_e32 v85, 0, v5
	v_fmac_f32_e32 v84, v53, v85
	v_max_i32_e32 v85, 0, v6
	v_fmac_f32_e32 v84, v54, v85
	v_max_i32_e32 v85, 0, v7
	v_fmac_f32_e32 v84, v55, v85
	v_max_i32_e32 v85, 0, v8
	v_fmac_f32_e32 v84, v56, v85
	v_max_i32_e32 v85, 0, v9
	v_fmac_f32_e32 v84, v57, v85
	v_max_i32_e32 v85, 0, v10
	v_fmac_f32_e32 v84, v58, v85
	v_max_i32_e32 v85, 0, v11
	v_fmac_f32_e32 v84, v59, v85
	v_max_i32_e32 v85, 0, v12
	v_fmac_f32_e32 v84, v60, v85
	v_max_i32_e32 v85, 0, v13
	v_fmac_f32_e32 v84, v61, v85
	v_max_i32_e32 v85, 0, v14
	s_cmp_eq_u32 s60, 14
	v_fmac_f32_e32 v84, v62, v85
	v_max_i32_e32 v85, 0, v15
	s_cselect_b64 s[0:1], -1, 0
	v_cmp_gt_i32_e32 vcc, v140, v203
	v_fmac_f32_e32 v84, v63, v85
	s_and_b64 vcc, s[0:1], vcc
	v_cndmask_b32_e32 v207, v84, v197, vcc
	s_branch .Lixj44
.Lixc43:
.LBB0_1825:
	v_cndmask_b32_e64 v80, 0, 1, s[66:67]
	v_cmp_ne_u32_e64 s[54:55], 1, v80
	s_andn2_b64 vcc, exec, s[66:67]
	v_mov_b32_e32 v208, 0xff800000
	s_cbranch_vccnz .LBB0_1827
	v_max_i32_e32 v16, 0, v16
	v_fma_f32 v16, v48, v16, 0
	v_max_i32_e32 v17, 0, v17
	v_fmac_f32_e32 v16, v49, v17
	v_max_i32_e32 v17, 0, v18
	v_fmac_f32_e32 v16, v50, v17
	v_max_i32_e32 v17, 0, v19
	v_fmac_f32_e32 v16, v51, v17
	v_max_i32_e32 v17, 0, v20
	v_fmac_f32_e32 v16, v52, v17
	v_max_i32_e32 v17, 0, v21
	v_fmac_f32_e32 v16, v53, v17
	v_max_i32_e32 v17, 0, v22
	v_fmac_f32_e32 v16, v54, v17
	v_max_i32_e32 v17, 0, v23
	v_fmac_f32_e32 v16, v55, v17
	v_max_i32_e32 v17, 0, v24
	v_fmac_f32_e32 v16, v56, v17
	v_max_i32_e32 v17, 0, v25
	v_fmac_f32_e32 v16, v57, v17
	v_max_i32_e32 v17, 0, v26
	v_fmac_f32_e32 v16, v58, v17
	v_max_i32_e32 v17, 0, v27
	v_fmac_f32_e32 v16, v59, v17
	v_max_i32_e32 v17, 0, v28
	v_fmac_f32_e32 v16, v60, v17
	v_max_i32_e32 v17, 0, v29
	v_fmac_f32_e32 v16, v61, v17
	v_max_i32_e32 v17, 0, v30
	s_cmp_eq_u32 s60, 15
	v_fmac_f32_e32 v16, v62, v17
	v_max_i32_e32 v17, 0, v31
	s_cselect_b64 s[0:1], -1, 0
	v_cmp_gt_i32_e32 vcc, v141, v203
	v_fmac_f32_e32 v16, v63, v17
	s_and_b64 vcc, s[0:1], vcc
	v_cndmask_b32_e32 v208, v16, v197, vcc
	s_branch .Lixj43
.Lixc42:
.LBB0_1837:
	s_nop 4
	v_max_i32_e32 v80, 0, v16
	v_fma_f32 v80, v48, v80, 0
	v_max_i32_e32 v81, 0, v17
	v_fmac_f32_e32 v80, v49, v81
	v_max_i32_e32 v81, 0, v18
	v_fmac_f32_e32 v80, v50, v81
	v_max_i32_e32 v81, 0, v19
	v_fmac_f32_e32 v80, v51, v81
	v_max_i32_e32 v81, 0, v20
	v_fmac_f32_e32 v80, v52, v81
	v_max_i32_e32 v81, 0, v21
	v_fmac_f32_e32 v80, v53, v81
	v_max_i32_e32 v81, 0, v22
	v_fmac_f32_e32 v80, v54, v81
	v_max_i32_e32 v81, 0, v23
	v_fmac_f32_e32 v80, v55, v81
	v_max_i32_e32 v81, 0, v24
	v_fmac_f32_e32 v80, v56, v81
	v_max_i32_e32 v81, 0, v25
	v_fmac_f32_e32 v80, v57, v81
	v_max_i32_e32 v81, 0, v26
	v_fmac_f32_e32 v80, v58, v81
	v_max_i32_e32 v81, 0, v27
	v_fmac_f32_e32 v80, v59, v81
	v_max_i32_e32 v81, 0, v28
	v_fmac_f32_e32 v80, v60, v81
	v_max_i32_e32 v81, 0, v29
	v_fmac_f32_e32 v80, v61, v81
	v_max_i32_e32 v81, 0, v30
	v_fmac_f32_e32 v80, v62, v81
	v_max_i32_e32 v81, 0, v31
	v_cmp_gt_i32_e32 vcc, v143, v203
	v_fmac_f32_e32 v80, v63, v81
	s_and_b64 vcc, s[54:55], vcc
	v_cndmask_b32_e32 v210, v80, v197, vcc
	s_branch .Lixj42
.Lixc41:
.LBB0_1839:
	v_cndmask_b32_e64 v84, 0, 1, s[0:1]
	v_cmp_ne_u32_e64 s[54:55], 1, v84
	s_andn2_b64 vcc, exec, s[0:1]
	v_mov_b32_e32 v211, 0xff800000
	s_cbranch_vccnz .LBB0_1841
	v_max_i32_e32 v84, 0, v0
	v_fma_f32 v84, v48, v84, 0
	v_max_i32_e32 v85, 0, v1
	v_fmac_f32_e32 v84, v49, v85
	v_max_i32_e32 v85, 0, v2
	v_fmac_f32_e32 v84, v50, v85
	v_max_i32_e32 v85, 0, v3
	v_fmac_f32_e32 v84, v51, v85
	v_max_i32_e32 v85, 0, v4
	v_fmac_f32_e32 v84, v52, v85
	v_max_i32_e32 v85, 0, v5
	v_fmac_f32_e32 v84, v53, v85
	v_max_i32_e32 v85, 0, v6
	v_fmac_f32_e32 v84, v54, v85
	v_max_i32_e32 v85, 0, v7
	v_fmac_f32_e32 v84, v55, v85
	v_max_i32_e32 v85, 0, v8
	v_fmac_f32_e32 v84, v56, v85
	v_max_i32_e32 v85, 0, v9
	v_fmac_f32_e32 v84, v57, v85
	v_max_i32_e32 v85, 0, v10
	v_fmac_f32_e32 v84, v58, v85
	v_max_i32_e32 v85, 0, v11
	v_fmac_f32_e32 v84, v59, v85
	v_max_i32_e32 v85, 0, v12
	v_fmac_f32_e32 v84, v60, v85
	v_max_i32_e32 v85, 0, v13
	v_fmac_f32_e32 v84, v61, v85
	v_max_i32_e32 v85, 0, v14
	s_cmp_eq_u32 s60, 18
	v_fmac_f32_e32 v84, v62, v85
	v_max_i32_e32 v85, 0, v15
	s_cselect_b64 s[0:1], -1, 0
	v_cmp_gt_i32_e32 vcc, v144, v203
	v_fmac_f32_e32 v84, v63, v85
	s_and_b64 vcc, s[0:1], vcc
	v_cndmask_b32_e32 v211, v84, v197, vcc
	s_branch .Lixj41
.Lixc40:
.LBB0_1845:
	v_cndmask_b32_e64 v80, 0, 1, s[66:67]
	v_cmp_ne_u32_e64 s[54:55], 1, v80
	s_andn2_b64 vcc, exec, s[66:67]
	v_mov_b32_e32 v212, 0xff800000
	s_cbranch_vccnz .LBB0_1847
	v_max_i32_e32 v80, 0, v16
	v_fma_f32 v80, v48, v80, 0
	v_max_i32_e32 v81, 0, v17
	v_fmac_f32_e32 v80, v49, v81
	v_max_i32_e32 v81, 0, v18
	v_fmac_f32_e32 v80, v50, v81
	v_max_i32_e32 v81, 0, v19
	v_fmac_f32_e32 v80, v51, v81
	v_max_i32_e32 v81, 0, v20
	v_fmac_f32_e32 v80, v52, v81
	v_max_i32_e32 v81, 0, v21
	v_fmac_f32_e32 v80, v53, v81
	v_max_i32_e32 v81, 0, v22
	v_fmac_f32_e32 v80, v54, v81
	v_max_i32_e32 v81, 0, v23
	v_fmac_f32_e32 v80, v55, v81
	v_max_i32_e32 v81, 0, v24
	v_fmac_f32_e32 v80, v56, v81
	v_max_i32_e32 v81, 0, v25
	v_fmac_f32_e32 v80, v57, v81
	v_max_i32_e32 v81, 0, v26
	v_fmac_f32_e32 v80, v58, v81
	v_max_i32_e32 v81, 0, v27
	v_fmac_f32_e32 v80, v59, v81
	v_max_i32_e32 v81, 0, v28
	v_fmac_f32_e32 v80, v60, v81
	v_max_i32_e32 v81, 0, v29
	v_fmac_f32_e32 v80, v61, v81
	v_max_i32_e32 v81, 0, v30
	s_cmp_eq_u32 s60, 19
	v_fmac_f32_e32 v80, v62, v81
	v_max_i32_e32 v81, 0, v31
	s_cselect_b64 s[0:1], -1, 0
	v_cmp_gt_i32_e32 vcc, v145, v203
	v_fmac_f32_e32 v80, v63, v81
	s_and_b64 vcc, s[0:1], vcc
	v_cndmask_b32_e32 v212, v80, v197, vcc
	s_branch .Lixj40
.Lixc39:
.LBB0_1851:
	v_cndmask_b32_e64 v84, 0, 1, s[68:69]
	v_cmp_ne_u32_e64 s[54:55], 1, v84
	s_andn2_b64 vcc, exec, s[68:69]
	v_mov_b32_e32 v213, 0xff800000
	s_cbranch_vccnz .LBB0_1853
	v_max_i32_e32 v84, 0, v0
	v_fma_f32 v84, v48, v84, 0
	v_max_i32_e32 v85, 0, v1
	v_fmac_f32_e32 v84, v49, v85
	v_max_i32_e32 v85, 0, v2
	v_fmac_f32_e32 v84, v50, v85
	v_max_i32_e32 v85, 0, v3
	v_fmac_f32_e32 v84, v51, v85
	v_max_i32_e32 v85, 0, v4
	v_fmac_f32_e32 v84, v52, v85
	v_max_i32_e32 v85, 0, v5
	v_fmac_f32_e32 v84, v53, v85
	v_max_i32_e32 v85, 0, v6
	v_fmac_f32_e32 v84, v54, v85
	v_max_i32_e32 v85, 0, v7
	v_fmac_f32_e32 v84, v55, v85
	v_max_i32_e32 v85, 0, v8
	v_fmac_f32_e32 v84, v56, v85
	v_max_i32_e32 v85, 0, v9
	v_fmac_f32_e32 v84, v57, v85
	v_max_i32_e32 v85, 0, v10
	v_fmac_f32_e32 v84, v58, v85
	v_max_i32_e32 v85, 0, v11
	v_fmac_f32_e32 v84, v59, v85
	v_max_i32_e32 v85, 0, v12
	v_fmac_f32_e32 v84, v60, v85
	v_max_i32_e32 v85, 0, v13
	v_fmac_f32_e32 v84, v61, v85
	v_max_i32_e32 v85, 0, v14
	s_cmp_eq_u32 s60, 20
	v_fmac_f32_e32 v84, v62, v85
	v_max_i32_e32 v85, 0, v15
	s_cselect_b64 s[0:1], -1, 0
	v_cmp_gt_i32_e32 vcc, v146, v203
	v_fmac_f32_e32 v84, v63, v85
	s_and_b64 vcc, s[0:1], vcc
	v_cndmask_b32_e32 v213, v84, v197, vcc
	s_branch .Lixj39
.Lixc38:
.LBB0_1857:
	v_cndmask_b32_e64 v80, 0, 1, s[66:67]
	v_cmp_ne_u32_e64 s[54:55], 1, v80
	s_andn2_b64 vcc, exec, s[66:67]
	v_mov_b32_e32 v214, 0xff800000
	s_cbranch_vccnz .LBB0_1859
	v_max_i32_e32 v80, 0, v16
	v_fma_f32 v80, v48, v80, 0
	v_max_i32_e32 v81, 0, v17
	v_fmac_f32_e32 v80, v49, v81
	v_max_i32_e32 v81, 0, v18
	v_fmac_f32_e32 v80, v50, v81
	v_max_i32_e32 v81, 0, v19
	v_fmac_f32_e32 v80, v51, v81
	v_max_i32_e32 v81, 0, v20
	v_fmac_f32_e32 v80, v52, v81
	v_max_i32_e32 v81, 0, v21
	v_fmac_f32_e32 v80, v53, v81
	v_max_i32_e32 v81, 0, v22
	v_fmac_f32_e32 v80, v54, v81
	v_max_i32_e32 v81, 0, v23
	v_fmac_f32_e32 v80, v55, v81
	v_max_i32_e32 v81, 0, v24
	v_fmac_f32_e32 v80, v56, v81
	v_max_i32_e32 v81, 0, v25
	v_fmac_f32_e32 v80, v57, v81
	v_max_i32_e32 v81, 0, v26
	v_fmac_f32_e32 v80, v58, v81
	v_max_i32_e32 v81, 0, v27
	v_fmac_f32_e32 v80, v59, v81
	v_max_i32_e32 v81, 0, v28
	v_fmac_f32_e32 v80, v60, v81
	v_max_i32_e32 v81, 0, v29
	v_fmac_f32_e32 v80, v61, v81
	v_max_i32_e32 v81, 0, v30
	s_cmp_eq_u32 s60, 21
	v_fmac_f32_e32 v80, v62, v81
	v_max_i32_e32 v81, 0, v31
	s_cselect_b64 s[0:1], -1, 0
	v_cmp_gt_i32_e32 vcc, v147, v203
	v_fmac_f32_e32 v80, v63, v81
	s_and_b64 vcc, s[0:1], vcc
	v_cndmask_b32_e32 v214, v80, v197, vcc
	s_branch .Lixj38
.Lixc37:
.LBB0_1863:
	v_cndmask_b32_e64 v84, 0, 1, s[68:69]
	v_cmp_ne_u32_e64 s[54:55], 1, v84
	s_andn2_b64 vcc, exec, s[68:69]
	v_mov_b32_e32 v216, 0xff800000
	s_cbranch_vccnz .LBB0_1865
	v_max_i32_e32 v84, 0, v0
	v_fma_f32 v84, v48, v84, 0
	v_max_i32_e32 v85, 0, v1
	v_fmac_f32_e32 v84, v49, v85
	v_max_i32_e32 v85, 0, v2
	v_fmac_f32_e32 v84, v50, v85
	v_max_i32_e32 v85, 0, v3
	v_fmac_f32_e32 v84, v51, v85
	v_max_i32_e32 v85, 0, v4
	v_fmac_f32_e32 v84, v52, v85
	v_max_i32_e32 v85, 0, v5
	v_fmac_f32_e32 v84, v53, v85
	v_max_i32_e32 v85, 0, v6
	v_fmac_f32_e32 v84, v54, v85
	v_max_i32_e32 v85, 0, v7
	v_fmac_f32_e32 v84, v55, v85
	v_max_i32_e32 v85, 0, v8
	v_fmac_f32_e32 v84, v56, v85
	v_max_i32_e32 v85, 0, v9
	v_fmac_f32_e32 v84, v57, v85
	v_max_i32_e32 v85, 0, v10
	v_fmac_f32_e32 v84, v58, v85
	v_max_i32_e32 v85, 0, v11
	v_fmac_f32_e32 v84, v59, v85
	v_max_i32_e32 v85, 0, v12
	v_fmac_f32_e32 v84, v60, v85
	v_max_i32_e32 v85, 0, v13
	v_fmac_f32_e32 v84, v61, v85
	v_max_i32_e32 v85, 0, v14
	s_cmp_eq_u32 s60, 22
	v_fmac_f32_e32 v84, v62, v85
	v_max_i32_e32 v85, 0, v15
	s_cselect_b64 s[0:1], -1, 0
	v_cmp_gt_i32_e32 vcc, v148, v203
	v_fmac_f32_e32 v84, v63, v85
	s_and_b64 vcc, s[0:1], vcc
	v_cndmask_b32_e32 v216, v84, v197, vcc
	s_branch .Lixj37
.Lixc36:
.LBB0_1869:
	v_cndmask_b32_e64 v80, 0, 1, s[66:67]
	v_cmp_ne_u32_e64 s[54:55], 1, v80
	s_andn2_b64 vcc, exec, s[66:67]
	v_mov_b32_e32 v217, 0xff800000
	s_cbranch_vccnz .LBB0_1871
	v_max_i32_e32 v16, 0, v16
	v_fma_f32 v16, v48, v16, 0
	v_max_i32_e32 v17, 0, v17
	v_fmac_f32_e32 v16, v49, v17
	v_max_i32_e32 v17, 0, v18
	v_fmac_f32_e32 v16, v50, v17
	v_max_i32_e32 v17, 0, v19
	v_fmac_f32_e32 v16, v51, v17
	v_max_i32_e32 v17, 0, v20
	v_fmac_f32_e32 v16, v52, v17
	v_max_i32_e32 v17, 0, v21
	v_fmac_f32_e32 v16, v53, v17
	v_max_i32_e32 v17, 0, v22
	v_fmac_f32_e32 v16, v54, v17
	v_max_i32_e32 v17, 0, v23
	v_fmac_f32_e32 v16, v55, v17
	v_max_i32_e32 v17, 0, v24
	v_fmac_f32_e32 v16, v56, v17
	v_max_i32_e32 v17, 0, v25
	v_fmac_f32_e32 v16, v57, v17
	v_max_i32_e32 v17, 0, v26
	v_fmac_f32_e32 v16, v58, v17
	v_max_i32_e32 v17, 0, v27
	v_fmac_f32_e32 v16, v59, v17
	v_max_i32_e32 v17, 0, v28
	v_fmac_f32_e32 v16, v60, v17
	v_max_i32_e32 v17, 0, v29
	v_fmac_f32_e32 v16, v61, v17
	v_max_i32_e32 v17, 0, v30
	s_cmp_eq_u32 s60, 23
	v_fmac_f32_e32 v16, v62, v17
	v_max_i32_e32 v17, 0, v31
	s_cselect_b64 s[0:1], -1, 0
	v_cmp_gt_i32_e32 vcc, v149, v203
	v_fmac_f32_e32 v16, v63, v17
	s_and_b64 vcc, s[0:1], vcc
	v_cndmask_b32_e32 v217, v16, v197, vcc
	s_branch .Lixj36
.Lixc35:
.LBB0_1881:
	s_nop 4
	v_max_i32_e32 v80, 0, v16
	v_fma_f32 v80, v48, v80, 0
	v_max_i32_e32 v81, 0, v17
	v_fmac_f32_e32 v80, v49, v81
	v_max_i32_e32 v81, 0, v18
	v_fmac_f32_e32 v80, v50, v81
	v_max_i32_e32 v81, 0, v19
	v_fmac_f32_e32 v80, v51, v81
	v_max_i32_e32 v81, 0, v20
	v_fmac_f32_e32 v80, v52, v81
	v_max_i32_e32 v81, 0, v21
	v_fmac_f32_e32 v80, v53, v81
	v_max_i32_e32 v81, 0, v22
	v_fmac_f32_e32 v80, v54, v81
	v_max_i32_e32 v81, 0, v23
	v_fmac_f32_e32 v80, v55, v81
	v_max_i32_e32 v81, 0, v24
	v_fmac_f32_e32 v80, v56, v81
	v_max_i32_e32 v81, 0, v25
	v_fmac_f32_e32 v80, v57, v81
	v_max_i32_e32 v81, 0, v26
	v_fmac_f32_e32 v80, v58, v81
	v_max_i32_e32 v81, 0, v27
	v_fmac_f32_e32 v80, v59, v81
	v_max_i32_e32 v81, 0, v28
	v_fmac_f32_e32 v80, v60, v81
	v_max_i32_e32 v81, 0, v29
	v_fmac_f32_e32 v80, v61, v81
	v_max_i32_e32 v81, 0, v30
	v_fmac_f32_e32 v80, v62, v81
	v_max_i32_e32 v81, 0, v31
	v_cmp_gt_i32_e32 vcc, v151, v203
	v_fmac_f32_e32 v80, v63, v81
	s_and_b64 vcc, s[54:55], vcc
	v_cndmask_b32_e32 v219, v80, v197, vcc
	s_branch .Lixj35
.Lixc34:
.LBB0_1883:
	v_cndmask_b32_e64 v84, 0, 1, s[0:1]
	v_cmp_ne_u32_e64 s[54:55], 1, v84
	s_andn2_b64 vcc, exec, s[0:1]
	v_mov_b32_e32 v220, 0xff800000
	s_cbranch_vccnz .LBB0_1885
	v_max_i32_e32 v84, 0, v0
	v_fma_f32 v84, v48, v84, 0
	v_max_i32_e32 v85, 0, v1
	v_fmac_f32_e32 v84, v49, v85
	v_max_i32_e32 v85, 0, v2
	v_fmac_f32_e32 v84, v50, v85
	v_max_i32_e32 v85, 0, v3
	v_fmac_f32_e32 v84, v51, v85
	v_max_i32_e32 v85, 0, v4
	v_fmac_f32_e32 v84, v52, v85
	v_max_i32_e32 v85, 0, v5
	v_fmac_f32_e32 v84, v53, v85
	v_max_i32_e32 v85, 0, v6
	v_fmac_f32_e32 v84, v54, v85
	v_max_i32_e32 v85, 0, v7
	v_fmac_f32_e32 v84, v55, v85
	v_max_i32_e32 v85, 0, v8
	v_fmac_f32_e32 v84, v56, v85
	v_max_i32_e32 v85, 0, v9
	v_fmac_f32_e32 v84, v57, v85
	v_max_i32_e32 v85, 0, v10
	v_fmac_f32_e32 v84, v58, v85
	v_max_i32_e32 v85, 0, v11
	v_fmac_f32_e32 v84, v59, v85
	v_max_i32_e32 v85, 0, v12
	v_fmac_f32_e32 v84, v60, v85
	v_max_i32_e32 v85, 0, v13
	v_fmac_f32_e32 v84, v61, v85
	v_max_i32_e32 v85, 0, v14
	s_cmp_eq_u32 s60, 26
	v_fmac_f32_e32 v84, v62, v85
	v_max_i32_e32 v85, 0, v15
	s_cselect_b64 s[0:1], -1, 0
	v_cmp_gt_i32_e32 vcc, v152, v203
	v_fmac_f32_e32 v84, v63, v85
	s_and_b64 vcc, s[0:1], vcc
	v_cndmask_b32_e32 v220, v84, v197, vcc
	s_branch .Lixj34
.Lixc33:
.LBB0_1889:
	v_cndmask_b32_e64 v80, 0, 1, s[66:67]
	v_cmp_ne_u32_e64 s[54:55], 1, v80
	s_andn2_b64 vcc, exec, s[66:67]
	v_mov_b32_e32 v221, 0xff800000
	s_cbranch_vccnz .LBB0_1891
	v_max_i32_e32 v80, 0, v16
	v_fma_f32 v80, v48, v80, 0
	v_max_i32_e32 v81, 0, v17
	v_fmac_f32_e32 v80, v49, v81
	v_max_i32_e32 v81, 0, v18
	v_fmac_f32_e32 v80, v50, v81
	v_max_i32_e32 v81, 0, v19
	v_fmac_f32_e32 v80, v51, v81
	v_max_i32_e32 v81, 0, v20
	v_fmac_f32_e32 v80, v52, v81
	v_max_i32_e32 v81, 0, v21
	v_fmac_f32_e32 v80, v53, v81
	v_max_i32_e32 v81, 0, v22
	v_fmac_f32_e32 v80, v54, v81
	v_max_i32_e32 v81, 0, v23
	v_fmac_f32_e32 v80, v55, v81
	v_max_i32_e32 v81, 0, v24
	v_fmac_f32_e32 v80, v56, v81
	v_max_i32_e32 v81, 0, v25
	v_fmac_f32_e32 v80, v57, v81
	v_max_i32_e32 v81, 0, v26
	v_fmac_f32_e32 v80, v58, v81
	v_max_i32_e32 v81, 0, v27
	v_fmac_f32_e32 v80, v59, v81
	v_max_i32_e32 v81, 0, v28
	v_fmac_f32_e32 v80, v60, v81
	v_max_i32_e32 v81, 0, v29
	v_fmac_f32_e32 v80, v61, v81
	v_max_i32_e32 v81, 0, v30
	s_cmp_eq_u32 s60, 27
	v_fmac_f32_e32 v80, v62, v81
	v_max_i32_e32 v81, 0, v31
	s_cselect_b64 s[0:1], -1, 0
	v_cmp_gt_i32_e32 vcc, v153, v203
	v_fmac_f32_e32 v80, v63, v81
	s_and_b64 vcc, s[0:1], vcc
	v_cndmask_b32_e32 v221, v80, v197, vcc
	s_branch .Lixj33
.Lixc32:
.LBB0_1895:
	v_cndmask_b32_e64 v84, 0, 1, s[68:69]
	v_cmp_ne_u32_e64 s[54:55], 1, v84
	s_andn2_b64 vcc, exec, s[68:69]
	v_mov_b32_e32 v222, 0xff800000
	s_cbranch_vccnz .LBB0_1897
	v_max_i32_e32 v84, 0, v0
	v_fma_f32 v84, v48, v84, 0
	v_max_i32_e32 v85, 0, v1
	v_fmac_f32_e32 v84, v49, v85
	v_max_i32_e32 v85, 0, v2
	v_fmac_f32_e32 v84, v50, v85
	v_max_i32_e32 v85, 0, v3
	v_fmac_f32_e32 v84, v51, v85
	v_max_i32_e32 v85, 0, v4
	v_fmac_f32_e32 v84, v52, v85
	v_max_i32_e32 v85, 0, v5
	v_fmac_f32_e32 v84, v53, v85
	v_max_i32_e32 v85, 0, v6
	v_fmac_f32_e32 v84, v54, v85
	v_max_i32_e32 v85, 0, v7
	v_fmac_f32_e32 v84, v55, v85
	v_max_i32_e32 v85, 0, v8
	v_fmac_f32_e32 v84, v56, v85
	v_max_i32_e32 v85, 0, v9
	v_fmac_f32_e32 v84, v57, v85
	v_max_i32_e32 v85, 0, v10
	v_fmac_f32_e32 v84, v58, v85
	v_max_i32_e32 v85, 0, v11
	v_fmac_f32_e32 v84, v59, v85
	v_max_i32_e32 v85, 0, v12
	v_fmac_f32_e32 v84, v60, v85
	v_max_i32_e32 v85, 0, v13
	v_fmac_f32_e32 v84, v61, v85
	v_max_i32_e32 v85, 0, v14
	s_cmp_eq_u32 s60, 28
	v_fmac_f32_e32 v84, v62, v85
	v_max_i32_e32 v85, 0, v15
	s_cselect_b64 s[0:1], -1, 0
	v_cmp_gt_i32_e32 vcc, v154, v203
	v_fmac_f32_e32 v84, v63, v85
	s_and_b64 vcc, s[0:1], vcc
	v_cndmask_b32_e32 v222, v84, v197, vcc
	s_branch .Lixj32
.Lixc31:
.LBB0_1901:
	v_cndmask_b32_e64 v80, 0, 1, s[66:67]
	v_cmp_ne_u32_e64 s[54:55], 1, v80
	s_andn2_b64 vcc, exec, s[66:67]
	v_mov_b32_e32 v223, 0xff800000
	s_cbranch_vccnz .LBB0_1903
	v_max_i32_e32 v80, 0, v16
	v_fma_f32 v80, v48, v80, 0
	v_max_i32_e32 v81, 0, v17
	v_fmac_f32_e32 v80, v49, v81
	v_max_i32_e32 v81, 0, v18
	v_fmac_f32_e32 v80, v50, v81
	v_max_i32_e32 v81, 0, v19
	v_fmac_f32_e32 v80, v51, v81
	v_max_i32_e32 v81, 0, v20
	v_fmac_f32_e32 v80, v52, v81
	v_max_i32_e32 v81, 0, v21
	v_fmac_f32_e32 v80, v53, v81
	v_max_i32_e32 v81, 0, v22
	v_fmac_f32_e32 v80, v54, v81
	v_max_i32_e32 v81, 0, v23
	v_fmac_f32_e32 v80, v55, v81
	v_max_i32_e32 v81, 0, v24
	v_fmac_f32_e32 v80, v56, v81
	v_max_i32_e32 v81, 0, v25
	v_fmac_f32_e32 v80, v57, v81
	v_max_i32_e32 v81, 0, v26
	v_fmac_f32_e32 v80, v58, v81
	v_max_i32_e32 v81, 0, v27
	v_fmac_f32_e32 v80, v59, v81
	v_max_i32_e32 v81, 0, v28
	v_fmac_f32_e32 v80, v60, v81
	v_max_i32_e32 v81, 0, v29
	v_fmac_f32_e32 v80, v61, v81
	v_max_i32_e32 v81, 0, v30
	s_cmp_eq_u32 s60, 29
	v_fmac_f32_e32 v80, v62, v81
	v_max_i32_e32 v81, 0, v31
	s_cselect_b64 s[0:1], -1, 0
	v_cmp_gt_i32_e32 vcc, v155, v203
	v_fmac_f32_e32 v80, v63, v81
	s_and_b64 vcc, s[0:1], vcc
	v_cndmask_b32_e32 v223, v80, v197, vcc
	s_branch .Lixj31
.Lixc30:
.LBB0_1907:
	v_cndmask_b32_e64 v84, 0, 1, s[68:69]
	v_cmp_ne_u32_e64 s[54:55], 1, v84
	s_andn2_b64 vcc, exec, s[68:69]
	v_mov_b32_e32 v224, 0xff800000
	s_cbranch_vccnz .LBB0_1909
	v_max_i32_e32 v84, 0, v0
	v_fma_f32 v84, v48, v84, 0
	v_max_i32_e32 v85, 0, v1
	v_fmac_f32_e32 v84, v49, v85
	v_max_i32_e32 v85, 0, v2
	v_fmac_f32_e32 v84, v50, v85
	v_max_i32_e32 v85, 0, v3
	v_fmac_f32_e32 v84, v51, v85
	v_max_i32_e32 v85, 0, v4
	v_fmac_f32_e32 v84, v52, v85
	v_max_i32_e32 v85, 0, v5
	v_fmac_f32_e32 v84, v53, v85
	v_max_i32_e32 v85, 0, v6
	v_fmac_f32_e32 v84, v54, v85
	v_max_i32_e32 v85, 0, v7
	v_fmac_f32_e32 v84, v55, v85
	v_max_i32_e32 v85, 0, v8
	v_fmac_f32_e32 v84, v56, v85
	v_max_i32_e32 v85, 0, v9
	v_fmac_f32_e32 v84, v57, v85
	v_max_i32_e32 v85, 0, v10
	v_fmac_f32_e32 v84, v58, v85
	v_max_i32_e32 v85, 0, v11
	v_fmac_f32_e32 v84, v59, v85
	v_max_i32_e32 v85, 0, v12
	v_fmac_f32_e32 v84, v60, v85
	v_max_i32_e32 v85, 0, v13
	v_fmac_f32_e32 v84, v61, v85
	v_max_i32_e32 v85, 0, v14
	s_cmp_eq_u32 s60, 30
	v_fmac_f32_e32 v84, v62, v85
	v_max_i32_e32 v85, 0, v15
	s_cselect_b64 s[0:1], -1, 0
	v_cmp_gt_i32_e32 vcc, v156, v203
	v_fmac_f32_e32 v84, v63, v85
	s_and_b64 vcc, s[0:1], vcc
	v_cndmask_b32_e32 v224, v84, v197, vcc
	s_branch .Lixj30
.Lixc29:
.LBB0_1913:
	v_cndmask_b32_e64 v80, 0, 1, s[66:67]
	v_cmp_ne_u32_e64 s[54:55], 1, v80
	s_andn2_b64 vcc, exec, s[66:67]
	v_mov_b32_e32 v225, 0xff800000
	s_cbranch_vccnz .LBB0_1915
	v_max_i32_e32 v16, 0, v16
	v_fma_f32 v16, v48, v16, 0
	v_max_i32_e32 v17, 0, v17
	v_fmac_f32_e32 v16, v49, v17
	v_max_i32_e32 v17, 0, v18
	v_fmac_f32_e32 v16, v50, v17
	v_max_i32_e32 v17, 0, v19
	v_fmac_f32_e32 v16, v51, v17
	v_max_i32_e32 v17, 0, v20
	v_fmac_f32_e32 v16, v52, v17
	v_max_i32_e32 v17, 0, v21
	v_fmac_f32_e32 v16, v53, v17
	v_max_i32_e32 v17, 0, v22
	v_fmac_f32_e32 v16, v54, v17
	v_max_i32_e32 v17, 0, v23
	v_fmac_f32_e32 v16, v55, v17
	v_max_i32_e32 v17, 0, v24
	v_fmac_f32_e32 v16, v56, v17
	v_max_i32_e32 v17, 0, v25
	v_fmac_f32_e32 v16, v57, v17
	v_max_i32_e32 v17, 0, v26
	v_fmac_f32_e32 v16, v58, v17
	v_max_i32_e32 v17, 0, v27
	v_fmac_f32_e32 v16, v59, v17
	v_max_i32_e32 v17, 0, v28
	v_fmac_f32_e32 v16, v60, v17
	v_max_i32_e32 v17, 0, v29
	v_fmac_f32_e32 v16, v61, v17
	v_max_i32_e32 v17, 0, v30
	s_cmp_eq_u32 s60, 31
	v_fmac_f32_e32 v16, v62, v17
	v_max_i32_e32 v17, 0, v31
	s_cselect_b64 s[0:1], -1, 0
	v_cmp_gt_i32_e32 vcc, v157, v203
	v_fmac_f32_e32 v16, v63, v17
	s_and_b64 vcc, s[0:1], vcc
	v_cndmask_b32_e32 v225, v16, v197, vcc
	s_branch .Lixj29
.Lixc28:
.LBB0_1925:
	s_nop 4
	v_max_i32_e32 v80, 0, v16
	v_fma_f32 v80, v48, v80, 0
	v_max_i32_e32 v81, 0, v17
	v_fmac_f32_e32 v80, v49, v81
	v_max_i32_e32 v81, 0, v18
	v_fmac_f32_e32 v80, v50, v81
	v_max_i32_e32 v81, 0, v19
	v_fmac_f32_e32 v80, v51, v81
	v_max_i32_e32 v81, 0, v20
	v_fmac_f32_e32 v80, v52, v81
	v_max_i32_e32 v81, 0, v21
	v_fmac_f32_e32 v80, v53, v81
	v_max_i32_e32 v81, 0, v22
	v_fmac_f32_e32 v80, v54, v81
	v_max_i32_e32 v81, 0, v23
	v_fmac_f32_e32 v80, v55, v81
	v_max_i32_e32 v81, 0, v24
	v_fmac_f32_e32 v80, v56, v81
	v_max_i32_e32 v81, 0, v25
	v_fmac_f32_e32 v80, v57, v81
	v_max_i32_e32 v81, 0, v26
	v_fmac_f32_e32 v80, v58, v81
	v_max_i32_e32 v81, 0, v27
	v_fmac_f32_e32 v80, v59, v81
	v_max_i32_e32 v81, 0, v28
	v_fmac_f32_e32 v80, v60, v81
	v_max_i32_e32 v81, 0, v29
	v_fmac_f32_e32 v80, v61, v81
	v_max_i32_e32 v81, 0, v30
	v_fmac_f32_e32 v80, v62, v81
	v_max_i32_e32 v81, 0, v31
	v_cmp_gt_i32_e32 vcc, v159, v203
	v_fmac_f32_e32 v80, v63, v81
	s_and_b64 vcc, s[54:55], vcc
	v_cndmask_b32_e32 v227, v80, v197, vcc
	s_branch .Lixj28
.Lixc27:
.LBB0_1927:
	v_cndmask_b32_e64 v84, 0, 1, s[0:1]
	v_cmp_ne_u32_e64 s[54:55], 1, v84
	s_andn2_b64 vcc, exec, s[0:1]
	v_mov_b32_e32 v228, 0xff800000
	s_cbranch_vccnz .LBB0_1929
	v_max_i32_e32 v84, 0, v0
	v_fma_f32 v84, v48, v84, 0
	v_max_i32_e32 v85, 0, v1
	v_fmac_f32_e32 v84, v49, v85
	v_max_i32_e32 v85, 0, v2
	v_fmac_f32_e32 v84, v50, v85
	v_max_i32_e32 v85, 0, v3
	v_fmac_f32_e32 v84, v51, v85
	v_max_i32_e32 v85, 0, v4
	v_fmac_f32_e32 v84, v52, v85
	v_max_i32_e32 v85, 0, v5
	v_fmac_f32_e32 v84, v53, v85
	v_max_i32_e32 v85, 0, v6
	v_fmac_f32_e32 v84, v54, v85
	v_max_i32_e32 v85, 0, v7
	v_fmac_f32_e32 v84, v55, v85
	v_max_i32_e32 v85, 0, v8
	v_fmac_f32_e32 v84, v56, v85
	v_max_i32_e32 v85, 0, v9
	v_fmac_f32_e32 v84, v57, v85
	v_max_i32_e32 v85, 0, v10
	v_fmac_f32_e32 v84, v58, v85
	v_max_i32_e32 v85, 0, v11
	v_fmac_f32_e32 v84, v59, v85
	v_max_i32_e32 v85, 0, v12
	v_fmac_f32_e32 v84, v60, v85
	v_max_i32_e32 v85, 0, v13
	v_fmac_f32_e32 v84, v61, v85
	v_max_i32_e32 v85, 0, v14
	s_cmp_eq_u32 s60, 34
	v_fmac_f32_e32 v84, v62, v85
	v_max_i32_e32 v85, 0, v15
	s_cselect_b64 s[0:1], -1, 0
	v_cmp_gt_i32_e32 vcc, v160, v203
	v_fmac_f32_e32 v84, v63, v85
	s_and_b64 vcc, s[0:1], vcc
	v_cndmask_b32_e32 v228, v84, v197, vcc
	s_branch .Lixj27
.Lixc26:
.LBB0_1933:
	v_cndmask_b32_e64 v80, 0, 1, s[66:67]
	v_cmp_ne_u32_e64 s[54:55], 1, v80
	s_andn2_b64 vcc, exec, s[66:67]
	v_mov_b32_e32 v229, 0xff800000
	s_cbranch_vccnz .LBB0_1935
	v_max_i32_e32 v80, 0, v16
	v_fma_f32 v80, v48, v80, 0
	v_max_i32_e32 v81, 0, v17
	v_fmac_f32_e32 v80, v49, v81
	v_max_i32_e32 v81, 0, v18
	v_fmac_f32_e32 v80, v50, v81
	v_max_i32_e32 v81, 0, v19
	v_fmac_f32_e32 v80, v51, v81
	v_max_i32_e32 v81, 0, v20
	v_fmac_f32_e32 v80, v52, v81
	v_max_i32_e32 v81, 0, v21
	v_fmac_f32_e32 v80, v53, v81
	v_max_i32_e32 v81, 0, v22
	v_fmac_f32_e32 v80, v54, v81
	v_max_i32_e32 v81, 0, v23
	v_fmac_f32_e32 v80, v55, v81
	v_max_i32_e32 v81, 0, v24
	v_fmac_f32_e32 v80, v56, v81
	v_max_i32_e32 v81, 0, v25
	v_fmac_f32_e32 v80, v57, v81
	v_max_i32_e32 v81, 0, v26
	v_fmac_f32_e32 v80, v58, v81
	v_max_i32_e32 v81, 0, v27
	v_fmac_f32_e32 v80, v59, v81
	v_max_i32_e32 v81, 0, v28
	v_fmac_f32_e32 v80, v60, v81
	v_max_i32_e32 v81, 0, v29
	v_fmac_f32_e32 v80, v61, v81
	v_max_i32_e32 v81, 0, v30
	s_cmp_eq_u32 s60, 35
	v_fmac_f32_e32 v80, v62, v81
	v_max_i32_e32 v81, 0, v31
	s_cselect_b64 s[0:1], -1, 0
	v_cmp_gt_i32_e32 vcc, v161, v203
	v_fmac_f32_e32 v80, v63, v81
	s_and_b64 vcc, s[0:1], vcc
	v_cndmask_b32_e32 v229, v80, v197, vcc
	s_branch .Lixj26
.Lixc25:
.LBB0_1939:
	v_cndmask_b32_e64 v84, 0, 1, s[68:69]
	v_cmp_ne_u32_e64 s[54:55], 1, v84
	s_andn2_b64 vcc, exec, s[68:69]
	v_mov_b32_e32 v230, 0xff800000
	s_cbranch_vccnz .LBB0_1941
	v_max_i32_e32 v84, 0, v0
	v_fma_f32 v84, v48, v84, 0
	v_max_i32_e32 v85, 0, v1
	v_fmac_f32_e32 v84, v49, v85
	v_max_i32_e32 v85, 0, v2
	v_fmac_f32_e32 v84, v50, v85
	v_max_i32_e32 v85, 0, v3
	v_fmac_f32_e32 v84, v51, v85
	v_max_i32_e32 v85, 0, v4
	v_fmac_f32_e32 v84, v52, v85
	v_max_i32_e32 v85, 0, v5
	v_fmac_f32_e32 v84, v53, v85
	v_max_i32_e32 v85, 0, v6
	v_fmac_f32_e32 v84, v54, v85
	v_max_i32_e32 v85, 0, v7
	v_fmac_f32_e32 v84, v55, v85
	v_max_i32_e32 v85, 0, v8
	v_fmac_f32_e32 v84, v56, v85
	v_max_i32_e32 v85, 0, v9
	v_fmac_f32_e32 v84, v57, v85
	v_max_i32_e32 v85, 0, v10
	v_fmac_f32_e32 v84, v58, v85
	v_max_i32_e32 v85, 0, v11
	v_fmac_f32_e32 v84, v59, v85
	v_max_i32_e32 v85, 0, v12
	v_fmac_f32_e32 v84, v60, v85
	v_max_i32_e32 v85, 0, v13
	v_fmac_f32_e32 v84, v61, v85
	v_max_i32_e32 v85, 0, v14
	s_cmp_eq_u32 s60, 36
	v_fmac_f32_e32 v84, v62, v85
	v_max_i32_e32 v85, 0, v15
	s_cselect_b64 s[0:1], -1, 0
	v_cmp_gt_i32_e32 vcc, v162, v203
	v_fmac_f32_e32 v84, v63, v85
	s_and_b64 vcc, s[0:1], vcc
	v_cndmask_b32_e32 v230, v84, v197, vcc
	s_branch .Lixj25
.Lixc24:
.LBB0_1945:
	v_cndmask_b32_e64 v80, 0, 1, s[66:67]
	v_cmp_ne_u32_e64 s[54:55], 1, v80
	s_andn2_b64 vcc, exec, s[66:67]
	v_mov_b32_e32 v231, 0xff800000
	s_cbranch_vccnz .LBB0_1947
	v_max_i32_e32 v80, 0, v16
	v_fma_f32 v80, v48, v80, 0
	v_max_i32_e32 v81, 0, v17
	v_fmac_f32_e32 v80, v49, v81
	v_max_i32_e32 v81, 0, v18
	v_fmac_f32_e32 v80, v50, v81
	v_max_i32_e32 v81, 0, v19
	v_fmac_f32_e32 v80, v51, v81
	v_max_i32_e32 v81, 0, v20
	v_fmac_f32_e32 v80, v52, v81
	v_max_i32_e32 v81, 0, v21
	v_fmac_f32_e32 v80, v53, v81
	v_max_i32_e32 v81, 0, v22
	v_fmac_f32_e32 v80, v54, v81
	v_max_i32_e32 v81, 0, v23
	v_fmac_f32_e32 v80, v55, v81
	v_max_i32_e32 v81, 0, v24
	v_fmac_f32_e32 v80, v56, v81
	v_max_i32_e32 v81, 0, v25
	v_fmac_f32_e32 v80, v57, v81
	v_max_i32_e32 v81, 0, v26
	v_fmac_f32_e32 v80, v58, v81
	v_max_i32_e32 v81, 0, v27
	v_fmac_f32_e32 v80, v59, v81
	v_max_i32_e32 v81, 0, v28
	v_fmac_f32_e32 v80, v60, v81
	v_max_i32_e32 v81, 0, v29
	v_fmac_f32_e32 v80, v61, v81
	v_max_i32_e32 v81, 0, v30
	s_cmp_eq_u32 s60, 37
	v_fmac_f32_e32 v80, v62, v81
	v_max_i32_e32 v81, 0, v31
	s_cselect_b64 s[0:1], -1, 0
	v_cmp_gt_i32_e32 vcc, v163, v203
	v_fmac_f32_e32 v80, v63, v81
	s_and_b64 vcc, s[0:1], vcc
	v_cndmask_b32_e32 v231, v80, v197, vcc
	s_branch .Lixj24
.Lixc23:
.LBB0_1951:
	v_cndmask_b32_e64 v84, 0, 1, s[68:69]
	v_cmp_ne_u32_e64 s[54:55], 1, v84
	s_andn2_b64 vcc, exec, s[68:69]
	v_mov_b32_e32 v232, 0xff800000
	s_cbranch_vccnz .LBB0_1953
	v_max_i32_e32 v84, 0, v0
	v_fma_f32 v84, v48, v84, 0
	v_max_i32_e32 v85, 0, v1
	v_fmac_f32_e32 v84, v49, v85
	v_max_i32_e32 v85, 0, v2
	v_fmac_f32_e32 v84, v50, v85
	v_max_i32_e32 v85, 0, v3
	v_fmac_f32_e32 v84, v51, v85
	v_max_i32_e32 v85, 0, v4
	v_fmac_f32_e32 v84, v52, v85
	v_max_i32_e32 v85, 0, v5
	v_fmac_f32_e32 v84, v53, v85
	v_max_i32_e32 v85, 0, v6
	v_fmac_f32_e32 v84, v54, v85
	v_max_i32_e32 v85, 0, v7
	v_fmac_f32_e32 v84, v55, v85
	v_max_i32_e32 v85, 0, v8
	v_fmac_f32_e32 v84, v56, v85
	v_max_i32_e32 v85, 0, v9
	v_fmac_f32_e32 v84, v57, v85
	v_max_i32_e32 v85, 0, v10
	v_fmac_f32_e32 v84, v58, v85
	v_max_i32_e32 v85, 0, v11
	v_fmac_f32_e32 v84, v59, v85
	v_max_i32_e32 v85, 0, v12
	v_fmac_f32_e32 v84, v60, v85
	v_max_i32_e32 v85, 0, v13
	v_fmac_f32_e32 v84, v61, v85
	v_max_i32_e32 v85, 0, v14
	s_cmp_eq_u32 s60, 38
	v_fmac_f32_e32 v84, v62, v85
	v_max_i32_e32 v85, 0, v15
	s_cselect_b64 s[0:1], -1, 0
	v_cmp_gt_i32_e32 vcc, v164, v203
	v_fmac_f32_e32 v84, v63, v85
	s_and_b64 vcc, s[0:1], vcc
	v_cndmask_b32_e32 v232, v84, v197, vcc
	s_branch .Lixj23
.Lixc22:
.LBB0_1957:
	v_cndmask_b32_e64 v80, 0, 1, s[66:67]
	v_cmp_ne_u32_e64 s[54:55], 1, v80
	s_andn2_b64 vcc, exec, s[66:67]
	v_mov_b32_e32 v233, 0xff800000
	s_cbranch_vccnz .LBB0_1959
	v_max_i32_e32 v16, 0, v16
	v_fma_f32 v16, v48, v16, 0
	v_max_i32_e32 v17, 0, v17
	v_fmac_f32_e32 v16, v49, v17
	v_max_i32_e32 v17, 0, v18
	v_fmac_f32_e32 v16, v50, v17
	v_max_i32_e32 v17, 0, v19
	v_fmac_f32_e32 v16, v51, v17
	v_max_i32_e32 v17, 0, v20
	v_fmac_f32_e32 v16, v52, v17
	v_max_i32_e32 v17, 0, v21
	v_fmac_f32_e32 v16, v53, v17
	v_max_i32_e32 v17, 0, v22
	v_fmac_f32_e32 v16, v54, v17
	v_max_i32_e32 v17, 0, v23
	v_fmac_f32_e32 v16, v55, v17
	v_max_i32_e32 v17, 0, v24
	v_fmac_f32_e32 v16, v56, v17
	v_max_i32_e32 v17, 0, v25
	v_fmac_f32_e32 v16, v57, v17
	v_max_i32_e32 v17, 0, v26
	v_fmac_f32_e32 v16, v58, v17
	v_max_i32_e32 v17, 0, v27
	v_fmac_f32_e32 v16, v59, v17
	v_max_i32_e32 v17, 0, v28
	v_fmac_f32_e32 v16, v60, v17
	v_max_i32_e32 v17, 0, v29
	v_fmac_f32_e32 v16, v61, v17
	v_max_i32_e32 v17, 0, v30
	s_cmp_eq_u32 s60, 39
	v_fmac_f32_e32 v16, v62, v17
	v_max_i32_e32 v17, 0, v31
	s_cselect_b64 s[0:1], -1, 0
	v_cmp_gt_i32_e32 vcc, v165, v203
	v_fmac_f32_e32 v16, v63, v17
	s_and_b64 vcc, s[0:1], vcc
	v_cndmask_b32_e32 v233, v16, v197, vcc
	s_branch .Lixj22
.Lixc21:
.LBB0_1969:
	s_nop 4
	v_max_i32_e32 v80, 0, v16
	v_fma_f32 v80, v48, v80, 0
	v_max_i32_e32 v81, 0, v17
	v_fmac_f32_e32 v80, v49, v81
	v_max_i32_e32 v81, 0, v18
	v_fmac_f32_e32 v80, v50, v81
	v_max_i32_e32 v81, 0, v19
	v_fmac_f32_e32 v80, v51, v81
	v_max_i32_e32 v81, 0, v20
	v_fmac_f32_e32 v80, v52, v81
	v_max_i32_e32 v81, 0, v21
	v_fmac_f32_e32 v80, v53, v81
	v_max_i32_e32 v81, 0, v22
	v_fmac_f32_e32 v80, v54, v81
	v_max_i32_e32 v81, 0, v23
	v_fmac_f32_e32 v80, v55, v81
	v_max_i32_e32 v81, 0, v24
	v_fmac_f32_e32 v80, v56, v81
	v_max_i32_e32 v81, 0, v25
	v_fmac_f32_e32 v80, v57, v81
	v_max_i32_e32 v81, 0, v26
	v_fmac_f32_e32 v80, v58, v81
	v_max_i32_e32 v81, 0, v27
	v_fmac_f32_e32 v80, v59, v81
	v_max_i32_e32 v81, 0, v28
	v_fmac_f32_e32 v80, v60, v81
	v_max_i32_e32 v81, 0, v29
	v_fmac_f32_e32 v80, v61, v81
	v_max_i32_e32 v81, 0, v30
	v_fmac_f32_e32 v80, v62, v81
	v_max_i32_e32 v81, 0, v31
	v_cmp_gt_i32_e32 vcc, v167, v203
	v_fmac_f32_e32 v80, v63, v81
	s_and_b64 vcc, s[54:55], vcc
	v_cndmask_b32_e32 v235, v80, v197, vcc
	s_branch .Lixj21
.Lixc20:
.LBB0_1971:
	v_cndmask_b32_e64 v84, 0, 1, s[0:1]
	v_cmp_ne_u32_e64 s[54:55], 1, v84
	s_andn2_b64 vcc, exec, s[0:1]
	v_mov_b32_e32 v236, 0xff800000
	s_cbranch_vccnz .LBB0_1973
	v_max_i32_e32 v84, 0, v0
	v_fma_f32 v84, v48, v84, 0
	v_max_i32_e32 v85, 0, v1
	v_fmac_f32_e32 v84, v49, v85
	v_max_i32_e32 v85, 0, v2
	v_fmac_f32_e32 v84, v50, v85
	v_max_i32_e32 v85, 0, v3
	v_fmac_f32_e32 v84, v51, v85
	v_max_i32_e32 v85, 0, v4
	v_fmac_f32_e32 v84, v52, v85
	v_max_i32_e32 v85, 0, v5
	v_fmac_f32_e32 v84, v53, v85
	v_max_i32_e32 v85, 0, v6
	v_fmac_f32_e32 v84, v54, v85
	v_max_i32_e32 v85, 0, v7
	v_fmac_f32_e32 v84, v55, v85
	v_max_i32_e32 v85, 0, v8
	v_fmac_f32_e32 v84, v56, v85
	v_max_i32_e32 v85, 0, v9
	v_fmac_f32_e32 v84, v57, v85
	v_max_i32_e32 v85, 0, v10
	v_fmac_f32_e32 v84, v58, v85
	v_max_i32_e32 v85, 0, v11
	v_fmac_f32_e32 v84, v59, v85
	v_max_i32_e32 v85, 0, v12
	v_fmac_f32_e32 v84, v60, v85
	v_max_i32_e32 v85, 0, v13
	v_fmac_f32_e32 v84, v61, v85
	v_max_i32_e32 v85, 0, v14
	s_cmp_eq_u32 s60, 42
	v_fmac_f32_e32 v84, v62, v85
	v_max_i32_e32 v85, 0, v15
	s_cselect_b64 s[0:1], -1, 0
	v_cmp_gt_i32_e32 vcc, v168, v203
	v_fmac_f32_e32 v84, v63, v85
	s_and_b64 vcc, s[0:1], vcc
	v_cndmask_b32_e32 v236, v84, v197, vcc
	s_branch .Lixj20
.Lixc19:
.LBB0_1977:
	v_cndmask_b32_e64 v80, 0, 1, s[66:67]
	v_cmp_ne_u32_e64 s[54:55], 1, v80
	s_andn2_b64 vcc, exec, s[66:67]
	v_mov_b32_e32 v237, 0xff800000
	s_cbranch_vccnz .LBB0_1979
	v_max_i32_e32 v80, 0, v16
	v_fma_f32 v80, v48, v80, 0
	v_max_i32_e32 v81, 0, v17
	v_fmac_f32_e32 v80, v49, v81
	v_max_i32_e32 v81, 0, v18
	v_fmac_f32_e32 v80, v50, v81
	v_max_i32_e32 v81, 0, v19
	v_fmac_f32_e32 v80, v51, v81
	v_max_i32_e32 v81, 0, v20
	v_fmac_f32_e32 v80, v52, v81
	v_max_i32_e32 v81, 0, v21
	v_fmac_f32_e32 v80, v53, v81
	v_max_i32_e32 v81, 0, v22
	v_fmac_f32_e32 v80, v54, v81
	v_max_i32_e32 v81, 0, v23
	v_fmac_f32_e32 v80, v55, v81
	v_max_i32_e32 v81, 0, v24
	v_fmac_f32_e32 v80, v56, v81
	v_max_i32_e32 v81, 0, v25
	v_fmac_f32_e32 v80, v57, v81
	v_max_i32_e32 v81, 0, v26
	v_fmac_f32_e32 v80, v58, v81
	v_max_i32_e32 v81, 0, v27
	v_fmac_f32_e32 v80, v59, v81
	v_max_i32_e32 v81, 0, v28
	v_fmac_f32_e32 v80, v60, v81
	v_max_i32_e32 v81, 0, v29
	v_fmac_f32_e32 v80, v61, v81
	v_max_i32_e32 v81, 0, v30
	s_cmp_eq_u32 s60, 43
	v_fmac_f32_e32 v80, v62, v81
	v_max_i32_e32 v81, 0, v31
	s_cselect_b64 s[0:1], -1, 0
	v_cmp_gt_i32_e32 vcc, v169, v203
	v_fmac_f32_e32 v80, v63, v81
	s_and_b64 vcc, s[0:1], vcc
	v_cndmask_b32_e32 v237, v80, v197, vcc
	s_branch .Lixj19
.Lixc18:
.LBB0_1983:
	v_cndmask_b32_e64 v84, 0, 1, s[68:69]
	v_cmp_ne_u32_e64 s[54:55], 1, v84
	s_andn2_b64 vcc, exec, s[68:69]
	v_mov_b32_e32 v238, 0xff800000
	s_cbranch_vccnz .LBB0_1985
	v_max_i32_e32 v84, 0, v0
	v_fma_f32 v84, v48, v84, 0
	v_max_i32_e32 v85, 0, v1
	v_fmac_f32_e32 v84, v49, v85
	v_max_i32_e32 v85, 0, v2
	v_fmac_f32_e32 v84, v50, v85
	v_max_i32_e32 v85, 0, v3
	v_fmac_f32_e32 v84, v51, v85
	v_max_i32_e32 v85, 0, v4
	v_fmac_f32_e32 v84, v52, v85
	v_max_i32_e32 v85, 0, v5
	v_fmac_f32_e32 v84, v53, v85
	v_max_i32_e32 v85, 0, v6
	v_fmac_f32_e32 v84, v54, v85
	v_max_i32_e32 v85, 0, v7
	v_fmac_f32_e32 v84, v55, v85
	v_max_i32_e32 v85, 0, v8
	v_fmac_f32_e32 v84, v56, v85
	v_max_i32_e32 v85, 0, v9
	v_fmac_f32_e32 v84, v57, v85
	v_max_i32_e32 v85, 0, v10
	v_fmac_f32_e32 v84, v58, v85
	v_max_i32_e32 v85, 0, v11
	v_fmac_f32_e32 v84, v59, v85
	v_max_i32_e32 v85, 0, v12
	v_fmac_f32_e32 v84, v60, v85
	v_max_i32_e32 v85, 0, v13
	v_fmac_f32_e32 v84, v61, v85
	v_max_i32_e32 v85, 0, v14
	s_cmp_eq_u32 s60, 44
	v_fmac_f32_e32 v84, v62, v85
	v_max_i32_e32 v85, 0, v15
	s_cselect_b64 s[0:1], -1, 0
	v_cmp_gt_i32_e32 vcc, v170, v203
	v_fmac_f32_e32 v84, v63, v85
	s_and_b64 vcc, s[0:1], vcc
	v_cndmask_b32_e32 v238, v84, v197, vcc
	s_branch .Lixj18
.Lixc17:
.LBB0_1989:
	v_cndmask_b32_e64 v80, 0, 1, s[66:67]
	v_cmp_ne_u32_e64 s[54:55], 1, v80
	s_andn2_b64 vcc, exec, s[66:67]
	v_mov_b32_e32 v239, 0xff800000
	s_cbranch_vccnz .LBB0_1991
	v_max_i32_e32 v80, 0, v16
	v_fma_f32 v80, v48, v80, 0
	v_max_i32_e32 v81, 0, v17
	v_fmac_f32_e32 v80, v49, v81
	v_max_i32_e32 v81, 0, v18
	v_fmac_f32_e32 v80, v50, v81
	v_max_i32_e32 v81, 0, v19
	v_fmac_f32_e32 v80, v51, v81
	v_max_i32_e32 v81, 0, v20
	v_fmac_f32_e32 v80, v52, v81
	v_max_i32_e32 v81, 0, v21
	v_fmac_f32_e32 v80, v53, v81
	v_max_i32_e32 v81, 0, v22
	v_fmac_f32_e32 v80, v54, v81
	v_max_i32_e32 v81, 0, v23
	v_fmac_f32_e32 v80, v55, v81
	v_max_i32_e32 v81, 0, v24
	v_fmac_f32_e32 v80, v56, v81
	v_max_i32_e32 v81, 0, v25
	v_fmac_f32_e32 v80, v57, v81
	v_max_i32_e32 v81, 0, v26
	v_fmac_f32_e32 v80, v58, v81
	v_max_i32_e32 v81, 0, v27
	v_fmac_f32_e32 v80, v59, v81
	v_max_i32_e32 v81, 0, v28
	v_fmac_f32_e32 v80, v60, v81
	v_max_i32_e32 v81, 0, v29
	v_fmac_f32_e32 v80, v61, v81
	v_max_i32_e32 v81, 0, v30
	s_cmp_eq_u32 s60, 45
	v_fmac_f32_e32 v80, v62, v81
	v_max_i32_e32 v81, 0, v31
	s_cselect_b64 s[0:1], -1, 0
	v_cmp_gt_i32_e32 vcc, v171, v203
	v_fmac_f32_e32 v80, v63, v81
	s_and_b64 vcc, s[0:1], vcc
	v_cndmask_b32_e32 v239, v80, v197, vcc
	s_branch .Lixj17
.Lixc16:
.LBB0_1995:
	v_cndmask_b32_e64 v84, 0, 1, s[68:69]
	v_cmp_ne_u32_e64 s[54:55], 1, v84
	s_andn2_b64 vcc, exec, s[68:69]
	v_mov_b32_e32 v240, 0xff800000
	s_cbranch_vccnz .LBB0_1997
	v_max_i32_e32 v84, 0, v0
	v_fma_f32 v84, v48, v84, 0
	v_max_i32_e32 v85, 0, v1
	v_fmac_f32_e32 v84, v49, v85
	v_max_i32_e32 v85, 0, v2
	v_fmac_f32_e32 v84, v50, v85
	v_max_i32_e32 v85, 0, v3
	v_fmac_f32_e32 v84, v51, v85
	v_max_i32_e32 v85, 0, v4
	v_fmac_f32_e32 v84, v52, v85
	v_max_i32_e32 v85, 0, v5
	v_fmac_f32_e32 v84, v53, v85
	v_max_i32_e32 v85, 0, v6
	v_fmac_f32_e32 v84, v54, v85
	v_max_i32_e32 v85, 0, v7
	v_fmac_f32_e32 v84, v55, v85
	v_max_i32_e32 v85, 0, v8
	v_fmac_f32_e32 v84, v56, v85
	v_max_i32_e32 v85, 0, v9
	v_fmac_f32_e32 v84, v57, v85
	v_max_i32_e32 v85, 0, v10
	v_fmac_f32_e32 v84, v58, v85
	v_max_i32_e32 v85, 0, v11
	v_fmac_f32_e32 v84, v59, v85
	v_max_i32_e32 v85, 0, v12
	v_fmac_f32_e32 v84, v60, v85
	v_max_i32_e32 v85, 0, v13
	v_fmac_f32_e32 v84, v61, v85
	v_max_i32_e32 v85, 0, v14
	s_cmp_eq_u32 s60, 46
	v_fmac_f32_e32 v84, v62, v85
	v_max_i32_e32 v85, 0, v15
	s_cselect_b64 s[0:1], -1, 0
	v_cmp_gt_i32_e32 vcc, v172, v203
	v_fmac_f32_e32 v84, v63, v85
	s_and_b64 vcc, s[0:1], vcc
	v_cndmask_b32_e32 v240, v84, v197, vcc
	s_branch .Lixj16
.Lixc15:
.LBB0_2001:
	v_cndmask_b32_e64 v80, 0, 1, s[66:67]
	v_cmp_ne_u32_e64 s[54:55], 1, v80
	s_andn2_b64 vcc, exec, s[66:67]
	v_mov_b32_e32 v241, 0xff800000
	s_cbranch_vccnz .LBB0_2003
	v_max_i32_e32 v16, 0, v16
	v_fma_f32 v16, v48, v16, 0
	v_max_i32_e32 v17, 0, v17
	v_fmac_f32_e32 v16, v49, v17
	v_max_i32_e32 v17, 0, v18
	v_fmac_f32_e32 v16, v50, v17
	v_max_i32_e32 v17, 0, v19
	v_fmac_f32_e32 v16, v51, v17
	v_max_i32_e32 v17, 0, v20
	v_fmac_f32_e32 v16, v52, v17
	v_max_i32_e32 v17, 0, v21
	v_fmac_f32_e32 v16, v53, v17
	v_max_i32_e32 v17, 0, v22
	v_fmac_f32_e32 v16, v54, v17
	v_max_i32_e32 v17, 0, v23
	v_fmac_f32_e32 v16, v55, v17
	v_max_i32_e32 v17, 0, v24
	v_fmac_f32_e32 v16, v56, v17
	v_max_i32_e32 v17, 0, v25
	v_fmac_f32_e32 v16, v57, v17
	v_max_i32_e32 v17, 0, v26
	v_fmac_f32_e32 v16, v58, v17
	v_max_i32_e32 v17, 0, v27
	v_fmac_f32_e32 v16, v59, v17
	v_max_i32_e32 v17, 0, v28
	v_fmac_f32_e32 v16, v60, v17
	v_max_i32_e32 v17, 0, v29
	v_fmac_f32_e32 v16, v61, v17
	v_max_i32_e32 v17, 0, v30
	s_cmp_eq_u32 s60, 47
	v_fmac_f32_e32 v16, v62, v17
	v_max_i32_e32 v17, 0, v31
	s_cselect_b64 s[0:1], -1, 0
	v_cmp_gt_i32_e32 vcc, v173, v203
	v_fmac_f32_e32 v16, v63, v17
	s_and_b64 vcc, s[0:1], vcc
	v_cndmask_b32_e32 v241, v16, v197, vcc
	s_branch .Lixj15
.Lixc14:
.LBB0_2013:
	s_nop 4
	v_max_i32_e32 v80, 0, v16
	v_fma_f32 v80, v48, v80, 0
	v_max_i32_e32 v81, 0, v17
	v_fmac_f32_e32 v80, v49, v81
	v_max_i32_e32 v81, 0, v18
	v_fmac_f32_e32 v80, v50, v81
	v_max_i32_e32 v81, 0, v19
	v_fmac_f32_e32 v80, v51, v81
	v_max_i32_e32 v81, 0, v20
	v_fmac_f32_e32 v80, v52, v81
	v_max_i32_e32 v81, 0, v21
	v_fmac_f32_e32 v80, v53, v81
	v_max_i32_e32 v81, 0, v22
	v_fmac_f32_e32 v80, v54, v81
	v_max_i32_e32 v81, 0, v23
	v_fmac_f32_e32 v80, v55, v81
	v_max_i32_e32 v81, 0, v24
	v_fmac_f32_e32 v80, v56, v81
	v_max_i32_e32 v81, 0, v25
	v_fmac_f32_e32 v80, v57, v81
	v_max_i32_e32 v81, 0, v26
	v_fmac_f32_e32 v80, v58, v81
	v_max_i32_e32 v81, 0, v27
	v_fmac_f32_e32 v80, v59, v81
	v_max_i32_e32 v81, 0, v28
	v_fmac_f32_e32 v80, v60, v81
	v_max_i32_e32 v81, 0, v29
	v_fmac_f32_e32 v80, v61, v81
	v_max_i32_e32 v81, 0, v30
	v_fmac_f32_e32 v80, v62, v81
	v_max_i32_e32 v81, 0, v31
	v_cmp_gt_i32_e32 vcc, v175, v203
	v_fmac_f32_e32 v80, v63, v81
	s_and_b64 vcc, s[54:55], vcc
	v_cndmask_b32_e32 v243, v80, v197, vcc
	s_branch .Lixj14
.Lixc13:
.LBB0_2015:
	v_cndmask_b32_e64 v84, 0, 1, s[0:1]
	v_cmp_ne_u32_e64 s[54:55], 1, v84
	s_andn2_b64 vcc, exec, s[0:1]
	v_mov_b32_e32 v244, 0xff800000
	s_cbranch_vccnz .LBB0_2017
	v_max_i32_e32 v84, 0, v0
	v_fma_f32 v84, v48, v84, 0
	v_max_i32_e32 v85, 0, v1
	v_fmac_f32_e32 v84, v49, v85
	v_max_i32_e32 v85, 0, v2
	v_fmac_f32_e32 v84, v50, v85
	v_max_i32_e32 v85, 0, v3
	v_fmac_f32_e32 v84, v51, v85
	v_max_i32_e32 v85, 0, v4
	v_fmac_f32_e32 v84, v52, v85
	v_max_i32_e32 v85, 0, v5
	v_fmac_f32_e32 v84, v53, v85
	v_max_i32_e32 v85, 0, v6
	v_fmac_f32_e32 v84, v54, v85
	v_max_i32_e32 v85, 0, v7
	v_fmac_f32_e32 v84, v55, v85
	v_max_i32_e32 v85, 0, v8
	v_fmac_f32_e32 v84, v56, v85
	v_max_i32_e32 v85, 0, v9
	v_fmac_f32_e32 v84, v57, v85
	v_max_i32_e32 v85, 0, v10
	v_fmac_f32_e32 v84, v58, v85
	v_max_i32_e32 v85, 0, v11
	v_fmac_f32_e32 v84, v59, v85
	v_max_i32_e32 v85, 0, v12
	v_fmac_f32_e32 v84, v60, v85
	v_max_i32_e32 v85, 0, v13
	v_fmac_f32_e32 v84, v61, v85
	v_max_i32_e32 v85, 0, v14
	s_cmp_eq_u32 s60, 50
	v_fmac_f32_e32 v84, v62, v85
	v_max_i32_e32 v85, 0, v15
	s_cselect_b64 s[0:1], -1, 0
	v_cmp_gt_i32_e32 vcc, v176, v203
	v_fmac_f32_e32 v84, v63, v85
	s_and_b64 vcc, s[0:1], vcc
	v_cndmask_b32_e32 v244, v84, v197, vcc
	s_branch .Lixj13
.Lixc12:
.LBB0_2021:
	v_cndmask_b32_e64 v80, 0, 1, s[62:63]
	v_cmp_ne_u32_e64 s[54:55], 1, v80
	s_andn2_b64 vcc, exec, s[62:63]
	v_mov_b32_e32 v245, 0xff800000
	s_cbranch_vccnz .LBB0_2023
	v_max_i32_e32 v80, 0, v16
	v_fma_f32 v80, v48, v80, 0
	v_max_i32_e32 v81, 0, v17
	v_fmac_f32_e32 v80, v49, v81
	v_max_i32_e32 v81, 0, v18
	v_fmac_f32_e32 v80, v50, v81
	v_max_i32_e32 v81, 0, v19
	v_fmac_f32_e32 v80, v51, v81
	v_max_i32_e32 v81, 0, v20
	v_fmac_f32_e32 v80, v52, v81
	v_max_i32_e32 v81, 0, v21
	v_fmac_f32_e32 v80, v53, v81
	v_max_i32_e32 v81, 0, v22
	v_fmac_f32_e32 v80, v54, v81
	v_max_i32_e32 v81, 0, v23
	v_fmac_f32_e32 v80, v55, v81
	v_max_i32_e32 v81, 0, v24
	v_fmac_f32_e32 v80, v56, v81
	v_max_i32_e32 v81, 0, v25
	v_fmac_f32_e32 v80, v57, v81
	v_max_i32_e32 v81, 0, v26
	v_fmac_f32_e32 v80, v58, v81
	v_max_i32_e32 v81, 0, v27
	v_fmac_f32_e32 v80, v59, v81
	v_max_i32_e32 v81, 0, v28
	v_fmac_f32_e32 v80, v60, v81
	v_max_i32_e32 v81, 0, v29
	v_fmac_f32_e32 v80, v61, v81
	v_max_i32_e32 v81, 0, v30
	s_cmp_eq_u32 s60, 51
	v_fmac_f32_e32 v80, v62, v81
	v_max_i32_e32 v81, 0, v31
	s_cselect_b64 s[0:1], -1, 0
	v_cmp_gt_i32_e32 vcc, v177, v203
	v_fmac_f32_e32 v80, v63, v81
	s_and_b64 vcc, s[0:1], vcc
	v_cndmask_b32_e32 v245, v80, v197, vcc
	s_branch .Lixj12
.Lixc11:
.LBB0_2027:
	v_cndmask_b32_e64 v84, 0, 1, s[66:67]
	v_cmp_ne_u32_e64 s[54:55], 1, v84
	s_andn2_b64 vcc, exec, s[66:67]
	v_mov_b32_e32 v246, 0xff800000
	s_cbranch_vccnz .LBB0_2029
	v_max_i32_e32 v84, 0, v0
	v_fma_f32 v84, v48, v84, 0
	v_max_i32_e32 v85, 0, v1
	v_fmac_f32_e32 v84, v49, v85
	v_max_i32_e32 v85, 0, v2
	v_fmac_f32_e32 v84, v50, v85
	v_max_i32_e32 v85, 0, v3
	v_fmac_f32_e32 v84, v51, v85
	v_max_i32_e32 v85, 0, v4
	v_fmac_f32_e32 v84, v52, v85
	v_max_i32_e32 v85, 0, v5
	v_fmac_f32_e32 v84, v53, v85
	v_max_i32_e32 v85, 0, v6
	v_fmac_f32_e32 v84, v54, v85
	v_max_i32_e32 v85, 0, v7
	v_fmac_f32_e32 v84, v55, v85
	v_max_i32_e32 v85, 0, v8
	v_fmac_f32_e32 v84, v56, v85
	v_max_i32_e32 v85, 0, v9
	v_fmac_f32_e32 v84, v57, v85
	v_max_i32_e32 v85, 0, v10
	v_fmac_f32_e32 v84, v58, v85
	v_max_i32_e32 v85, 0, v11
	v_fmac_f32_e32 v84, v59, v85
	v_max_i32_e32 v85, 0, v12
	v_fmac_f32_e32 v84, v60, v85
	v_max_i32_e32 v85, 0, v13
	v_fmac_f32_e32 v84, v61, v85
	v_max_i32_e32 v85, 0, v14
	s_cmp_eq_u32 s60, 52
	v_fmac_f32_e32 v84, v62, v85
	v_max_i32_e32 v85, 0, v15
	s_cselect_b64 s[0:1], -1, 0
	v_cmp_gt_i32_e32 vcc, v178, v203
	v_fmac_f32_e32 v84, v63, v85
	s_and_b64 vcc, s[0:1], vcc
	v_cndmask_b32_e32 v246, v84, v197, vcc
	s_branch .Lixj11
.Lixc10:
.LBB0_2033:
	v_cndmask_b32_e64 v80, 0, 1, s[62:63]
	v_cmp_ne_u32_e64 s[54:55], 1, v80
	s_andn2_b64 vcc, exec, s[62:63]
	v_mov_b32_e32 v247, 0xff800000
	s_cbranch_vccnz .LBB0_2035
	v_max_i32_e32 v80, 0, v16
	v_fma_f32 v80, v48, v80, 0
	v_max_i32_e32 v81, 0, v17
	v_fmac_f32_e32 v80, v49, v81
	v_max_i32_e32 v81, 0, v18
	v_fmac_f32_e32 v80, v50, v81
	v_max_i32_e32 v81, 0, v19
	v_fmac_f32_e32 v80, v51, v81
	v_max_i32_e32 v81, 0, v20
	v_fmac_f32_e32 v80, v52, v81
	v_max_i32_e32 v81, 0, v21
	v_fmac_f32_e32 v80, v53, v81
	v_max_i32_e32 v81, 0, v22
	v_fmac_f32_e32 v80, v54, v81
	v_max_i32_e32 v81, 0, v23
	v_fmac_f32_e32 v80, v55, v81
	v_max_i32_e32 v81, 0, v24
	v_fmac_f32_e32 v80, v56, v81
	v_max_i32_e32 v81, 0, v25
	v_fmac_f32_e32 v80, v57, v81
	v_max_i32_e32 v81, 0, v26
	v_fmac_f32_e32 v80, v58, v81
	v_max_i32_e32 v81, 0, v27
	v_fmac_f32_e32 v80, v59, v81
	v_max_i32_e32 v81, 0, v28
	v_fmac_f32_e32 v80, v60, v81
	v_max_i32_e32 v81, 0, v29
	v_fmac_f32_e32 v80, v61, v81
	v_max_i32_e32 v81, 0, v30
	s_cmp_eq_u32 s60, 53
	v_fmac_f32_e32 v80, v62, v81
	v_max_i32_e32 v81, 0, v31
	s_cselect_b64 s[0:1], -1, 0
	v_cmp_gt_i32_e32 vcc, v179, v203
	v_fmac_f32_e32 v80, v63, v81
	s_and_b64 vcc, s[0:1], vcc
	v_cndmask_b32_e32 v247, v80, v197, vcc
	s_branch .Lixj10
.Lixc9:
.LBB0_2039:
	v_cndmask_b32_e64 v84, 0, 1, s[66:67]
	v_cmp_ne_u32_e64 s[54:55], 1, v84
	s_andn2_b64 vcc, exec, s[66:67]
	v_mov_b32_e32 v248, 0xff800000
	s_cbranch_vccnz .LBB0_2041
	v_max_i32_e32 v84, 0, v0
	v_fma_f32 v84, v48, v84, 0
	v_max_i32_e32 v85, 0, v1
	v_fmac_f32_e32 v84, v49, v85
	v_max_i32_e32 v85, 0, v2
	v_fmac_f32_e32 v84, v50, v85
	v_max_i32_e32 v85, 0, v3
	v_fmac_f32_e32 v84, v51, v85
	v_max_i32_e32 v85, 0, v4
	v_fmac_f32_e32 v84, v52, v85
	v_max_i32_e32 v85, 0, v5
	v_fmac_f32_e32 v84, v53, v85
	v_max_i32_e32 v85, 0, v6
	v_fmac_f32_e32 v84, v54, v85
	v_max_i32_e32 v85, 0, v7
	v_fmac_f32_e32 v84, v55, v85
	v_max_i32_e32 v85, 0, v8
	v_fmac_f32_e32 v84, v56, v85
	v_max_i32_e32 v85, 0, v9
	v_fmac_f32_e32 v84, v57, v85
	v_max_i32_e32 v85, 0, v10
	v_fmac_f32_e32 v84, v58, v85
	v_max_i32_e32 v85, 0, v11
	v_fmac_f32_e32 v84, v59, v85
	v_max_i32_e32 v85, 0, v12
	v_fmac_f32_e32 v84, v60, v85
	v_max_i32_e32 v85, 0, v13
	v_fmac_f32_e32 v84, v61, v85
	v_max_i32_e32 v85, 0, v14
	s_cmp_eq_u32 s60, 54
	v_fmac_f32_e32 v84, v62, v85
	v_max_i32_e32 v85, 0, v15
	s_cselect_b64 s[0:1], -1, 0
	v_cmp_gt_i32_e32 vcc, v180, v203
	v_fmac_f32_e32 v84, v63, v85
	s_and_b64 vcc, s[0:1], vcc
	v_cndmask_b32_e32 v248, v84, v197, vcc
	s_branch .Lixj9
.Lixc8:
.LBB0_2045:
	v_cndmask_b32_e64 v80, 0, 1, s[62:63]
	v_cmp_ne_u32_e64 s[54:55], 1, v80
	s_andn2_b64 vcc, exec, s[62:63]
	v_mov_b32_e32 v249, 0xff800000
	s_cbranch_vccnz .LBB0_2047
	v_max_i32_e32 v16, 0, v16
	v_fma_f32 v16, v48, v16, 0
	v_max_i32_e32 v17, 0, v17
	v_fmac_f32_e32 v16, v49, v17
	v_max_i32_e32 v17, 0, v18
	v_fmac_f32_e32 v16, v50, v17
	v_max_i32_e32 v17, 0, v19
	v_fmac_f32_e32 v16, v51, v17
	v_max_i32_e32 v17, 0, v20
	v_fmac_f32_e32 v16, v52, v17
	v_max_i32_e32 v17, 0, v21
	v_fmac_f32_e32 v16, v53, v17
	v_max_i32_e32 v17, 0, v22
	v_fmac_f32_e32 v16, v54, v17
	v_max_i32_e32 v17, 0, v23
	v_fmac_f32_e32 v16, v55, v17
	v_max_i32_e32 v17, 0, v24
	v_fmac_f32_e32 v16, v56, v17
	v_max_i32_e32 v17, 0, v25
	v_fmac_f32_e32 v16, v57, v17
	v_max_i32_e32 v17, 0, v26
	v_fmac_f32_e32 v16, v58, v17
	v_max_i32_e32 v17, 0, v27
	v_fmac_f32_e32 v16, v59, v17
	v_max_i32_e32 v17, 0, v28
	v_fmac_f32_e32 v16, v60, v17
	v_max_i32_e32 v17, 0, v29
	v_fmac_f32_e32 v16, v61, v17
	v_max_i32_e32 v17, 0, v30
	s_cmp_eq_u32 s60, 55
	v_fmac_f32_e32 v16, v62, v17
	v_max_i32_e32 v17, 0, v31
	s_cselect_b64 s[0:1], -1, 0
	v_cmp_gt_i32_e32 vcc, v181, v203
	v_fmac_f32_e32 v16, v63, v17
	s_and_b64 vcc, s[0:1], vcc
	v_cndmask_b32_e32 v249, v16, v197, vcc
	s_branch .Lixj8
.Lixc7:
.LBB0_2055:
	s_nop 4
	v_max_i32_e32 v80, 0, v16
	v_fma_f32 v80, v48, v80, 0
	v_max_i32_e32 v81, 0, v17
	v_fmac_f32_e32 v80, v49, v81
	v_max_i32_e32 v81, 0, v18
	v_fmac_f32_e32 v80, v50, v81
	v_max_i32_e32 v81, 0, v19
	v_fmac_f32_e32 v80, v51, v81
	v_max_i32_e32 v81, 0, v20
	v_fmac_f32_e32 v80, v52, v81
	v_max_i32_e32 v81, 0, v21
	v_fmac_f32_e32 v80, v53, v81
	v_max_i32_e32 v81, 0, v22
	v_fmac_f32_e32 v80, v54, v81
	v_max_i32_e32 v81, 0, v23
	v_fmac_f32_e32 v80, v55, v81
	v_max_i32_e32 v81, 0, v24
	v_fmac_f32_e32 v80, v56, v81
	v_max_i32_e32 v81, 0, v25
	v_fmac_f32_e32 v80, v57, v81
	v_max_i32_e32 v81, 0, v26
	v_fmac_f32_e32 v80, v58, v81
	v_max_i32_e32 v81, 0, v27
	v_fmac_f32_e32 v80, v59, v81
	v_max_i32_e32 v81, 0, v28
	v_fmac_f32_e32 v80, v60, v81
	v_max_i32_e32 v81, 0, v29
	v_fmac_f32_e32 v80, v61, v81
	v_max_i32_e32 v81, 0, v30
	v_fmac_f32_e32 v80, v62, v81
	v_max_i32_e32 v81, 0, v31
	v_cmp_gt_i32_e32 vcc, v183, v203
	v_fmac_f32_e32 v80, v63, v81
	s_and_b64 vcc, s[54:55], vcc
	v_cndmask_b32_e32 v251, v80, v197, vcc
	s_branch .Lixj7
.Lixc6:
.LBB0_2057:
	v_cndmask_b32_e64 v84, 0, 1, s[0:1]
	v_cmp_ne_u32_e64 s[54:55], 1, v84
	s_andn2_b64 vcc, exec, s[0:1]
	v_mov_b32_e32 v252, 0xff800000
	s_cbranch_vccnz .LBB0_2059
	v_max_i32_e32 v84, 0, v0
	v_fma_f32 v84, v48, v84, 0
	v_max_i32_e32 v85, 0, v1
	v_fmac_f32_e32 v84, v49, v85
	v_max_i32_e32 v85, 0, v2
	v_fmac_f32_e32 v84, v50, v85
	v_max_i32_e32 v85, 0, v3
	v_fmac_f32_e32 v84, v51, v85
	v_max_i32_e32 v85, 0, v4
	v_fmac_f32_e32 v84, v52, v85
	v_max_i32_e32 v85, 0, v5
	v_fmac_f32_e32 v84, v53, v85
	v_max_i32_e32 v85, 0, v6
	v_fmac_f32_e32 v84, v54, v85
	v_max_i32_e32 v85, 0, v7
	v_fmac_f32_e32 v84, v55, v85
	v_max_i32_e32 v85, 0, v8
	v_fmac_f32_e32 v84, v56, v85
	v_max_i32_e32 v85, 0, v9
	v_fmac_f32_e32 v84, v57, v85
	v_max_i32_e32 v85, 0, v10
	v_fmac_f32_e32 v84, v58, v85
	v_max_i32_e32 v85, 0, v11
	v_fmac_f32_e32 v84, v59, v85
	v_max_i32_e32 v85, 0, v12
	v_fmac_f32_e32 v84, v60, v85
	v_max_i32_e32 v85, 0, v13
	v_fmac_f32_e32 v84, v61, v85
	v_max_i32_e32 v85, 0, v14
	s_cmp_eq_u32 s60, 58
	v_fmac_f32_e32 v84, v62, v85
	v_max_i32_e32 v85, 0, v15
	s_cselect_b64 s[0:1], -1, 0
	v_cmp_gt_i32_e32 vcc, v184, v203
	v_fmac_f32_e32 v84, v63, v85
	s_and_b64 vcc, s[0:1], vcc
	v_cndmask_b32_e32 v252, v84, v197, vcc
	s_branch .Lixj6
.Lixc5:
.LBB0_2063:
	v_cndmask_b32_e64 v80, 0, 1, s[62:63]
	v_cmp_ne_u32_e64 s[54:55], 1, v80
	s_andn2_b64 vcc, exec, s[62:63]
	v_mov_b32_e32 v253, 0xff800000
	s_cbranch_vccnz .LBB0_2065
	v_max_i32_e32 v80, 0, v16
	v_fma_f32 v80, v48, v80, 0
	v_max_i32_e32 v81, 0, v17
	v_fmac_f32_e32 v80, v49, v81
	v_max_i32_e32 v81, 0, v18
	v_fmac_f32_e32 v80, v50, v81
	v_max_i32_e32 v81, 0, v19
	v_fmac_f32_e32 v80, v51, v81
	v_max_i32_e32 v81, 0, v20
	v_fmac_f32_e32 v80, v52, v81
	v_max_i32_e32 v81, 0, v21
	v_fmac_f32_e32 v80, v53, v81
	v_max_i32_e32 v81, 0, v22
	v_fmac_f32_e32 v80, v54, v81
	v_max_i32_e32 v81, 0, v23
	v_fmac_f32_e32 v80, v55, v81
	v_max_i32_e32 v81, 0, v24
	v_fmac_f32_e32 v80, v56, v81
	v_max_i32_e32 v81, 0, v25
	v_fmac_f32_e32 v80, v57, v81
	v_max_i32_e32 v81, 0, v26
	v_fmac_f32_e32 v80, v58, v81
	v_max_i32_e32 v81, 0, v27
	v_fmac_f32_e32 v80, v59, v81
	v_max_i32_e32 v81, 0, v28
	v_fmac_f32_e32 v80, v60, v81
	v_max_i32_e32 v81, 0, v29
	v_fmac_f32_e32 v80, v61, v81
	v_max_i32_e32 v81, 0, v30
	s_cmp_eq_u32 s60, 59
	v_fmac_f32_e32 v80, v62, v81
	v_max_i32_e32 v81, 0, v31
	s_cselect_b64 s[0:1], -1, 0
	v_cmp_gt_i32_e32 vcc, v185, v203
	v_fmac_f32_e32 v80, v63, v81
	s_and_b64 vcc, s[0:1], vcc
	v_cndmask_b32_e32 v253, v80, v197, vcc
	s_branch .Lixj5
.Lixc4:
.LBB0_2069:
	v_cndmask_b32_e64 v84, 0, 1, s[64:65]
	v_cmp_ne_u32_e64 s[54:55], 1, v84
	s_andn2_b64 vcc, exec, s[64:65]
	v_mov_b32_e32 v215, 0xff800000
	s_cbranch_vccnz .LBB0_2071
	v_max_i32_e32 v84, 0, v0
	v_fma_f32 v84, v48, v84, 0
	v_max_i32_e32 v85, 0, v1
	v_fmac_f32_e32 v84, v49, v85
	v_max_i32_e32 v85, 0, v2
	v_fmac_f32_e32 v84, v50, v85
	v_max_i32_e32 v85, 0, v3
	v_fmac_f32_e32 v84, v51, v85
	v_max_i32_e32 v85, 0, v4
	v_fmac_f32_e32 v84, v52, v85
	v_max_i32_e32 v85, 0, v5
	v_fmac_f32_e32 v84, v53, v85
	v_max_i32_e32 v85, 0, v6
	v_fmac_f32_e32 v84, v54, v85
	v_max_i32_e32 v85, 0, v7
	v_fmac_f32_e32 v84, v55, v85
	v_max_i32_e32 v85, 0, v8
	v_fmac_f32_e32 v84, v56, v85
	v_max_i32_e32 v85, 0, v9
	v_fmac_f32_e32 v84, v57, v85
	v_max_i32_e32 v85, 0, v10
	v_fmac_f32_e32 v84, v58, v85
	v_max_i32_e32 v85, 0, v11
	v_fmac_f32_e32 v84, v59, v85
	v_max_i32_e32 v85, 0, v12
	v_fmac_f32_e32 v84, v60, v85
	v_max_i32_e32 v85, 0, v13
	v_fmac_f32_e32 v84, v61, v85
	v_max_i32_e32 v85, 0, v14
	s_cmp_eq_u32 s60, 60
	v_fmac_f32_e32 v84, v62, v85
	v_max_i32_e32 v85, 0, v15
	s_cselect_b64 s[0:1], -1, 0
	v_cmp_gt_i32_e32 vcc, v186, v203
	v_fmac_f32_e32 v84, v63, v85
	s_and_b64 vcc, s[0:1], vcc
	v_cndmask_b32_e32 v215, v84, v197, vcc
	s_branch .Lixj4
.Lixc3:
.LBB0_2075:
	v_cndmask_b32_e64 v80, 0, 1, s[62:63]
	v_cmp_ne_u32_e64 s[54:55], 1, v80
	s_andn2_b64 vcc, exec, s[62:63]
	v_mov_b32_e32 v133, 0xff800000
	s_cbranch_vccnz .LBB0_2077
	v_max_i32_e32 v80, 0, v16
	v_fma_f32 v80, v48, v80, 0
	v_max_i32_e32 v81, 0, v17
	v_fmac_f32_e32 v80, v49, v81
	v_max_i32_e32 v81, 0, v18
	v_fmac_f32_e32 v80, v50, v81
	v_max_i32_e32 v81, 0, v19
	v_fmac_f32_e32 v80, v51, v81
	v_max_i32_e32 v81, 0, v20
	v_fmac_f32_e32 v80, v52, v81
	v_max_i32_e32 v81, 0, v21
	v_fmac_f32_e32 v80, v53, v81
	v_max_i32_e32 v81, 0, v22
	v_fmac_f32_e32 v80, v54, v81
	v_max_i32_e32 v81, 0, v23
	v_fmac_f32_e32 v80, v55, v81
	v_max_i32_e32 v81, 0, v24
	v_fmac_f32_e32 v80, v56, v81
	v_max_i32_e32 v81, 0, v25
	v_fmac_f32_e32 v80, v57, v81
	v_max_i32_e32 v81, 0, v26
	v_fmac_f32_e32 v80, v58, v81
	v_max_i32_e32 v81, 0, v27
	v_fmac_f32_e32 v80, v59, v81
	v_max_i32_e32 v81, 0, v28
	v_fmac_f32_e32 v80, v60, v81
	v_max_i32_e32 v81, 0, v29
	v_fmac_f32_e32 v80, v61, v81
	v_max_i32_e32 v81, 0, v30
	s_cmp_eq_u32 s60, 61
	v_fmac_f32_e32 v80, v62, v81
	v_max_i32_e32 v81, 0, v31
	s_cselect_b64 s[0:1], -1, 0
	v_cmp_gt_i32_e32 vcc, v187, v203
	v_fmac_f32_e32 v80, v63, v81
	s_and_b64 vcc, s[0:1], vcc
	v_cndmask_b32_e32 v133, v80, v197, vcc
	s_branch .Lixj3
.Lixc2:
.LBB0_2081:
	v_cndmask_b32_e64 v84, 0, 1, s[64:65]
	v_cmp_ne_u32_e64 s[54:55], 1, v84
	s_andn2_b64 vcc, exec, s[64:65]
	v_mov_b32_e32 v84, 0xff800000
	s_cbranch_vccnz .LBB0_2083
	v_max_i32_e32 v84, 0, v0
	v_fma_f32 v84, v48, v84, 0
	v_max_i32_e32 v85, 0, v1
	v_fmac_f32_e32 v84, v49, v85
	v_max_i32_e32 v85, 0, v2
	v_fmac_f32_e32 v84, v50, v85
	v_max_i32_e32 v85, 0, v3
	v_fmac_f32_e32 v84, v51, v85
	v_max_i32_e32 v85, 0, v4
	v_fmac_f32_e32 v84, v52, v85
	v_max_i32_e32 v85, 0, v5
	v_fmac_f32_e32 v84, v53, v85
	v_max_i32_e32 v85, 0, v6
	v_fmac_f32_e32 v84, v54, v85
	v_max_i32_e32 v85, 0, v7
	v_fmac_f32_e32 v84, v55, v85
	v_max_i32_e32 v85, 0, v8
	v_fmac_f32_e32 v84, v56, v85
	v_max_i32_e32 v85, 0, v9
	v_fmac_f32_e32 v84, v57, v85
	v_max_i32_e32 v85, 0, v10
	v_fmac_f32_e32 v84, v58, v85
	v_max_i32_e32 v85, 0, v11
	v_fmac_f32_e32 v84, v59, v85
	v_max_i32_e32 v85, 0, v12
	v_fmac_f32_e32 v84, v60, v85
	v_max_i32_e32 v85, 0, v13
	v_fmac_f32_e32 v84, v61, v85
	v_max_i32_e32 v85, 0, v14
	s_cmp_eq_u32 s60, 62
	v_fmac_f32_e32 v84, v62, v85
	v_max_i32_e32 v85, 0, v15
	s_cselect_b64 s[0:1], -1, 0
	v_cmp_gt_i32_e32 vcc, v188, v203
	v_fmac_f32_e32 v84, v63, v85
	s_and_b64 vcc, s[0:1], vcc
	v_cndmask_b32_e32 v84, v84, v197, vcc
	s_branch .Lixj2
.Lixc1:
.LBB0_2087:
	v_cndmask_b32_e64 v80, 0, 1, s[62:63]
	v_cmp_ne_u32_e64 s[54:55], 1, v80
	s_andn2_b64 vcc, exec, s[62:63]
	v_mov_b32_e32 v80, 0xff800000
	s_cbranch_vccnz .LBB0_2089
	v_max_i32_e32 v16, 0, v16
	v_fma_f32 v16, v48, v16, 0
	v_max_i32_e32 v17, 0, v17
	v_fmac_f32_e32 v16, v49, v17
	v_max_i32_e32 v17, 0, v18
	v_fmac_f32_e32 v16, v50, v17
	v_max_i32_e32 v17, 0, v19
	v_fmac_f32_e32 v16, v51, v17
	v_max_i32_e32 v17, 0, v20
	v_fmac_f32_e32 v16, v52, v17
	v_max_i32_e32 v17, 0, v21
	v_fmac_f32_e32 v16, v53, v17
	v_max_i32_e32 v17, 0, v22
	v_fmac_f32_e32 v16, v54, v17
	v_max_i32_e32 v17, 0, v23
	v_fmac_f32_e32 v16, v55, v17
	v_max_i32_e32 v17, 0, v24
	v_fmac_f32_e32 v16, v56, v17
	v_max_i32_e32 v17, 0, v25
	v_fmac_f32_e32 v16, v57, v17
	v_max_i32_e32 v17, 0, v26
	v_fmac_f32_e32 v16, v58, v17
	v_max_i32_e32 v17, 0, v27
	v_fmac_f32_e32 v16, v59, v17
	v_max_i32_e32 v17, 0, v28
	v_fmac_f32_e32 v16, v60, v17
	v_max_i32_e32 v17, 0, v29
	v_fmac_f32_e32 v16, v61, v17
	v_max_i32_e32 v17, 0, v30
	s_cmp_eq_u32 s60, 63
	v_fmac_f32_e32 v16, v62, v17
	v_max_i32_e32 v17, 0, v31
	s_cselect_b64 s[0:1], -1, 0
	v_cmp_gt_i32_e32 vcc, v189, v203
	v_fmac_f32_e32 v16, v63, v17
	s_and_b64 vcc, s[0:1], vcc
	v_cndmask_b32_e32 v80, v16, v197, vcc
	s_branch .Lixj1
